# setprio 1 before barrier, drop redundant lgkmcnt(0) after barrier in GEMM loops
# baseline (speedup 1.0000x reference)
.LBB0_152:
	ds_read_b128 v[160:163], v155
	ds_read_b128 v[164:167], v155 offset:1024
	ds_read_b128 v[168:171], v155 offset:2048
	ds_read_b128 v[172:175], v155 offset:3072
	ds_read_b128 v[176:179], v156
	ds_read_b128 v[180:183], v156 offset:1024
	ds_read_b128 v[184:187], v156 offset:2048
	ds_read_b128 v[188:191], v156 offset:3072
	s_add_u32 s50, s48, 0xfffc0080
	s_addc_u32 s51, s49, -1
	s_cmp_eq_u32 s73, 12
	s_cselect_b32 s53, s27, s51
	s_cselect_b32 s52, s69, s50
	s_cselect_b32 s51, s25, s72
	s_cselect_b32 s50, s70, s71
	v_lshl_add_u64 v[148:149], s[48:49], 0, v[140:141]
	s_add_i32 m0, s57, 0xc000
	ds_read_b128 v[192:195], v157
	ds_read_b128 v[196:199], v157 offset:1024
	ds_read_b128 v[200:203], v157 offset:2048
	ds_read_b128 v[204:207], v157 offset:3072
	ds_read_b128 v[208:211], v157 offset:4096
	ds_read_b128 v[212:215], v157 offset:5120
	ds_read_b128 v[216:219], v157 offset:6144
	ds_read_b128 v[220:223], v157 offset:7168
	global_load_lds_dwordx4 v[148:149], off
	v_lshl_add_u64 v[148:149], s[48:49], 0, v[142:143]
	s_add_i32 m0, s57, 0xe000
	s_nop 0
	global_load_lds_dwordx4 v[148:149], off
	s_waitcnt vmcnt(8)
	s_waitcnt lgkmcnt(0)
	s_setprio 1
	s_barrier
	v_mfma_f32_16x16x32_bf16 v[118:121], v[160:163], v[192:195], v[118:121]
	v_mfma_f32_16x16x32_bf16 v[114:117], v[168:171], v[192:195], v[114:117]
	v_mfma_f32_16x16x32_bf16 v[106:109], v[160:163], v[200:203], v[106:109]
	v_mfma_f32_16x16x32_bf16 v[98:101], v[168:171], v[200:203], v[98:101]
	v_mfma_f32_16x16x32_bf16 v[90:93], v[160:163], v[208:211], v[90:93]
	v_mfma_f32_16x16x32_bf16 v[82:85], v[168:171], v[208:211], v[82:85]
	v_mfma_f32_16x16x32_bf16 v[74:77], v[160:163], v[216:219], v[74:77]
	v_mfma_f32_16x16x32_bf16 v[66:69], v[168:171], v[216:219], v[66:69]
	v_mfma_f32_16x16x32_bf16 v[118:121], v[164:167], v[196:199], v[118:121]
	v_mfma_f32_16x16x32_bf16 v[114:117], v[172:175], v[196:199], v[114:117]
	v_mfma_f32_16x16x32_bf16 v[106:109], v[164:167], v[204:207], v[106:109]
	v_mfma_f32_16x16x32_bf16 v[98:101], v[172:175], v[204:207], v[98:101]
	v_mfma_f32_16x16x32_bf16 v[90:93], v[164:167], v[212:215], v[90:93]
	v_mfma_f32_16x16x32_bf16 v[82:85], v[172:175], v[212:215], v[82:85]
	v_mfma_f32_16x16x32_bf16 v[74:77], v[164:167], v[220:223], v[74:77]
	v_mfma_f32_16x16x32_bf16 v[66:69], v[172:175], v[220:223], v[66:69]
	s_setprio 0
	s_setprio 1
	v_mfma_f32_16x16x32_bf16 v[126:129], v[176:179], v[192:195], v[126:129]
	v_mfma_f32_16x16x32_bf16 v[122:125], v[184:187], v[192:195], v[122:125]
	v_mfma_f32_16x16x32_bf16 v[110:113], v[176:179], v[200:203], v[110:113]
	v_mfma_f32_16x16x32_bf16 v[102:105], v[184:187], v[200:203], v[102:105]
	v_mfma_f32_16x16x32_bf16 v[94:97], v[176:179], v[208:211], v[94:97]
	v_mfma_f32_16x16x32_bf16 v[86:89], v[184:187], v[208:211], v[86:89]
	v_mfma_f32_16x16x32_bf16 v[78:81], v[176:179], v[216:219], v[78:81]
	v_mfma_f32_16x16x32_bf16 v[70:73], v[184:187], v[216:219], v[70:73]
	v_mfma_f32_16x16x32_bf16 v[126:129], v[180:183], v[196:199], v[126:129]
	v_mfma_f32_16x16x32_bf16 v[122:125], v[188:191], v[196:199], v[122:125]
	v_mfma_f32_16x16x32_bf16 v[110:113], v[180:183], v[204:207], v[110:113]
	v_mfma_f32_16x16x32_bf16 v[102:105], v[188:191], v[204:207], v[102:105]
	v_mfma_f32_16x16x32_bf16 v[94:97], v[180:183], v[212:215], v[94:97]
	v_mfma_f32_16x16x32_bf16 v[86:89], v[188:191], v[212:215], v[86:89]
	v_mfma_f32_16x16x32_bf16 v[78:81], v[180:183], v[220:223], v[78:81]
	v_mfma_f32_16x16x32_bf16 v[70:73], v[188:191], v[220:223], v[70:73]
	s_setprio 0
	s_barrier
	s_add_i32 s74, s66, s54
	v_lshl_add_u64 v[148:149], s[50:51], 0, v[134:135]
	s_mov_b32 m0, s74
	ds_read_b128 v[192:195], v157 offset:16384
	ds_read_b128 v[196:199], v157 offset:17408
	ds_read_b128 v[200:203], v157 offset:18432
	ds_read_b128 v[204:207], v157 offset:19456
	ds_read_b128 v[208:211], v157 offset:20480
	ds_read_b128 v[212:215], v157 offset:21504
	ds_read_b128 v[216:219], v157 offset:22528
	ds_read_b128 v[220:223], v157 offset:23552
	global_load_lds_dwordx4 v[148:149], off
	s_add_i32 m0, s74, 0x2000
	s_add_u32 s74, s50, 0x40000
	v_lshl_add_u64 v[224:225], s[50:51], 0, v[130:131]
	s_addc_u32 s75, s51, 0
	s_add_i32 s76, s67, s54
	global_load_lds_dwordx4 v[224:225], off
	v_lshl_add_u64 v[226:227], s[74:75], 0, v[134:135]
	s_mov_b32 m0, s76
	v_lshl_add_u64 v[228:229], s[52:53], 0, v[132:133]
	global_load_lds_dwordx4 v[226:227], off
	v_lshl_add_u64 v[226:227], s[74:75], 0, v[130:131]
	s_add_i32 m0, s76, 0x2000
	s_nop 0
	global_load_lds_dwordx4 v[226:227], off
	v_lshl_add_u64 v[226:227], s[52:53], 0, v[136:137]
	s_mov_b32 m0, s57
	s_nop 0
	global_load_lds_dwordx4 v[226:227], off
	s_mov_b32 m0, s58
	s_nop 0
	global_load_lds_dwordx4 v[228:229], off
	s_waitcnt vmcnt(8)
	s_waitcnt lgkmcnt(0)
	s_setprio 1
	s_barrier
	v_mfma_f32_16x16x32_bf16 v[58:61], v[160:163], v[192:195], v[58:61]
	v_mfma_f32_16x16x32_bf16 v[50:53], v[168:171], v[192:195], v[50:53]
	v_mfma_f32_16x16x32_bf16 v[42:45], v[160:163], v[200:203], v[42:45]
	v_mfma_f32_16x16x32_bf16 v[34:37], v[168:171], v[200:203], v[34:37]
	v_mfma_f32_16x16x32_bf16 v[26:29], v[160:163], v[208:211], v[26:29]
	v_mfma_f32_16x16x32_bf16 v[18:21], v[168:171], v[208:211], v[18:21]
	v_mfma_f32_16x16x32_bf16 v[10:13], v[160:163], v[216:219], v[10:13]
	v_mfma_f32_16x16x32_bf16 v[6:9], v[168:171], v[216:219], v[6:9]
	v_mfma_f32_16x16x32_bf16 v[58:61], v[164:167], v[196:199], v[58:61]
	v_mfma_f32_16x16x32_bf16 v[50:53], v[172:175], v[196:199], v[50:53]
	v_mfma_f32_16x16x32_bf16 v[42:45], v[164:167], v[204:207], v[42:45]
	v_mfma_f32_16x16x32_bf16 v[34:37], v[172:175], v[204:207], v[34:37]
	v_mfma_f32_16x16x32_bf16 v[26:29], v[164:167], v[212:215], v[26:29]
	v_mfma_f32_16x16x32_bf16 v[18:21], v[172:175], v[212:215], v[18:21]
	v_mfma_f32_16x16x32_bf16 v[10:13], v[164:167], v[220:223], v[10:13]
	v_mfma_f32_16x16x32_bf16 v[6:9], v[172:175], v[220:223], v[6:9]
	s_setprio 0
	s_setprio 1
	v_mfma_f32_16x16x32_bf16 v[62:65], v[176:179], v[192:195], v[62:65]
	v_mfma_f32_16x16x32_bf16 v[54:57], v[184:187], v[192:195], v[54:57]
	v_mfma_f32_16x16x32_bf16 v[46:49], v[176:179], v[200:203], v[46:49]
	v_mfma_f32_16x16x32_bf16 v[38:41], v[184:187], v[200:203], v[38:41]
	v_mfma_f32_16x16x32_bf16 v[30:33], v[176:179], v[208:211], v[30:33]
	v_mfma_f32_16x16x32_bf16 v[22:25], v[184:187], v[208:211], v[22:25]
	v_mfma_f32_16x16x32_bf16 v[14:17], v[176:179], v[216:219], v[14:17]
	v_mfma_f32_16x16x32_bf16 v[2:5], v[184:187], v[216:219], v[2:5]
	v_mfma_f32_16x16x32_bf16 v[62:65], v[180:183], v[196:199], v[62:65]
	v_mfma_f32_16x16x32_bf16 v[54:57], v[188:191], v[196:199], v[54:57]
	v_mfma_f32_16x16x32_bf16 v[46:49], v[180:183], v[204:207], v[46:49]
	v_mfma_f32_16x16x32_bf16 v[38:41], v[188:191], v[204:207], v[38:41]
	v_mfma_f32_16x16x32_bf16 v[30:33], v[180:183], v[212:215], v[30:33]
	v_mfma_f32_16x16x32_bf16 v[22:25], v[188:191], v[212:215], v[22:25]
	v_mfma_f32_16x16x32_bf16 v[14:17], v[180:183], v[220:223], v[14:17]
	v_mfma_f32_16x16x32_bf16 v[2:5], v[188:191], v[220:223], v[2:5]
	s_setprio 0
	s_barrier
	s_add_i32 s74, 0, 0x18000
	v_add_u32_e32 v159, s74, v151
	s_add_i32 s75, 0, 0x1c000
	ds_read_b128 v[160:163], v159
	ds_read_b128 v[164:167], v159 offset:1024
	ds_read_b128 v[168:171], v159 offset:2048
	ds_read_b128 v[172:175], v159 offset:3072
	v_add_u32_e32 v159, s75, v151
	ds_read_b128 v[176:179], v159
	ds_read_b128 v[180:183], v159 offset:1024
	ds_read_b128 v[184:187], v159 offset:2048
	ds_read_b128 v[188:191], v159 offset:3072
	s_add_u32 s52, s52, 0x40000
	s_addc_u32 s53, s53, 0
	s_mov_b32 m0, s59
	v_lshl_add_u64 v[230:231], s[52:53], 0, v[136:137]
	ds_read_b128 v[192:195], v157 offset:32768
	ds_read_b128 v[196:199], v157 offset:33792
	ds_read_b128 v[200:203], v157 offset:34816
	ds_read_b128 v[204:207], v157 offset:35840
	ds_read_b128 v[208:211], v157 offset:36864
	ds_read_b128 v[212:215], v157 offset:37888
	ds_read_b128 v[216:219], v157 offset:38912
	ds_read_b128 v[220:223], v157 offset:39936
	global_load_lds_dwordx4 v[230:231], off
	v_lshl_add_u64 v[230:231], s[52:53], 0, v[132:133]
	s_mov_b32 m0, s60
	s_nop 0
	global_load_lds_dwordx4 v[230:231], off
	s_waitcnt vmcnt(8)
	s_waitcnt lgkmcnt(0)
	s_setprio 1
	s_barrier
	v_mfma_f32_16x16x32_bf16 v[118:121], v[160:163], v[192:195], v[118:121]
	v_mfma_f32_16x16x32_bf16 v[114:117], v[168:171], v[192:195], v[114:117]
	v_mfma_f32_16x16x32_bf16 v[106:109], v[160:163], v[200:203], v[106:109]
	v_mfma_f32_16x16x32_bf16 v[98:101], v[168:171], v[200:203], v[98:101]
	v_mfma_f32_16x16x32_bf16 v[90:93], v[160:163], v[208:211], v[90:93]
	v_mfma_f32_16x16x32_bf16 v[82:85], v[168:171], v[208:211], v[82:85]
	v_mfma_f32_16x16x32_bf16 v[74:77], v[160:163], v[216:219], v[74:77]
	v_mfma_f32_16x16x32_bf16 v[66:69], v[168:171], v[216:219], v[66:69]
	v_mfma_f32_16x16x32_bf16 v[118:121], v[164:167], v[196:199], v[118:121]
	v_mfma_f32_16x16x32_bf16 v[114:117], v[172:175], v[196:199], v[114:117]
	v_mfma_f32_16x16x32_bf16 v[106:109], v[164:167], v[204:207], v[106:109]
	v_mfma_f32_16x16x32_bf16 v[98:101], v[172:175], v[204:207], v[98:101]
	v_mfma_f32_16x16x32_bf16 v[90:93], v[164:167], v[212:215], v[90:93]
	v_mfma_f32_16x16x32_bf16 v[82:85], v[172:175], v[212:215], v[82:85]
	v_mfma_f32_16x16x32_bf16 v[74:77], v[164:167], v[220:223], v[74:77]
	v_mfma_f32_16x16x32_bf16 v[66:69], v[172:175], v[220:223], v[66:69]
	s_setprio 0
	s_setprio 1
	v_mfma_f32_16x16x32_bf16 v[126:129], v[176:179], v[192:195], v[126:129]
	v_mfma_f32_16x16x32_bf16 v[122:125], v[184:187], v[192:195], v[122:125]
	v_mfma_f32_16x16x32_bf16 v[110:113], v[176:179], v[200:203], v[110:113]
	v_mfma_f32_16x16x32_bf16 v[102:105], v[184:187], v[200:203], v[102:105]
	v_mfma_f32_16x16x32_bf16 v[94:97], v[176:179], v[208:211], v[94:97]
	v_mfma_f32_16x16x32_bf16 v[86:89], v[184:187], v[208:211], v[86:89]
	v_mfma_f32_16x16x32_bf16 v[78:81], v[176:179], v[216:219], v[78:81]
	v_mfma_f32_16x16x32_bf16 v[70:73], v[184:187], v[216:219], v[70:73]
	v_mfma_f32_16x16x32_bf16 v[126:129], v[180:183], v[196:199], v[126:129]
	v_mfma_f32_16x16x32_bf16 v[122:125], v[188:191], v[196:199], v[122:125]
	v_mfma_f32_16x16x32_bf16 v[110:113], v[180:183], v[204:207], v[110:113]
	v_mfma_f32_16x16x32_bf16 v[102:105], v[188:191], v[204:207], v[102:105]
	v_mfma_f32_16x16x32_bf16 v[94:97], v[180:183], v[212:215], v[94:97]
	v_mfma_f32_16x16x32_bf16 v[86:89], v[188:191], v[212:215], v[86:89]
	v_mfma_f32_16x16x32_bf16 v[78:81], v[180:183], v[220:223], v[78:81]
	v_mfma_f32_16x16x32_bf16 v[70:73], v[188:191], v[220:223], v[70:73]
	s_setprio 0
	s_barrier
	s_add_i32 s52, s74, s54
	v_lshl_add_u64 v[148:149], v[148:149], 0, s[14:15]
	s_mov_b32 m0, s52
	ds_read_b128 v[192:195], v157 offset:49152
	ds_read_b128 v[196:199], v157 offset:50176
	ds_read_b128 v[200:203], v157 offset:51200
	ds_read_b128 v[204:207], v157 offset:52224
	ds_read_b128 v[208:211], v157 offset:53248
	ds_read_b128 v[212:215], v157 offset:54272
	ds_read_b128 v[216:219], v157 offset:55296
	ds_read_b128 v[220:223], v157 offset:56320
	global_load_lds_dwordx4 v[148:149], off
	s_add_i32 m0, s52, 0x2000
	s_add_u32 s50, s50, 0x40080
	v_lshl_add_u64 v[148:149], v[224:225], 0, s[14:15]
	s_addc_u32 s51, s51, 0
	s_add_i32 s52, s75, s54
	global_load_lds_dwordx4 v[148:149], off
	v_lshl_add_u64 v[148:149], s[50:51], 0, v[134:135]
	s_mov_b32 m0, s52
	s_nop 0
	global_load_lds_dwordx4 v[148:149], off
	v_lshl_add_u64 v[148:149], s[50:51], 0, v[130:131]
	s_add_i32 m0, s52, 0x2000
	s_nop 0
	global_load_lds_dwordx4 v[148:149], off
	v_lshl_add_u64 v[148:149], v[226:227], 0, s[14:15]
	s_mov_b32 m0, s62
	s_nop 0
	global_load_lds_dwordx4 v[148:149], off
	v_lshl_add_u64 v[148:149], v[228:229], 0, s[14:15]
	s_mov_b32 m0, s63
	s_nop 0
	global_load_lds_dwordx4 v[148:149], off
	s_waitcnt vmcnt(8)
	s_waitcnt lgkmcnt(0)
	s_setprio 1
	s_barrier
	v_mfma_f32_16x16x32_bf16 v[58:61], v[160:163], v[192:195], v[58:61]
	v_mfma_f32_16x16x32_bf16 v[50:53], v[168:171], v[192:195], v[50:53]
	v_mfma_f32_16x16x32_bf16 v[42:45], v[160:163], v[200:203], v[42:45]
	v_mfma_f32_16x16x32_bf16 v[34:37], v[168:171], v[200:203], v[34:37]
	v_mfma_f32_16x16x32_bf16 v[26:29], v[160:163], v[208:211], v[26:29]
	v_mfma_f32_16x16x32_bf16 v[18:21], v[168:171], v[208:211], v[18:21]
	v_mfma_f32_16x16x32_bf16 v[10:13], v[160:163], v[216:219], v[10:13]
	v_mfma_f32_16x16x32_bf16 v[6:9], v[168:171], v[216:219], v[6:9]
	v_mfma_f32_16x16x32_bf16 v[58:61], v[164:167], v[196:199], v[58:61]
	v_mfma_f32_16x16x32_bf16 v[50:53], v[172:175], v[196:199], v[50:53]
	v_mfma_f32_16x16x32_bf16 v[42:45], v[164:167], v[204:207], v[42:45]
	v_mfma_f32_16x16x32_bf16 v[34:37], v[172:175], v[204:207], v[34:37]
	v_mfma_f32_16x16x32_bf16 v[26:29], v[164:167], v[212:215], v[26:29]
	v_mfma_f32_16x16x32_bf16 v[18:21], v[172:175], v[212:215], v[18:21]
	v_mfma_f32_16x16x32_bf16 v[10:13], v[164:167], v[220:223], v[10:13]
	v_mfma_f32_16x16x32_bf16 v[6:9], v[172:175], v[220:223], v[6:9]
	s_setprio 0
	s_setprio 1
	v_mfma_f32_16x16x32_bf16 v[62:65], v[176:179], v[192:195], v[62:65]
	v_mfma_f32_16x16x32_bf16 v[54:57], v[184:187], v[192:195], v[54:57]
	v_mfma_f32_16x16x32_bf16 v[46:49], v[176:179], v[200:203], v[46:49]
	v_mfma_f32_16x16x32_bf16 v[38:41], v[184:187], v[200:203], v[38:41]
	v_mfma_f32_16x16x32_bf16 v[30:33], v[176:179], v[208:211], v[30:33]
	v_mfma_f32_16x16x32_bf16 v[22:25], v[184:187], v[208:211], v[22:25]
	v_mfma_f32_16x16x32_bf16 v[14:17], v[176:179], v[216:219], v[14:17]
	v_mfma_f32_16x16x32_bf16 v[2:5], v[184:187], v[216:219], v[2:5]
	v_mfma_f32_16x16x32_bf16 v[62:65], v[180:183], v[196:199], v[62:65]
	v_mfma_f32_16x16x32_bf16 v[54:57], v[188:191], v[196:199], v[54:57]
	v_mfma_f32_16x16x32_bf16 v[46:49], v[180:183], v[204:207], v[46:49]
	v_mfma_f32_16x16x32_bf16 v[38:41], v[188:191], v[204:207], v[38:41]
	v_mfma_f32_16x16x32_bf16 v[30:33], v[180:183], v[212:215], v[30:33]
	v_mfma_f32_16x16x32_bf16 v[22:25], v[188:191], v[212:215], v[22:25]
	v_mfma_f32_16x16x32_bf16 v[14:17], v[180:183], v[220:223], v[14:17]
	v_mfma_f32_16x16x32_bf16 v[2:5], v[188:191], v[220:223], v[2:5]
	s_setprio 0
	s_barrier
	s_add_i32 s73, s73, 2
	s_add_u32 s48, s48, 0x100
	s_addc_u32 s49, s49, 0
	s_add_u32 s71, s71, 0x100
	s_addc_u32 s72, s72, 0
	s_cmp_gt_u32 s73, 13
	s_cbranch_scc0 .LBB0_152
	s_lshl_b32 s25, s46, 8
	v_add_u32_e32 v148, s25, v150
	v_ashrrev_i32_e32 v149, 31, v148
	v_lshl_add_u64 v[160:161], v[148:149], 2, s[8:9]
	global_load_dword v149, v[160:161], off
	global_load_dword v232, v[160:161], off offset:64
	global_load_dword v233, v[160:161], off offset:128
	global_load_dword v234, v[160:161], off offset:192
	global_load_dword v235, v[160:161], off offset:512
	global_load_dword v236, v[160:161], off offset:576
	global_load_dword v237, v[160:161], off offset:640
	global_load_dword v238, v[160:161], off offset:704
	s_and_b64 vcc, exec, s[16:17]
	s_cbranch_vccz .LBB0_155
	s_barrier

.LBB0_251:
	ds_read_b128 v[122:125], v245
	ds_read_b128 v[126:129], v245 offset:1024
	ds_read_b128 v[130:133], v245 offset:2048
	ds_read_b128 v[134:137], v245 offset:3072
	ds_read_b128 v[138:141], v246
	ds_read_b128 v[142:145], v246 offset:1024
	ds_read_b128 v[146:149], v246 offset:2048
	ds_read_b128 v[158:161], v246 offset:3072
	s_add_u32 s46, s44, 0x100
	s_addc_u32 s47, s45, 0
	s_cmp_eq_u32 s71, 40
	s_cselect_b32 s51, s9, s47
	s_cselect_b32 s50, s8, s46
	s_cselect_b32 s49, s43, s70
	s_cselect_b32 s48, s42, s69
	v_lshl_add_u64 v[210:211], s[44:45], 0, v[206:207]
	s_add_i32 m0, s53, 0xc000
	ds_read_b128 v[162:165], v247
	ds_read_b128 v[166:169], v247 offset:1024
	ds_read_b128 v[170:173], v247 offset:2048
	ds_read_b128 v[174:177], v247 offset:3072
	ds_read_b128 v[178:181], v247 offset:4096
	ds_read_b128 v[182:185], v247 offset:5120
	ds_read_b128 v[186:189], v247 offset:6144
	ds_read_b128 v[190:193], v247 offset:7168
	global_load_lds_dwordx4 v[210:211], off
	v_lshl_add_u64 v[210:211], s[44:45], 0, v[208:209]
	s_add_i32 m0, s53, 0xe000
	s_nop 0
	global_load_lds_dwordx4 v[210:211], off
	s_waitcnt vmcnt(8)
	s_waitcnt lgkmcnt(0)
	s_setprio 1
	s_barrier
	v_mfma_f32_16x16x32_bf16 v[154:157], v[122:125], v[162:165], v[154:157]
	v_mfma_f32_16x16x32_bf16 v[150:153], v[130:133], v[162:165], v[150:153]
	v_mfma_f32_16x16x32_bf16 v[110:113], v[122:125], v[170:173], v[110:113]
	v_mfma_f32_16x16x32_bf16 v[106:109], v[130:133], v[170:173], v[106:109]
	v_mfma_f32_16x16x32_bf16 v[94:97], v[122:125], v[178:181], v[94:97]
	v_mfma_f32_16x16x32_bf16 v[90:93], v[130:133], v[178:181], v[90:93]
	v_mfma_f32_16x16x32_bf16 v[78:81], v[122:125], v[186:189], v[78:81]
	v_mfma_f32_16x16x32_bf16 v[74:77], v[130:133], v[186:189], v[74:77]
	v_mfma_f32_16x16x32_bf16 v[154:157], v[126:129], v[166:169], v[154:157]
	v_mfma_f32_16x16x32_bf16 v[150:153], v[134:137], v[166:169], v[150:153]
	v_mfma_f32_16x16x32_bf16 v[110:113], v[126:129], v[174:177], v[110:113]
	v_mfma_f32_16x16x32_bf16 v[106:109], v[134:137], v[174:177], v[106:109]
	v_mfma_f32_16x16x32_bf16 v[94:97], v[126:129], v[182:185], v[94:97]
	v_mfma_f32_16x16x32_bf16 v[90:93], v[134:137], v[182:185], v[90:93]
	v_mfma_f32_16x16x32_bf16 v[78:81], v[126:129], v[190:193], v[78:81]
	v_mfma_f32_16x16x32_bf16 v[74:77], v[134:137], v[190:193], v[74:77]
	s_setprio 0
	s_setprio 1
	v_mfma_f32_16x16x32_bf16 v[118:121], v[138:141], v[162:165], v[118:121]
	v_mfma_f32_16x16x32_bf16 v[114:117], v[146:149], v[162:165], v[114:117]
	v_mfma_f32_16x16x32_bf16 v[102:105], v[138:141], v[170:173], v[102:105]
	v_mfma_f32_16x16x32_bf16 v[98:101], v[146:149], v[170:173], v[98:101]
	v_mfma_f32_16x16x32_bf16 v[86:89], v[138:141], v[178:181], v[86:89]
	v_mfma_f32_16x16x32_bf16 v[82:85], v[146:149], v[178:181], v[82:85]
	v_mfma_f32_16x16x32_bf16 v[70:73], v[138:141], v[186:189], v[70:73]
	v_mfma_f32_16x16x32_bf16 v[66:69], v[146:149], v[186:189], v[66:69]
	v_mfma_f32_16x16x32_bf16 v[118:121], v[142:145], v[166:169], v[118:121]
	v_mfma_f32_16x16x32_bf16 v[114:117], v[158:161], v[166:169], v[114:117]
	v_mfma_f32_16x16x32_bf16 v[102:105], v[142:145], v[174:177], v[102:105]
	v_mfma_f32_16x16x32_bf16 v[98:101], v[158:161], v[174:177], v[98:101]
	v_mfma_f32_16x16x32_bf16 v[86:89], v[142:145], v[182:185], v[86:89]
	v_mfma_f32_16x16x32_bf16 v[82:85], v[158:161], v[182:185], v[82:85]
	v_mfma_f32_16x16x32_bf16 v[70:73], v[142:145], v[190:193], v[70:73]
	v_mfma_f32_16x16x32_bf16 v[66:69], v[158:161], v[190:193], v[66:69]
	s_setprio 0
	s_barrier
	s_add_i32 s44, s63, s52
	v_lshl_add_u64 v[210:211], s[48:49], 0, v[196:197]
	s_mov_b32 m0, s44
	ds_read_b128 v[162:165], v247 offset:16384
	ds_read_b128 v[166:169], v247 offset:17408
	ds_read_b128 v[170:173], v247 offset:18432
	ds_read_b128 v[174:177], v247 offset:19456
	ds_read_b128 v[178:181], v247 offset:20480
	ds_read_b128 v[182:185], v247 offset:21504
	ds_read_b128 v[186:189], v247 offset:22528
	ds_read_b128 v[190:193], v247 offset:23552
	global_load_lds_dwordx4 v[210:211], off
	s_add_i32 m0, s44, 0x2000
	s_add_u32 s44, s48, 0xb0000
	v_lshl_add_u64 v[212:213], s[48:49], 0, v[200:201]
	s_addc_u32 s45, s49, 0
	s_add_i32 s72, s64, s52
	global_load_lds_dwordx4 v[212:213], off
	v_lshl_add_u64 v[214:215], s[44:45], 0, v[196:197]
	s_mov_b32 m0, s72
	v_lshl_add_u64 v[216:217], s[50:51], 0, v[198:199]
	global_load_lds_dwordx4 v[214:215], off
	v_lshl_add_u64 v[214:215], s[44:45], 0, v[200:201]
	s_add_i32 m0, s72, 0x2000
	s_nop 0
	global_load_lds_dwordx4 v[214:215], off
	v_lshl_add_u64 v[214:215], s[50:51], 0, v[194:195]
	s_mov_b32 m0, s53
	s_nop 0
	global_load_lds_dwordx4 v[214:215], off
	s_mov_b32 m0, s54
	s_nop 0
	global_load_lds_dwordx4 v[216:217], off
	s_waitcnt vmcnt(8)
	s_waitcnt lgkmcnt(0)
	s_setprio 1
	s_barrier
	v_mfma_f32_16x16x32_bf16 v[62:65], v[122:125], v[162:165], v[62:65]
	v_mfma_f32_16x16x32_bf16 v[58:61], v[130:133], v[162:165], v[58:61]
	v_mfma_f32_16x16x32_bf16 v[46:49], v[122:125], v[170:173], v[46:49]
	v_mfma_f32_16x16x32_bf16 v[42:45], v[130:133], v[170:173], v[42:45]
	v_mfma_f32_16x16x32_bf16 v[30:33], v[122:125], v[178:181], v[30:33]
	v_mfma_f32_16x16x32_bf16 v[26:29], v[130:133], v[178:181], v[26:29]
	v_mfma_f32_16x16x32_bf16 v[14:17], v[122:125], v[186:189], v[14:17]
	v_mfma_f32_16x16x32_bf16 v[10:13], v[130:133], v[186:189], v[10:13]
	v_mfma_f32_16x16x32_bf16 v[62:65], v[126:129], v[166:169], v[62:65]
	v_mfma_f32_16x16x32_bf16 v[58:61], v[134:137], v[166:169], v[58:61]
	v_mfma_f32_16x16x32_bf16 v[46:49], v[126:129], v[174:177], v[46:49]
	v_mfma_f32_16x16x32_bf16 v[42:45], v[134:137], v[174:177], v[42:45]
	v_mfma_f32_16x16x32_bf16 v[30:33], v[126:129], v[182:185], v[30:33]
	v_mfma_f32_16x16x32_bf16 v[26:29], v[134:137], v[182:185], v[26:29]
	v_mfma_f32_16x16x32_bf16 v[14:17], v[126:129], v[190:193], v[14:17]
	v_mfma_f32_16x16x32_bf16 v[10:13], v[134:137], v[190:193], v[10:13]
	s_setprio 0
	s_setprio 1
	v_mfma_f32_16x16x32_bf16 v[54:57], v[138:141], v[162:165], v[54:57]
	v_mfma_f32_16x16x32_bf16 v[50:53], v[146:149], v[162:165], v[50:53]
	v_mfma_f32_16x16x32_bf16 v[38:41], v[138:141], v[170:173], v[38:41]
	v_mfma_f32_16x16x32_bf16 v[34:37], v[146:149], v[170:173], v[34:37]
	v_mfma_f32_16x16x32_bf16 v[22:25], v[138:141], v[178:181], v[22:25]
	v_mfma_f32_16x16x32_bf16 v[18:21], v[146:149], v[178:181], v[18:21]
	v_mfma_f32_16x16x32_bf16 v[6:9], v[138:141], v[186:189], v[6:9]
	v_mfma_f32_16x16x32_bf16 v[2:5], v[146:149], v[186:189], v[2:5]
	v_mfma_f32_16x16x32_bf16 v[54:57], v[142:145], v[166:169], v[54:57]
	v_mfma_f32_16x16x32_bf16 v[50:53], v[158:161], v[166:169], v[50:53]
	v_mfma_f32_16x16x32_bf16 v[38:41], v[142:145], v[174:177], v[38:41]
	v_mfma_f32_16x16x32_bf16 v[34:37], v[158:161], v[174:177], v[34:37]
	v_mfma_f32_16x16x32_bf16 v[22:25], v[142:145], v[182:185], v[22:25]
	v_mfma_f32_16x16x32_bf16 v[18:21], v[158:161], v[182:185], v[18:21]
	v_mfma_f32_16x16x32_bf16 v[6:9], v[142:145], v[190:193], v[6:9]
	v_mfma_f32_16x16x32_bf16 v[2:5], v[158:161], v[190:193], v[2:5]
	s_setprio 0
	s_barrier
	s_add_i32 s72, 0, 0x18000
	s_add_i32 s73, 0, 0x1c000
	v_add_u32_e32 v134, s72, v244
	v_add_u32_e32 v158, s73, v244
	ds_read_b128 v[122:125], v134
	ds_read_b128 v[126:129], v134 offset:1024
	ds_read_b128 v[130:133], v134 offset:2048
	ds_read_b128 v[134:137], v134 offset:3072
	ds_read_b128 v[138:141], v158
	ds_read_b128 v[142:145], v158 offset:1024
	ds_read_b128 v[146:149], v158 offset:2048
	ds_read_b128 v[158:161], v158 offset:3072
	s_add_u32 s44, s50, 0xb0000
	s_addc_u32 s45, s51, 0
	s_mov_b32 m0, s55
	v_lshl_add_u64 v[218:219], s[44:45], 0, v[194:195]
	ds_read_b128 v[162:165], v247 offset:32768
	ds_read_b128 v[166:169], v247 offset:33792
	ds_read_b128 v[170:173], v247 offset:34816
	ds_read_b128 v[174:177], v247 offset:35840
	ds_read_b128 v[178:181], v247 offset:36864
	ds_read_b128 v[182:185], v247 offset:37888
	ds_read_b128 v[186:189], v247 offset:38912
	ds_read_b128 v[190:193], v247 offset:39936
	global_load_lds_dwordx4 v[218:219], off
	v_lshl_add_u64 v[218:219], s[44:45], 0, v[198:199]
	s_mov_b32 m0, s56
	s_nop 0
	global_load_lds_dwordx4 v[218:219], off
	s_waitcnt vmcnt(8)
	s_waitcnt lgkmcnt(0)
	s_setprio 1
	s_barrier
	v_mfma_f32_16x16x32_bf16 v[154:157], v[122:125], v[162:165], v[154:157]
	v_mfma_f32_16x16x32_bf16 v[150:153], v[130:133], v[162:165], v[150:153]
	v_mfma_f32_16x16x32_bf16 v[110:113], v[122:125], v[170:173], v[110:113]
	v_mfma_f32_16x16x32_bf16 v[106:109], v[130:133], v[170:173], v[106:109]
	v_mfma_f32_16x16x32_bf16 v[94:97], v[122:125], v[178:181], v[94:97]
	v_mfma_f32_16x16x32_bf16 v[90:93], v[130:133], v[178:181], v[90:93]
	v_mfma_f32_16x16x32_bf16 v[78:81], v[122:125], v[186:189], v[78:81]
	v_mfma_f32_16x16x32_bf16 v[74:77], v[130:133], v[186:189], v[74:77]
	v_mfma_f32_16x16x32_bf16 v[154:157], v[126:129], v[166:169], v[154:157]
	v_mfma_f32_16x16x32_bf16 v[150:153], v[134:137], v[166:169], v[150:153]
	v_mfma_f32_16x16x32_bf16 v[110:113], v[126:129], v[174:177], v[110:113]
	v_mfma_f32_16x16x32_bf16 v[106:109], v[134:137], v[174:177], v[106:109]
	v_mfma_f32_16x16x32_bf16 v[94:97], v[126:129], v[182:185], v[94:97]
	v_mfma_f32_16x16x32_bf16 v[90:93], v[134:137], v[182:185], v[90:93]
	v_mfma_f32_16x16x32_bf16 v[78:81], v[126:129], v[190:193], v[78:81]
	v_mfma_f32_16x16x32_bf16 v[74:77], v[134:137], v[190:193], v[74:77]
	s_setprio 0
	s_setprio 1
	v_mfma_f32_16x16x32_bf16 v[118:121], v[138:141], v[162:165], v[118:121]
	v_mfma_f32_16x16x32_bf16 v[114:117], v[146:149], v[162:165], v[114:117]
	v_mfma_f32_16x16x32_bf16 v[102:105], v[138:141], v[170:173], v[102:105]
	v_mfma_f32_16x16x32_bf16 v[98:101], v[146:149], v[170:173], v[98:101]
	v_mfma_f32_16x16x32_bf16 v[86:89], v[138:141], v[178:181], v[86:89]
	v_mfma_f32_16x16x32_bf16 v[82:85], v[146:149], v[178:181], v[82:85]
	v_mfma_f32_16x16x32_bf16 v[70:73], v[138:141], v[186:189], v[70:73]
	v_mfma_f32_16x16x32_bf16 v[66:69], v[146:149], v[186:189], v[66:69]
	v_mfma_f32_16x16x32_bf16 v[118:121], v[142:145], v[166:169], v[118:121]
	v_mfma_f32_16x16x32_bf16 v[114:117], v[158:161], v[166:169], v[114:117]
	v_mfma_f32_16x16x32_bf16 v[102:105], v[142:145], v[174:177], v[102:105]
	v_mfma_f32_16x16x32_bf16 v[98:101], v[158:161], v[174:177], v[98:101]
	v_mfma_f32_16x16x32_bf16 v[86:89], v[142:145], v[182:185], v[86:89]
	v_mfma_f32_16x16x32_bf16 v[82:85], v[158:161], v[182:185], v[82:85]
	v_mfma_f32_16x16x32_bf16 v[70:73], v[142:145], v[190:193], v[70:73]
	v_mfma_f32_16x16x32_bf16 v[66:69], v[158:161], v[190:193], v[66:69]
	s_setprio 0
	s_barrier
	s_add_i32 s44, s72, s52
	v_lshl_add_u64 v[210:211], v[210:211], 0, s[24:25]
	s_mov_b32 m0, s44
	ds_read_b128 v[162:165], v247 offset:49152
	ds_read_b128 v[166:169], v247 offset:50176
	ds_read_b128 v[170:173], v247 offset:51200
	ds_read_b128 v[174:177], v247 offset:52224
	ds_read_b128 v[178:181], v247 offset:53248
	ds_read_b128 v[182:185], v247 offset:54272
	ds_read_b128 v[186:189], v247 offset:55296
	ds_read_b128 v[190:193], v247 offset:56320
	global_load_lds_dwordx4 v[210:211], off
	s_add_i32 m0, s44, 0x2000
	s_add_u32 s44, s48, 0xb0080
	v_lshl_add_u64 v[210:211], v[212:213], 0, s[24:25]
	s_addc_u32 s45, s49, 0
	s_add_i32 s48, s73, s52
	global_load_lds_dwordx4 v[210:211], off
	v_lshl_add_u64 v[210:211], s[44:45], 0, v[196:197]
	s_mov_b32 m0, s48
	s_nop 0
	global_load_lds_dwordx4 v[210:211], off
	v_lshl_add_u64 v[210:211], s[44:45], 0, v[200:201]
	s_add_i32 m0, s48, 0x2000
	s_nop 0
	global_load_lds_dwordx4 v[210:211], off
	v_lshl_add_u64 v[210:211], v[214:215], 0, s[24:25]
	s_mov_b32 m0, s58
	s_nop 0
	global_load_lds_dwordx4 v[210:211], off
	v_lshl_add_u64 v[210:211], v[216:217], 0, s[24:25]
	s_mov_b32 m0, s59
	s_nop 0
	global_load_lds_dwordx4 v[210:211], off
	s_waitcnt vmcnt(8)
	s_waitcnt lgkmcnt(0)
	s_setprio 1
	s_barrier
	v_mfma_f32_16x16x32_bf16 v[62:65], v[122:125], v[162:165], v[62:65]
	v_mfma_f32_16x16x32_bf16 v[58:61], v[130:133], v[162:165], v[58:61]
	v_mfma_f32_16x16x32_bf16 v[46:49], v[122:125], v[170:173], v[46:49]
	v_mfma_f32_16x16x32_bf16 v[42:45], v[130:133], v[170:173], v[42:45]
	v_mfma_f32_16x16x32_bf16 v[30:33], v[122:125], v[178:181], v[30:33]
	v_mfma_f32_16x16x32_bf16 v[26:29], v[130:133], v[178:181], v[26:29]
	v_mfma_f32_16x16x32_bf16 v[14:17], v[122:125], v[186:189], v[14:17]
	v_mfma_f32_16x16x32_bf16 v[10:13], v[130:133], v[186:189], v[10:13]
	v_mfma_f32_16x16x32_bf16 v[62:65], v[126:129], v[166:169], v[62:65]
	v_mfma_f32_16x16x32_bf16 v[58:61], v[134:137], v[166:169], v[58:61]
	v_mfma_f32_16x16x32_bf16 v[46:49], v[126:129], v[174:177], v[46:49]
	v_mfma_f32_16x16x32_bf16 v[42:45], v[134:137], v[174:177], v[42:45]
	v_mfma_f32_16x16x32_bf16 v[30:33], v[126:129], v[182:185], v[30:33]
	v_mfma_f32_16x16x32_bf16 v[26:29], v[134:137], v[182:185], v[26:29]
	v_mfma_f32_16x16x32_bf16 v[14:17], v[126:129], v[190:193], v[14:17]
	v_mfma_f32_16x16x32_bf16 v[10:13], v[134:137], v[190:193], v[10:13]
	s_setprio 0
	s_setprio 1
	v_mfma_f32_16x16x32_bf16 v[54:57], v[138:141], v[162:165], v[54:57]
	v_mfma_f32_16x16x32_bf16 v[50:53], v[146:149], v[162:165], v[50:53]
	v_mfma_f32_16x16x32_bf16 v[38:41], v[138:141], v[170:173], v[38:41]
	v_mfma_f32_16x16x32_bf16 v[34:37], v[146:149], v[170:173], v[34:37]
	v_mfma_f32_16x16x32_bf16 v[22:25], v[138:141], v[178:181], v[22:25]
	v_mfma_f32_16x16x32_bf16 v[18:21], v[146:149], v[178:181], v[18:21]
	v_mfma_f32_16x16x32_bf16 v[6:9], v[138:141], v[186:189], v[6:9]
	v_mfma_f32_16x16x32_bf16 v[2:5], v[146:149], v[186:189], v[2:5]
	v_mfma_f32_16x16x32_bf16 v[54:57], v[142:145], v[166:169], v[54:57]
	v_mfma_f32_16x16x32_bf16 v[50:53], v[158:161], v[166:169], v[50:53]
	v_mfma_f32_16x16x32_bf16 v[38:41], v[142:145], v[174:177], v[38:41]
	v_mfma_f32_16x16x32_bf16 v[34:37], v[158:161], v[174:177], v[34:37]
	v_mfma_f32_16x16x32_bf16 v[22:25], v[142:145], v[182:185], v[22:25]
	v_mfma_f32_16x16x32_bf16 v[18:21], v[158:161], v[182:185], v[18:21]
	v_mfma_f32_16x16x32_bf16 v[6:9], v[142:145], v[190:193], v[6:9]
	v_mfma_f32_16x16x32_bf16 v[2:5], v[158:161], v[190:193], v[2:5]
	s_setprio 0
	s_barrier
	s_add_i32 s71, s71, 2
	s_add_u32 s69, s69, 0x100
	s_addc_u32 s70, s70, 0
	s_cmp_gt_u32 s71, 41
	s_mov_b64 s[44:45], s[46:47]
	s_cbranch_scc0 .LBB0_251
	s_and_b64 vcc, exec, s[26:27]
	s_cbranch_vccz .LBB0_254
	s_barrier

.LBB0_352:
	ds_read_b128 v[156:159], v152
	ds_read_b128 v[160:163], v152 offset:1024
	ds_read_b128 v[164:167], v152 offset:2048
	ds_read_b128 v[168:171], v152 offset:3072
	ds_read_b128 v[172:175], v153
	ds_read_b128 v[176:179], v153 offset:1024
	ds_read_b128 v[180:183], v153 offset:2048
	ds_read_b128 v[184:187], v153 offset:3072
	s_add_u32 s50, s48, 0xfffc0080
	s_addc_u32 s51, s49, -1
	s_cmp_eq_u32 s73, 12
	s_cselect_b32 s53, s7, s51
	s_cselect_b32 s52, s43, s50
	s_cselect_b32 s51, s27, s72
	s_cselect_b32 s50, s70, s71
	v_lshl_add_u64 v[148:149], s[48:49], 0, v[140:141]
	s_add_i32 m0, s57, 0xc000
	ds_read_b128 v[188:191], v154
	ds_read_b128 v[192:195], v154 offset:1024
	ds_read_b128 v[196:199], v154 offset:2048
	ds_read_b128 v[200:203], v154 offset:3072
	ds_read_b128 v[204:207], v154 offset:4096
	ds_read_b128 v[208:211], v154 offset:5120
	ds_read_b128 v[212:215], v154 offset:6144
	ds_read_b128 v[216:219], v154 offset:7168
	global_load_lds_dwordx4 v[148:149], off
	v_lshl_add_u64 v[148:149], s[48:49], 0, v[142:143]
	s_add_i32 m0, s57, 0xe000
	s_nop 0
	global_load_lds_dwordx4 v[148:149], off
	s_waitcnt vmcnt(8)
	s_waitcnt lgkmcnt(0)
	s_setprio 1
	s_barrier
	v_mfma_f32_16x16x32_bf16 v[126:129], v[156:159], v[188:191], v[126:129]
	v_mfma_f32_16x16x32_bf16 v[122:125], v[164:167], v[188:191], v[122:125]
	v_mfma_f32_16x16x32_bf16 v[110:113], v[156:159], v[196:199], v[110:113]
	v_mfma_f32_16x16x32_bf16 v[106:109], v[164:167], v[196:199], v[106:109]
	v_mfma_f32_16x16x32_bf16 v[94:97], v[156:159], v[204:207], v[94:97]
	v_mfma_f32_16x16x32_bf16 v[90:93], v[164:167], v[204:207], v[90:93]
	v_mfma_f32_16x16x32_bf16 v[78:81], v[156:159], v[212:215], v[78:81]
	v_mfma_f32_16x16x32_bf16 v[74:77], v[164:167], v[212:215], v[74:77]
	v_mfma_f32_16x16x32_bf16 v[126:129], v[160:163], v[192:195], v[126:129]
	v_mfma_f32_16x16x32_bf16 v[122:125], v[168:171], v[192:195], v[122:125]
	v_mfma_f32_16x16x32_bf16 v[110:113], v[160:163], v[200:203], v[110:113]
	v_mfma_f32_16x16x32_bf16 v[106:109], v[168:171], v[200:203], v[106:109]
	v_mfma_f32_16x16x32_bf16 v[94:97], v[160:163], v[208:211], v[94:97]
	v_mfma_f32_16x16x32_bf16 v[90:93], v[168:171], v[208:211], v[90:93]
	v_mfma_f32_16x16x32_bf16 v[78:81], v[160:163], v[216:219], v[78:81]
	v_mfma_f32_16x16x32_bf16 v[74:77], v[168:171], v[216:219], v[74:77]
	s_setprio 0
	s_setprio 1
	v_mfma_f32_16x16x32_bf16 v[118:121], v[172:175], v[188:191], v[118:121]
	v_mfma_f32_16x16x32_bf16 v[114:117], v[180:183], v[188:191], v[114:117]
	v_mfma_f32_16x16x32_bf16 v[102:105], v[172:175], v[196:199], v[102:105]
	v_mfma_f32_16x16x32_bf16 v[98:101], v[180:183], v[196:199], v[98:101]
	v_mfma_f32_16x16x32_bf16 v[86:89], v[172:175], v[204:207], v[86:89]
	v_mfma_f32_16x16x32_bf16 v[82:85], v[180:183], v[204:207], v[82:85]
	v_mfma_f32_16x16x32_bf16 v[70:73], v[172:175], v[212:215], v[70:73]
	v_mfma_f32_16x16x32_bf16 v[66:69], v[180:183], v[212:215], v[66:69]
	v_mfma_f32_16x16x32_bf16 v[118:121], v[176:179], v[192:195], v[118:121]
	v_mfma_f32_16x16x32_bf16 v[114:117], v[184:187], v[192:195], v[114:117]
	v_mfma_f32_16x16x32_bf16 v[102:105], v[176:179], v[200:203], v[102:105]
	v_mfma_f32_16x16x32_bf16 v[98:101], v[184:187], v[200:203], v[98:101]
	v_mfma_f32_16x16x32_bf16 v[86:89], v[176:179], v[208:211], v[86:89]
	v_mfma_f32_16x16x32_bf16 v[82:85], v[184:187], v[208:211], v[82:85]
	v_mfma_f32_16x16x32_bf16 v[70:73], v[176:179], v[216:219], v[70:73]
	v_mfma_f32_16x16x32_bf16 v[66:69], v[184:187], v[216:219], v[66:69]
	s_setprio 0
	s_barrier
	s_add_i32 s74, s67, s54
	v_lshl_add_u64 v[148:149], s[50:51], 0, v[134:135]
	s_mov_b32 m0, s74
	ds_read_b128 v[188:191], v154 offset:16384
	ds_read_b128 v[192:195], v154 offset:17408
	ds_read_b128 v[196:199], v154 offset:18432
	ds_read_b128 v[200:203], v154 offset:19456
	ds_read_b128 v[204:207], v154 offset:20480
	ds_read_b128 v[208:211], v154 offset:21504
	ds_read_b128 v[212:215], v154 offset:22528
	ds_read_b128 v[216:219], v154 offset:23552
	global_load_lds_dwordx4 v[148:149], off
	s_add_i32 m0, s74, 0x2000
	s_add_u32 s74, s50, 0x40000
	v_lshl_add_u64 v[220:221], s[50:51], 0, v[130:131]
	s_addc_u32 s75, s51, 0
	s_add_i32 s76, s68, s54
	global_load_lds_dwordx4 v[220:221], off
	v_lshl_add_u64 v[222:223], s[74:75], 0, v[134:135]
	s_mov_b32 m0, s76
	v_lshl_add_u64 v[224:225], s[52:53], 0, v[132:133]
	global_load_lds_dwordx4 v[222:223], off
	v_lshl_add_u64 v[222:223], s[74:75], 0, v[130:131]
	s_add_i32 m0, s76, 0x2000
	s_nop 0
	global_load_lds_dwordx4 v[222:223], off
	v_lshl_add_u64 v[222:223], s[52:53], 0, v[136:137]
	s_mov_b32 m0, s57
	s_nop 0
	global_load_lds_dwordx4 v[222:223], off
	s_mov_b32 m0, s58
	s_nop 0
	global_load_lds_dwordx4 v[224:225], off
	s_waitcnt vmcnt(8)
	s_waitcnt lgkmcnt(0)
	s_setprio 1
	s_barrier
	v_mfma_f32_16x16x32_bf16 v[62:65], v[156:159], v[188:191], v[62:65]
	v_mfma_f32_16x16x32_bf16 v[58:61], v[164:167], v[188:191], v[58:61]
	v_mfma_f32_16x16x32_bf16 v[46:49], v[156:159], v[196:199], v[46:49]
	v_mfma_f32_16x16x32_bf16 v[42:45], v[164:167], v[196:199], v[42:45]
	v_mfma_f32_16x16x32_bf16 v[30:33], v[156:159], v[204:207], v[30:33]
	v_mfma_f32_16x16x32_bf16 v[26:29], v[164:167], v[204:207], v[26:29]
	v_mfma_f32_16x16x32_bf16 v[14:17], v[156:159], v[212:215], v[14:17]
	v_mfma_f32_16x16x32_bf16 v[10:13], v[164:167], v[212:215], v[10:13]
	v_mfma_f32_16x16x32_bf16 v[62:65], v[160:163], v[192:195], v[62:65]
	v_mfma_f32_16x16x32_bf16 v[58:61], v[168:171], v[192:195], v[58:61]
	v_mfma_f32_16x16x32_bf16 v[46:49], v[160:163], v[200:203], v[46:49]
	v_mfma_f32_16x16x32_bf16 v[42:45], v[168:171], v[200:203], v[42:45]
	v_mfma_f32_16x16x32_bf16 v[30:33], v[160:163], v[208:211], v[30:33]
	v_mfma_f32_16x16x32_bf16 v[26:29], v[168:171], v[208:211], v[26:29]
	v_mfma_f32_16x16x32_bf16 v[14:17], v[160:163], v[216:219], v[14:17]
	v_mfma_f32_16x16x32_bf16 v[10:13], v[168:171], v[216:219], v[10:13]
	s_setprio 0
	s_setprio 1
	v_mfma_f32_16x16x32_bf16 v[54:57], v[172:175], v[188:191], v[54:57]
	v_mfma_f32_16x16x32_bf16 v[50:53], v[180:183], v[188:191], v[50:53]
	v_mfma_f32_16x16x32_bf16 v[38:41], v[172:175], v[196:199], v[38:41]
	v_mfma_f32_16x16x32_bf16 v[34:37], v[180:183], v[196:199], v[34:37]
	v_mfma_f32_16x16x32_bf16 v[22:25], v[172:175], v[204:207], v[22:25]
	v_mfma_f32_16x16x32_bf16 v[18:21], v[180:183], v[204:207], v[18:21]
	v_mfma_f32_16x16x32_bf16 v[6:9], v[172:175], v[212:215], v[6:9]
	v_mfma_f32_16x16x32_bf16 v[2:5], v[180:183], v[212:215], v[2:5]
	v_mfma_f32_16x16x32_bf16 v[54:57], v[176:179], v[192:195], v[54:57]
	v_mfma_f32_16x16x32_bf16 v[50:53], v[184:187], v[192:195], v[50:53]
	v_mfma_f32_16x16x32_bf16 v[38:41], v[176:179], v[200:203], v[38:41]
	v_mfma_f32_16x16x32_bf16 v[34:37], v[184:187], v[200:203], v[34:37]
	v_mfma_f32_16x16x32_bf16 v[22:25], v[176:179], v[208:211], v[22:25]
	v_mfma_f32_16x16x32_bf16 v[18:21], v[184:187], v[208:211], v[18:21]
	v_mfma_f32_16x16x32_bf16 v[6:9], v[176:179], v[216:219], v[6:9]
	v_mfma_f32_16x16x32_bf16 v[2:5], v[184:187], v[216:219], v[2:5]
	s_setprio 0
	s_barrier
	s_add_i32 s74, 0, 0x18000
	s_add_i32 s75, 0, 0x1c000
	v_add_u32_e32 v168, s74, v151
	v_add_u32_e32 v184, s75, v151
	ds_read_b128 v[156:159], v168
	ds_read_b128 v[160:163], v168 offset:1024
	ds_read_b128 v[164:167], v168 offset:2048
	ds_read_b128 v[168:171], v168 offset:3072
	ds_read_b128 v[172:175], v184
	ds_read_b128 v[176:179], v184 offset:1024
	ds_read_b128 v[180:183], v184 offset:2048
	ds_read_b128 v[184:187], v184 offset:3072
	s_add_u32 s52, s52, 0x40000
	s_addc_u32 s53, s53, 0
	s_mov_b32 m0, s59
	v_lshl_add_u64 v[226:227], s[52:53], 0, v[136:137]
	ds_read_b128 v[188:191], v154 offset:32768
	ds_read_b128 v[192:195], v154 offset:33792
	ds_read_b128 v[196:199], v154 offset:34816
	ds_read_b128 v[200:203], v154 offset:35840
	ds_read_b128 v[204:207], v154 offset:36864
	ds_read_b128 v[208:211], v154 offset:37888
	ds_read_b128 v[212:215], v154 offset:38912
	ds_read_b128 v[216:219], v154 offset:39936
	global_load_lds_dwordx4 v[226:227], off
	v_lshl_add_u64 v[226:227], s[52:53], 0, v[132:133]
	s_mov_b32 m0, s60
	s_nop 0
	global_load_lds_dwordx4 v[226:227], off
	s_waitcnt vmcnt(8)
	s_waitcnt lgkmcnt(0)
	s_setprio 1
	s_barrier
	v_mfma_f32_16x16x32_bf16 v[126:129], v[156:159], v[188:191], v[126:129]
	v_mfma_f32_16x16x32_bf16 v[122:125], v[164:167], v[188:191], v[122:125]
	v_mfma_f32_16x16x32_bf16 v[110:113], v[156:159], v[196:199], v[110:113]
	v_mfma_f32_16x16x32_bf16 v[106:109], v[164:167], v[196:199], v[106:109]
	v_mfma_f32_16x16x32_bf16 v[94:97], v[156:159], v[204:207], v[94:97]
	v_mfma_f32_16x16x32_bf16 v[90:93], v[164:167], v[204:207], v[90:93]
	v_mfma_f32_16x16x32_bf16 v[78:81], v[156:159], v[212:215], v[78:81]
	v_mfma_f32_16x16x32_bf16 v[74:77], v[164:167], v[212:215], v[74:77]
	v_mfma_f32_16x16x32_bf16 v[126:129], v[160:163], v[192:195], v[126:129]
	v_mfma_f32_16x16x32_bf16 v[122:125], v[168:171], v[192:195], v[122:125]
	v_mfma_f32_16x16x32_bf16 v[110:113], v[160:163], v[200:203], v[110:113]
	v_mfma_f32_16x16x32_bf16 v[106:109], v[168:171], v[200:203], v[106:109]
	v_mfma_f32_16x16x32_bf16 v[94:97], v[160:163], v[208:211], v[94:97]
	v_mfma_f32_16x16x32_bf16 v[90:93], v[168:171], v[208:211], v[90:93]
	v_mfma_f32_16x16x32_bf16 v[78:81], v[160:163], v[216:219], v[78:81]
	v_mfma_f32_16x16x32_bf16 v[74:77], v[168:171], v[216:219], v[74:77]
	s_setprio 0
	s_setprio 1
	v_mfma_f32_16x16x32_bf16 v[118:121], v[172:175], v[188:191], v[118:121]
	v_mfma_f32_16x16x32_bf16 v[114:117], v[180:183], v[188:191], v[114:117]
	v_mfma_f32_16x16x32_bf16 v[102:105], v[172:175], v[196:199], v[102:105]
	v_mfma_f32_16x16x32_bf16 v[98:101], v[180:183], v[196:199], v[98:101]
	v_mfma_f32_16x16x32_bf16 v[86:89], v[172:175], v[204:207], v[86:89]
	v_mfma_f32_16x16x32_bf16 v[82:85], v[180:183], v[204:207], v[82:85]
	v_mfma_f32_16x16x32_bf16 v[70:73], v[172:175], v[212:215], v[70:73]
	v_mfma_f32_16x16x32_bf16 v[66:69], v[180:183], v[212:215], v[66:69]
	v_mfma_f32_16x16x32_bf16 v[118:121], v[176:179], v[192:195], v[118:121]
	v_mfma_f32_16x16x32_bf16 v[114:117], v[184:187], v[192:195], v[114:117]
	v_mfma_f32_16x16x32_bf16 v[102:105], v[176:179], v[200:203], v[102:105]
	v_mfma_f32_16x16x32_bf16 v[98:101], v[184:187], v[200:203], v[98:101]
	v_mfma_f32_16x16x32_bf16 v[86:89], v[176:179], v[208:211], v[86:89]
	v_mfma_f32_16x16x32_bf16 v[82:85], v[184:187], v[208:211], v[82:85]
	v_mfma_f32_16x16x32_bf16 v[70:73], v[176:179], v[216:219], v[70:73]
	v_mfma_f32_16x16x32_bf16 v[66:69], v[184:187], v[216:219], v[66:69]
	s_setprio 0
	s_barrier
	s_add_i32 s52, s74, s54
	v_lshl_add_u64 v[148:149], v[148:149], 0, s[16:17]
	s_mov_b32 m0, s52
	ds_read_b128 v[188:191], v154 offset:49152
	ds_read_b128 v[192:195], v154 offset:50176
	ds_read_b128 v[196:199], v154 offset:51200
	ds_read_b128 v[200:203], v154 offset:52224
	ds_read_b128 v[204:207], v154 offset:53248
	ds_read_b128 v[208:211], v154 offset:54272
	ds_read_b128 v[212:215], v154 offset:55296
	ds_read_b128 v[216:219], v154 offset:56320
	global_load_lds_dwordx4 v[148:149], off
	s_add_i32 m0, s52, 0x2000
	s_add_u32 s50, s50, 0x40080
	v_lshl_add_u64 v[148:149], v[220:221], 0, s[16:17]
	s_addc_u32 s51, s51, 0
	s_add_i32 s52, s75, s54
	global_load_lds_dwordx4 v[148:149], off
	v_lshl_add_u64 v[148:149], s[50:51], 0, v[134:135]
	s_mov_b32 m0, s52
	s_nop 0
	global_load_lds_dwordx4 v[148:149], off
	v_lshl_add_u64 v[148:149], s[50:51], 0, v[130:131]
	s_add_i32 m0, s52, 0x2000
	s_nop 0
	global_load_lds_dwordx4 v[148:149], off
	v_lshl_add_u64 v[148:149], v[222:223], 0, s[16:17]
	s_mov_b32 m0, s63
	s_nop 0
	global_load_lds_dwordx4 v[148:149], off
	v_lshl_add_u64 v[148:149], v[224:225], 0, s[16:17]
	s_mov_b32 m0, s64
	s_nop 0
	global_load_lds_dwordx4 v[148:149], off
	s_waitcnt vmcnt(8)
	s_waitcnt lgkmcnt(0)
	s_setprio 1
	s_barrier
	v_mfma_f32_16x16x32_bf16 v[62:65], v[156:159], v[188:191], v[62:65]
	v_mfma_f32_16x16x32_bf16 v[58:61], v[164:167], v[188:191], v[58:61]
	v_mfma_f32_16x16x32_bf16 v[46:49], v[156:159], v[196:199], v[46:49]
	v_mfma_f32_16x16x32_bf16 v[42:45], v[164:167], v[196:199], v[42:45]
	v_mfma_f32_16x16x32_bf16 v[30:33], v[156:159], v[204:207], v[30:33]
	v_mfma_f32_16x16x32_bf16 v[26:29], v[164:167], v[204:207], v[26:29]
	v_mfma_f32_16x16x32_bf16 v[14:17], v[156:159], v[212:215], v[14:17]
	v_mfma_f32_16x16x32_bf16 v[10:13], v[164:167], v[212:215], v[10:13]
	v_mfma_f32_16x16x32_bf16 v[62:65], v[160:163], v[192:195], v[62:65]
	v_mfma_f32_16x16x32_bf16 v[58:61], v[168:171], v[192:195], v[58:61]
	v_mfma_f32_16x16x32_bf16 v[46:49], v[160:163], v[200:203], v[46:49]
	v_mfma_f32_16x16x32_bf16 v[42:45], v[168:171], v[200:203], v[42:45]
	v_mfma_f32_16x16x32_bf16 v[30:33], v[160:163], v[208:211], v[30:33]
	v_mfma_f32_16x16x32_bf16 v[26:29], v[168:171], v[208:211], v[26:29]
	v_mfma_f32_16x16x32_bf16 v[14:17], v[160:163], v[216:219], v[14:17]
	v_mfma_f32_16x16x32_bf16 v[10:13], v[168:171], v[216:219], v[10:13]
	s_setprio 0
	s_setprio 1
	v_mfma_f32_16x16x32_bf16 v[54:57], v[172:175], v[188:191], v[54:57]
	v_mfma_f32_16x16x32_bf16 v[50:53], v[180:183], v[188:191], v[50:53]
	v_mfma_f32_16x16x32_bf16 v[38:41], v[172:175], v[196:199], v[38:41]
	v_mfma_f32_16x16x32_bf16 v[34:37], v[180:183], v[196:199], v[34:37]
	v_mfma_f32_16x16x32_bf16 v[22:25], v[172:175], v[204:207], v[22:25]
	v_mfma_f32_16x16x32_bf16 v[18:21], v[180:183], v[204:207], v[18:21]
	v_mfma_f32_16x16x32_bf16 v[6:9], v[172:175], v[212:215], v[6:9]
	v_mfma_f32_16x16x32_bf16 v[2:5], v[180:183], v[212:215], v[2:5]
	v_mfma_f32_16x16x32_bf16 v[54:57], v[176:179], v[192:195], v[54:57]
	v_mfma_f32_16x16x32_bf16 v[50:53], v[184:187], v[192:195], v[50:53]
	v_mfma_f32_16x16x32_bf16 v[38:41], v[176:179], v[200:203], v[38:41]
	v_mfma_f32_16x16x32_bf16 v[34:37], v[184:187], v[200:203], v[34:37]
	v_mfma_f32_16x16x32_bf16 v[22:25], v[176:179], v[208:211], v[22:25]
	v_mfma_f32_16x16x32_bf16 v[18:21], v[184:187], v[208:211], v[18:21]
	v_mfma_f32_16x16x32_bf16 v[6:9], v[176:179], v[216:219], v[6:9]
	v_mfma_f32_16x16x32_bf16 v[2:5], v[184:187], v[216:219], v[2:5]
	s_setprio 0
	s_barrier
	s_add_i32 s73, s73, 2
	s_add_u32 s48, s48, 0x100
	s_addc_u32 s49, s49, 0
	s_add_u32 s71, s71, 0x100
	s_addc_u32 s72, s72, 0
	s_cmp_gt_u32 s73, 13
	s_cbranch_scc0 .LBB0_352
	s_and_b64 vcc, exec, s[24:25]
	s_cbranch_vccz .LBB0_355
	s_barrier

.LBB0_739:
	ds_read_b128 v[122:125], v245
	ds_read_b128 v[126:129], v245 offset:1024
	ds_read_b128 v[130:133], v245 offset:2048
	ds_read_b128 v[134:137], v245 offset:3072
	ds_read_b128 v[138:141], v246
	ds_read_b128 v[142:145], v246 offset:1024
	ds_read_b128 v[146:149], v246 offset:2048
	ds_read_b128 v[158:161], v246 offset:3072
	s_add_u32 s54, s52, 0xfffc0080
	s_addc_u32 s55, s53, -1
	s_cmp_eq_u32 s73, 12
	s_cselect_b32 s57, s43, s55
	s_cselect_b32 s56, s49, s54
	s_cselect_b32 s55, s27, s72
	s_cselect_b32 s54, s51, s71
	v_lshl_add_u64 v[210:211], s[52:53], 0, v[206:207]
	s_add_i32 m0, s59, 0xc000
	ds_read_b128 v[162:165], v247
	ds_read_b128 v[166:169], v247 offset:1024
	ds_read_b128 v[170:173], v247 offset:2048
	ds_read_b128 v[174:177], v247 offset:3072
	ds_read_b128 v[178:181], v247 offset:4096
	ds_read_b128 v[182:185], v247 offset:5120
	ds_read_b128 v[186:189], v247 offset:6144
	ds_read_b128 v[190:193], v247 offset:7168
	global_load_lds_dwordx4 v[210:211], off
	v_lshl_add_u64 v[210:211], s[52:53], 0, v[208:209]
	s_add_i32 m0, s59, 0xe000
	s_nop 0
	global_load_lds_dwordx4 v[210:211], off
	s_waitcnt vmcnt(8)
	s_waitcnt lgkmcnt(0)
	s_setprio 1
	s_barrier
	v_mfma_f32_16x16x32_bf16 v[154:157], v[122:125], v[162:165], v[154:157]
	v_mfma_f32_16x16x32_bf16 v[150:153], v[130:133], v[162:165], v[150:153]
	v_mfma_f32_16x16x32_bf16 v[110:113], v[122:125], v[170:173], v[110:113]
	v_mfma_f32_16x16x32_bf16 v[106:109], v[130:133], v[170:173], v[106:109]
	v_mfma_f32_16x16x32_bf16 v[94:97], v[122:125], v[178:181], v[94:97]
	v_mfma_f32_16x16x32_bf16 v[90:93], v[130:133], v[178:181], v[90:93]
	v_mfma_f32_16x16x32_bf16 v[78:81], v[122:125], v[186:189], v[78:81]
	v_mfma_f32_16x16x32_bf16 v[74:77], v[130:133], v[186:189], v[74:77]
	v_mfma_f32_16x16x32_bf16 v[154:157], v[126:129], v[166:169], v[154:157]
	v_mfma_f32_16x16x32_bf16 v[150:153], v[134:137], v[166:169], v[150:153]
	v_mfma_f32_16x16x32_bf16 v[110:113], v[126:129], v[174:177], v[110:113]
	v_mfma_f32_16x16x32_bf16 v[106:109], v[134:137], v[174:177], v[106:109]
	v_mfma_f32_16x16x32_bf16 v[94:97], v[126:129], v[182:185], v[94:97]
	v_mfma_f32_16x16x32_bf16 v[90:93], v[134:137], v[182:185], v[90:93]
	v_mfma_f32_16x16x32_bf16 v[78:81], v[126:129], v[190:193], v[78:81]
	v_mfma_f32_16x16x32_bf16 v[74:77], v[134:137], v[190:193], v[74:77]
	s_setprio 0
	s_setprio 1
	v_mfma_f32_16x16x32_bf16 v[118:121], v[138:141], v[162:165], v[118:121]
	v_mfma_f32_16x16x32_bf16 v[114:117], v[146:149], v[162:165], v[114:117]
	v_mfma_f32_16x16x32_bf16 v[102:105], v[138:141], v[170:173], v[102:105]
	v_mfma_f32_16x16x32_bf16 v[98:101], v[146:149], v[170:173], v[98:101]
	v_mfma_f32_16x16x32_bf16 v[86:89], v[138:141], v[178:181], v[86:89]
	v_mfma_f32_16x16x32_bf16 v[82:85], v[146:149], v[178:181], v[82:85]
	v_mfma_f32_16x16x32_bf16 v[70:73], v[138:141], v[186:189], v[70:73]
	v_mfma_f32_16x16x32_bf16 v[66:69], v[146:149], v[186:189], v[66:69]
	v_mfma_f32_16x16x32_bf16 v[118:121], v[142:145], v[166:169], v[118:121]
	v_mfma_f32_16x16x32_bf16 v[114:117], v[158:161], v[166:169], v[114:117]
	v_mfma_f32_16x16x32_bf16 v[102:105], v[142:145], v[174:177], v[102:105]
	v_mfma_f32_16x16x32_bf16 v[98:101], v[158:161], v[174:177], v[98:101]
	v_mfma_f32_16x16x32_bf16 v[86:89], v[142:145], v[182:185], v[86:89]
	v_mfma_f32_16x16x32_bf16 v[82:85], v[158:161], v[182:185], v[82:85]
	v_mfma_f32_16x16x32_bf16 v[70:73], v[142:145], v[190:193], v[70:73]
	v_mfma_f32_16x16x32_bf16 v[66:69], v[158:161], v[190:193], v[66:69]
	s_setprio 0
	s_barrier
	s_add_i32 s74, s69, s58
	v_lshl_add_u64 v[210:211], s[54:55], 0, v[196:197]
	s_mov_b32 m0, s74
	ds_read_b128 v[162:165], v247 offset:16384
	ds_read_b128 v[166:169], v247 offset:17408
	ds_read_b128 v[170:173], v247 offset:18432
	ds_read_b128 v[174:177], v247 offset:19456
	ds_read_b128 v[178:181], v247 offset:20480
	ds_read_b128 v[182:185], v247 offset:21504
	ds_read_b128 v[186:189], v247 offset:22528
	ds_read_b128 v[190:193], v247 offset:23552
	global_load_lds_dwordx4 v[210:211], off
	s_add_i32 m0, s74, 0x2000
	s_add_u32 s74, s54, 0x40000
	v_lshl_add_u64 v[212:213], s[54:55], 0, v[200:201]
	s_addc_u32 s75, s55, 0
	s_add_i32 s76, s70, s58
	global_load_lds_dwordx4 v[212:213], off
	v_lshl_add_u64 v[214:215], s[74:75], 0, v[196:197]
	s_mov_b32 m0, s76
	v_lshl_add_u64 v[216:217], s[56:57], 0, v[198:199]
	global_load_lds_dwordx4 v[214:215], off
	v_lshl_add_u64 v[214:215], s[74:75], 0, v[200:201]
	s_add_i32 m0, s76, 0x2000
	s_nop 0
	global_load_lds_dwordx4 v[214:215], off
	v_lshl_add_u64 v[214:215], s[56:57], 0, v[194:195]
	s_mov_b32 m0, s59
	s_nop 0
	global_load_lds_dwordx4 v[214:215], off
	s_mov_b32 m0, s60
	s_nop 0
	global_load_lds_dwordx4 v[216:217], off
	s_waitcnt vmcnt(8)
	s_waitcnt lgkmcnt(0)
	s_setprio 1
	s_barrier
	v_mfma_f32_16x16x32_bf16 v[62:65], v[122:125], v[162:165], v[62:65]
	v_mfma_f32_16x16x32_bf16 v[58:61], v[130:133], v[162:165], v[58:61]
	v_mfma_f32_16x16x32_bf16 v[46:49], v[122:125], v[170:173], v[46:49]
	v_mfma_f32_16x16x32_bf16 v[42:45], v[130:133], v[170:173], v[42:45]
	v_mfma_f32_16x16x32_bf16 v[30:33], v[122:125], v[178:181], v[30:33]
	v_mfma_f32_16x16x32_bf16 v[26:29], v[130:133], v[178:181], v[26:29]
	v_mfma_f32_16x16x32_bf16 v[14:17], v[122:125], v[186:189], v[14:17]
	v_mfma_f32_16x16x32_bf16 v[10:13], v[130:133], v[186:189], v[10:13]
	v_mfma_f32_16x16x32_bf16 v[62:65], v[126:129], v[166:169], v[62:65]
	v_mfma_f32_16x16x32_bf16 v[58:61], v[134:137], v[166:169], v[58:61]
	v_mfma_f32_16x16x32_bf16 v[46:49], v[126:129], v[174:177], v[46:49]
	v_mfma_f32_16x16x32_bf16 v[42:45], v[134:137], v[174:177], v[42:45]
	v_mfma_f32_16x16x32_bf16 v[30:33], v[126:129], v[182:185], v[30:33]
	v_mfma_f32_16x16x32_bf16 v[26:29], v[134:137], v[182:185], v[26:29]
	v_mfma_f32_16x16x32_bf16 v[14:17], v[126:129], v[190:193], v[14:17]
	v_mfma_f32_16x16x32_bf16 v[10:13], v[134:137], v[190:193], v[10:13]
	s_setprio 0
	s_setprio 1
	v_mfma_f32_16x16x32_bf16 v[54:57], v[138:141], v[162:165], v[54:57]
	v_mfma_f32_16x16x32_bf16 v[50:53], v[146:149], v[162:165], v[50:53]
	v_mfma_f32_16x16x32_bf16 v[38:41], v[138:141], v[170:173], v[38:41]
	v_mfma_f32_16x16x32_bf16 v[34:37], v[146:149], v[170:173], v[34:37]
	v_mfma_f32_16x16x32_bf16 v[22:25], v[138:141], v[178:181], v[22:25]
	v_mfma_f32_16x16x32_bf16 v[18:21], v[146:149], v[178:181], v[18:21]
	v_mfma_f32_16x16x32_bf16 v[6:9], v[138:141], v[186:189], v[6:9]
	v_mfma_f32_16x16x32_bf16 v[2:5], v[146:149], v[186:189], v[2:5]
	v_mfma_f32_16x16x32_bf16 v[54:57], v[142:145], v[166:169], v[54:57]
	v_mfma_f32_16x16x32_bf16 v[50:53], v[158:161], v[166:169], v[50:53]
	v_mfma_f32_16x16x32_bf16 v[38:41], v[142:145], v[174:177], v[38:41]
	v_mfma_f32_16x16x32_bf16 v[34:37], v[158:161], v[174:177], v[34:37]
	v_mfma_f32_16x16x32_bf16 v[22:25], v[142:145], v[182:185], v[22:25]
	v_mfma_f32_16x16x32_bf16 v[18:21], v[158:161], v[182:185], v[18:21]
	v_mfma_f32_16x16x32_bf16 v[6:9], v[142:145], v[190:193], v[6:9]
	v_mfma_f32_16x16x32_bf16 v[2:5], v[158:161], v[190:193], v[2:5]
	s_setprio 0
	s_barrier
	s_add_i32 s74, 0, 0x18000
	s_add_i32 s75, 0, 0x1c000
	v_add_u32_e32 v134, s74, v244
	v_add_u32_e32 v158, s75, v244
	ds_read_b128 v[122:125], v134
	ds_read_b128 v[126:129], v134 offset:1024
	ds_read_b128 v[130:133], v134 offset:2048
	ds_read_b128 v[134:137], v134 offset:3072
	ds_read_b128 v[138:141], v158
	ds_read_b128 v[142:145], v158 offset:1024
	ds_read_b128 v[146:149], v158 offset:2048
	ds_read_b128 v[158:161], v158 offset:3072
	s_add_u32 s56, s56, 0x40000
	s_addc_u32 s57, s57, 0
	s_mov_b32 m0, s61
	v_lshl_add_u64 v[218:219], s[56:57], 0, v[194:195]
	ds_read_b128 v[162:165], v247 offset:32768
	ds_read_b128 v[166:169], v247 offset:33792
	ds_read_b128 v[170:173], v247 offset:34816
	ds_read_b128 v[174:177], v247 offset:35840
	ds_read_b128 v[178:181], v247 offset:36864
	ds_read_b128 v[182:185], v247 offset:37888
	ds_read_b128 v[186:189], v247 offset:38912
	ds_read_b128 v[190:193], v247 offset:39936
	global_load_lds_dwordx4 v[218:219], off
	v_lshl_add_u64 v[218:219], s[56:57], 0, v[198:199]
	s_mov_b32 m0, s62
	s_nop 0
	global_load_lds_dwordx4 v[218:219], off
	s_waitcnt vmcnt(8)
	s_waitcnt lgkmcnt(0)
	s_setprio 1
	s_barrier
	v_mfma_f32_16x16x32_bf16 v[154:157], v[122:125], v[162:165], v[154:157]
	v_mfma_f32_16x16x32_bf16 v[150:153], v[130:133], v[162:165], v[150:153]
	v_mfma_f32_16x16x32_bf16 v[110:113], v[122:125], v[170:173], v[110:113]
	v_mfma_f32_16x16x32_bf16 v[106:109], v[130:133], v[170:173], v[106:109]
	v_mfma_f32_16x16x32_bf16 v[94:97], v[122:125], v[178:181], v[94:97]
	v_mfma_f32_16x16x32_bf16 v[90:93], v[130:133], v[178:181], v[90:93]
	v_mfma_f32_16x16x32_bf16 v[78:81], v[122:125], v[186:189], v[78:81]
	v_mfma_f32_16x16x32_bf16 v[74:77], v[130:133], v[186:189], v[74:77]
	v_mfma_f32_16x16x32_bf16 v[154:157], v[126:129], v[166:169], v[154:157]
	v_mfma_f32_16x16x32_bf16 v[150:153], v[134:137], v[166:169], v[150:153]
	v_mfma_f32_16x16x32_bf16 v[110:113], v[126:129], v[174:177], v[110:113]
	v_mfma_f32_16x16x32_bf16 v[106:109], v[134:137], v[174:177], v[106:109]
	v_mfma_f32_16x16x32_bf16 v[94:97], v[126:129], v[182:185], v[94:97]
	v_mfma_f32_16x16x32_bf16 v[90:93], v[134:137], v[182:185], v[90:93]
	v_mfma_f32_16x16x32_bf16 v[78:81], v[126:129], v[190:193], v[78:81]
	v_mfma_f32_16x16x32_bf16 v[74:77], v[134:137], v[190:193], v[74:77]
	s_setprio 0
	s_setprio 1
	v_mfma_f32_16x16x32_bf16 v[118:121], v[138:141], v[162:165], v[118:121]
	v_mfma_f32_16x16x32_bf16 v[114:117], v[146:149], v[162:165], v[114:117]
	v_mfma_f32_16x16x32_bf16 v[102:105], v[138:141], v[170:173], v[102:105]
	v_mfma_f32_16x16x32_bf16 v[98:101], v[146:149], v[170:173], v[98:101]
	v_mfma_f32_16x16x32_bf16 v[86:89], v[138:141], v[178:181], v[86:89]
	v_mfma_f32_16x16x32_bf16 v[82:85], v[146:149], v[178:181], v[82:85]
	v_mfma_f32_16x16x32_bf16 v[70:73], v[138:141], v[186:189], v[70:73]
	v_mfma_f32_16x16x32_bf16 v[66:69], v[146:149], v[186:189], v[66:69]
	v_mfma_f32_16x16x32_bf16 v[118:121], v[142:145], v[166:169], v[118:121]
	v_mfma_f32_16x16x32_bf16 v[114:117], v[158:161], v[166:169], v[114:117]
	v_mfma_f32_16x16x32_bf16 v[102:105], v[142:145], v[174:177], v[102:105]
	v_mfma_f32_16x16x32_bf16 v[98:101], v[158:161], v[174:177], v[98:101]
	v_mfma_f32_16x16x32_bf16 v[86:89], v[142:145], v[182:185], v[86:89]
	v_mfma_f32_16x16x32_bf16 v[82:85], v[158:161], v[182:185], v[82:85]
	v_mfma_f32_16x16x32_bf16 v[70:73], v[142:145], v[190:193], v[70:73]
	v_mfma_f32_16x16x32_bf16 v[66:69], v[158:161], v[190:193], v[66:69]
	s_setprio 0
	s_barrier
	s_add_i32 s56, s74, s58
	v_lshl_add_u64 v[210:211], v[210:211], 0, s[16:17]
	s_mov_b32 m0, s56
	ds_read_b128 v[162:165], v247 offset:49152
	ds_read_b128 v[166:169], v247 offset:50176
	ds_read_b128 v[170:173], v247 offset:51200
	ds_read_b128 v[174:177], v247 offset:52224
	ds_read_b128 v[178:181], v247 offset:53248
	ds_read_b128 v[182:185], v247 offset:54272
	ds_read_b128 v[186:189], v247 offset:55296
	ds_read_b128 v[190:193], v247 offset:56320
	global_load_lds_dwordx4 v[210:211], off
	s_add_i32 m0, s56, 0x2000
	s_add_u32 s54, s54, 0x40080
	v_lshl_add_u64 v[210:211], v[212:213], 0, s[16:17]
	s_addc_u32 s55, s55, 0
	s_add_i32 s56, s75, s58
	global_load_lds_dwordx4 v[210:211], off
	v_lshl_add_u64 v[210:211], s[54:55], 0, v[196:197]
	s_mov_b32 m0, s56
	s_nop 0
	global_load_lds_dwordx4 v[210:211], off
	v_lshl_add_u64 v[210:211], s[54:55], 0, v[200:201]
	s_add_i32 m0, s56, 0x2000
	s_nop 0
	global_load_lds_dwordx4 v[210:211], off
	v_lshl_add_u64 v[210:211], v[214:215], 0, s[16:17]
	s_mov_b32 m0, s64
	s_nop 0
	global_load_lds_dwordx4 v[210:211], off
	v_lshl_add_u64 v[210:211], v[216:217], 0, s[16:17]
	s_mov_b32 m0, s65
	s_nop 0
	global_load_lds_dwordx4 v[210:211], off
	s_waitcnt vmcnt(8)
	s_waitcnt lgkmcnt(0)
	s_setprio 1
	s_barrier
	v_mfma_f32_16x16x32_bf16 v[62:65], v[122:125], v[162:165], v[62:65]
	v_mfma_f32_16x16x32_bf16 v[58:61], v[130:133], v[162:165], v[58:61]
	v_mfma_f32_16x16x32_bf16 v[46:49], v[122:125], v[170:173], v[46:49]
	v_mfma_f32_16x16x32_bf16 v[42:45], v[130:133], v[170:173], v[42:45]
	v_mfma_f32_16x16x32_bf16 v[30:33], v[122:125], v[178:181], v[30:33]
	v_mfma_f32_16x16x32_bf16 v[26:29], v[130:133], v[178:181], v[26:29]
	v_mfma_f32_16x16x32_bf16 v[14:17], v[122:125], v[186:189], v[14:17]
	v_mfma_f32_16x16x32_bf16 v[10:13], v[130:133], v[186:189], v[10:13]
	v_mfma_f32_16x16x32_bf16 v[62:65], v[126:129], v[166:169], v[62:65]
	v_mfma_f32_16x16x32_bf16 v[58:61], v[134:137], v[166:169], v[58:61]
	v_mfma_f32_16x16x32_bf16 v[46:49], v[126:129], v[174:177], v[46:49]
	v_mfma_f32_16x16x32_bf16 v[42:45], v[134:137], v[174:177], v[42:45]
	v_mfma_f32_16x16x32_bf16 v[30:33], v[126:129], v[182:185], v[30:33]
	v_mfma_f32_16x16x32_bf16 v[26:29], v[134:137], v[182:185], v[26:29]
	v_mfma_f32_16x16x32_bf16 v[14:17], v[126:129], v[190:193], v[14:17]
	v_mfma_f32_16x16x32_bf16 v[10:13], v[134:137], v[190:193], v[10:13]
	s_setprio 0
	s_setprio 1
	v_mfma_f32_16x16x32_bf16 v[54:57], v[138:141], v[162:165], v[54:57]
	v_mfma_f32_16x16x32_bf16 v[50:53], v[146:149], v[162:165], v[50:53]
	v_mfma_f32_16x16x32_bf16 v[38:41], v[138:141], v[170:173], v[38:41]
	v_mfma_f32_16x16x32_bf16 v[34:37], v[146:149], v[170:173], v[34:37]
	v_mfma_f32_16x16x32_bf16 v[22:25], v[138:141], v[178:181], v[22:25]
	v_mfma_f32_16x16x32_bf16 v[18:21], v[146:149], v[178:181], v[18:21]
	v_mfma_f32_16x16x32_bf16 v[6:9], v[138:141], v[186:189], v[6:9]
	v_mfma_f32_16x16x32_bf16 v[2:5], v[146:149], v[186:189], v[2:5]
	v_mfma_f32_16x16x32_bf16 v[54:57], v[142:145], v[166:169], v[54:57]
	v_mfma_f32_16x16x32_bf16 v[50:53], v[158:161], v[166:169], v[50:53]
	v_mfma_f32_16x16x32_bf16 v[38:41], v[142:145], v[174:177], v[38:41]
	v_mfma_f32_16x16x32_bf16 v[34:37], v[158:161], v[174:177], v[34:37]
	v_mfma_f32_16x16x32_bf16 v[22:25], v[142:145], v[182:185], v[22:25]
	v_mfma_f32_16x16x32_bf16 v[18:21], v[158:161], v[182:185], v[18:21]
	v_mfma_f32_16x16x32_bf16 v[6:9], v[142:145], v[190:193], v[6:9]
	v_mfma_f32_16x16x32_bf16 v[2:5], v[158:161], v[190:193], v[2:5]
	s_setprio 0
	s_barrier
	s_add_i32 s73, s73, 2
	s_add_u32 s52, s52, 0x100
	s_addc_u32 s53, s53, 0
	s_add_u32 s71, s71, 0x100
	s_addc_u32 s72, s72, 0
	s_cmp_gt_u32 s73, 13
	s_cbranch_scc0 .LBB0_739
	s_and_b64 vcc, exec, s[24:25]
	s_cbranch_vccz .LBB0_742
	s_barrier

.LBB0_840:
	ds_read_b128 v[160:163], v155
	ds_read_b128 v[164:167], v155 offset:1024
	ds_read_b128 v[168:171], v155 offset:2048
	ds_read_b128 v[172:175], v155 offset:3072
	ds_read_b128 v[176:179], v156
	ds_read_b128 v[180:183], v156 offset:1024
	ds_read_b128 v[184:187], v156 offset:2048
	ds_read_b128 v[188:191], v156 offset:3072
	s_add_u32 s50, s48, 0xfffc0080
	s_addc_u32 s51, s49, -1
	s_cmp_eq_u32 s73, 12
	s_cselect_b32 s53, s27, s51
	s_cselect_b32 s52, s69, s50
	s_cselect_b32 s51, s25, s72
	s_cselect_b32 s50, s70, s71
	v_lshl_add_u64 v[148:149], s[48:49], 0, v[140:141]
	s_add_i32 m0, s57, 0xc000
	ds_read_b128 v[192:195], v157
	ds_read_b128 v[196:199], v157 offset:1024
	ds_read_b128 v[200:203], v157 offset:2048
	ds_read_b128 v[204:207], v157 offset:3072
	ds_read_b128 v[208:211], v157 offset:4096
	ds_read_b128 v[212:215], v157 offset:5120
	ds_read_b128 v[216:219], v157 offset:6144
	ds_read_b128 v[220:223], v157 offset:7168
	global_load_lds_dwordx4 v[148:149], off
	v_lshl_add_u64 v[148:149], s[48:49], 0, v[142:143]
	s_add_i32 m0, s57, 0xe000
	s_nop 0
	global_load_lds_dwordx4 v[148:149], off
	s_waitcnt vmcnt(8)
	s_waitcnt lgkmcnt(0)
	s_setprio 1
	s_barrier
	v_mfma_f32_16x16x32_bf16 v[118:121], v[160:163], v[192:195], v[118:121]
	v_mfma_f32_16x16x32_bf16 v[114:117], v[168:171], v[192:195], v[114:117]
	v_mfma_f32_16x16x32_bf16 v[106:109], v[160:163], v[200:203], v[106:109]
	v_mfma_f32_16x16x32_bf16 v[98:101], v[168:171], v[200:203], v[98:101]
	v_mfma_f32_16x16x32_bf16 v[90:93], v[160:163], v[208:211], v[90:93]
	v_mfma_f32_16x16x32_bf16 v[82:85], v[168:171], v[208:211], v[82:85]
	v_mfma_f32_16x16x32_bf16 v[74:77], v[160:163], v[216:219], v[74:77]
	v_mfma_f32_16x16x32_bf16 v[66:69], v[168:171], v[216:219], v[66:69]
	v_mfma_f32_16x16x32_bf16 v[118:121], v[164:167], v[196:199], v[118:121]
	v_mfma_f32_16x16x32_bf16 v[114:117], v[172:175], v[196:199], v[114:117]
	v_mfma_f32_16x16x32_bf16 v[106:109], v[164:167], v[204:207], v[106:109]
	v_mfma_f32_16x16x32_bf16 v[98:101], v[172:175], v[204:207], v[98:101]
	v_mfma_f32_16x16x32_bf16 v[90:93], v[164:167], v[212:215], v[90:93]
	v_mfma_f32_16x16x32_bf16 v[82:85], v[172:175], v[212:215], v[82:85]
	v_mfma_f32_16x16x32_bf16 v[74:77], v[164:167], v[220:223], v[74:77]
	v_mfma_f32_16x16x32_bf16 v[66:69], v[172:175], v[220:223], v[66:69]
	s_setprio 0
	s_setprio 1
	v_mfma_f32_16x16x32_bf16 v[126:129], v[176:179], v[192:195], v[126:129]
	v_mfma_f32_16x16x32_bf16 v[122:125], v[184:187], v[192:195], v[122:125]
	v_mfma_f32_16x16x32_bf16 v[110:113], v[176:179], v[200:203], v[110:113]
	v_mfma_f32_16x16x32_bf16 v[102:105], v[184:187], v[200:203], v[102:105]
	v_mfma_f32_16x16x32_bf16 v[94:97], v[176:179], v[208:211], v[94:97]
	v_mfma_f32_16x16x32_bf16 v[86:89], v[184:187], v[208:211], v[86:89]
	v_mfma_f32_16x16x32_bf16 v[78:81], v[176:179], v[216:219], v[78:81]
	v_mfma_f32_16x16x32_bf16 v[70:73], v[184:187], v[216:219], v[70:73]
	v_mfma_f32_16x16x32_bf16 v[126:129], v[180:183], v[196:199], v[126:129]
	v_mfma_f32_16x16x32_bf16 v[122:125], v[188:191], v[196:199], v[122:125]
	v_mfma_f32_16x16x32_bf16 v[110:113], v[180:183], v[204:207], v[110:113]
	v_mfma_f32_16x16x32_bf16 v[102:105], v[188:191], v[204:207], v[102:105]
	v_mfma_f32_16x16x32_bf16 v[94:97], v[180:183], v[212:215], v[94:97]
	v_mfma_f32_16x16x32_bf16 v[86:89], v[188:191], v[212:215], v[86:89]
	v_mfma_f32_16x16x32_bf16 v[78:81], v[180:183], v[220:223], v[78:81]
	v_mfma_f32_16x16x32_bf16 v[70:73], v[188:191], v[220:223], v[70:73]
	s_setprio 0
	s_barrier
	s_add_i32 s74, s66, s54
	v_lshl_add_u64 v[148:149], s[50:51], 0, v[134:135]
	s_mov_b32 m0, s74
	ds_read_b128 v[192:195], v157 offset:16384
	ds_read_b128 v[196:199], v157 offset:17408
	ds_read_b128 v[200:203], v157 offset:18432
	ds_read_b128 v[204:207], v157 offset:19456
	ds_read_b128 v[208:211], v157 offset:20480
	ds_read_b128 v[212:215], v157 offset:21504
	ds_read_b128 v[216:219], v157 offset:22528
	ds_read_b128 v[220:223], v157 offset:23552
	global_load_lds_dwordx4 v[148:149], off
	s_add_i32 m0, s74, 0x2000
	s_add_u32 s74, s50, 0x40000
	v_lshl_add_u64 v[224:225], s[50:51], 0, v[130:131]
	s_addc_u32 s75, s51, 0
	s_add_i32 s76, s67, s54
	global_load_lds_dwordx4 v[224:225], off
	v_lshl_add_u64 v[226:227], s[74:75], 0, v[134:135]
	s_mov_b32 m0, s76
	v_lshl_add_u64 v[228:229], s[52:53], 0, v[132:133]
	global_load_lds_dwordx4 v[226:227], off
	v_lshl_add_u64 v[226:227], s[74:75], 0, v[130:131]
	s_add_i32 m0, s76, 0x2000
	s_nop 0
	global_load_lds_dwordx4 v[226:227], off
	v_lshl_add_u64 v[226:227], s[52:53], 0, v[136:137]
	s_mov_b32 m0, s57
	s_nop 0
	global_load_lds_dwordx4 v[226:227], off
	s_mov_b32 m0, s58
	s_nop 0
	global_load_lds_dwordx4 v[228:229], off
	s_waitcnt vmcnt(8)
	s_waitcnt lgkmcnt(0)
	s_setprio 1
	s_barrier
	v_mfma_f32_16x16x32_bf16 v[58:61], v[160:163], v[192:195], v[58:61]
	v_mfma_f32_16x16x32_bf16 v[50:53], v[168:171], v[192:195], v[50:53]
	v_mfma_f32_16x16x32_bf16 v[42:45], v[160:163], v[200:203], v[42:45]
	v_mfma_f32_16x16x32_bf16 v[34:37], v[168:171], v[200:203], v[34:37]
	v_mfma_f32_16x16x32_bf16 v[26:29], v[160:163], v[208:211], v[26:29]
	v_mfma_f32_16x16x32_bf16 v[18:21], v[168:171], v[208:211], v[18:21]
	v_mfma_f32_16x16x32_bf16 v[10:13], v[160:163], v[216:219], v[10:13]
	v_mfma_f32_16x16x32_bf16 v[6:9], v[168:171], v[216:219], v[6:9]
	v_mfma_f32_16x16x32_bf16 v[58:61], v[164:167], v[196:199], v[58:61]
	v_mfma_f32_16x16x32_bf16 v[50:53], v[172:175], v[196:199], v[50:53]
	v_mfma_f32_16x16x32_bf16 v[42:45], v[164:167], v[204:207], v[42:45]
	v_mfma_f32_16x16x32_bf16 v[34:37], v[172:175], v[204:207], v[34:37]
	v_mfma_f32_16x16x32_bf16 v[26:29], v[164:167], v[212:215], v[26:29]
	v_mfma_f32_16x16x32_bf16 v[18:21], v[172:175], v[212:215], v[18:21]
	v_mfma_f32_16x16x32_bf16 v[10:13], v[164:167], v[220:223], v[10:13]
	v_mfma_f32_16x16x32_bf16 v[6:9], v[172:175], v[220:223], v[6:9]
	s_setprio 0
	s_setprio 1
	v_mfma_f32_16x16x32_bf16 v[62:65], v[176:179], v[192:195], v[62:65]
	v_mfma_f32_16x16x32_bf16 v[54:57], v[184:187], v[192:195], v[54:57]
	v_mfma_f32_16x16x32_bf16 v[46:49], v[176:179], v[200:203], v[46:49]
	v_mfma_f32_16x16x32_bf16 v[38:41], v[184:187], v[200:203], v[38:41]
	v_mfma_f32_16x16x32_bf16 v[30:33], v[176:179], v[208:211], v[30:33]
	v_mfma_f32_16x16x32_bf16 v[22:25], v[184:187], v[208:211], v[22:25]
	v_mfma_f32_16x16x32_bf16 v[14:17], v[176:179], v[216:219], v[14:17]
	v_mfma_f32_16x16x32_bf16 v[2:5], v[184:187], v[216:219], v[2:5]
	v_mfma_f32_16x16x32_bf16 v[62:65], v[180:183], v[196:199], v[62:65]
	v_mfma_f32_16x16x32_bf16 v[54:57], v[188:191], v[196:199], v[54:57]
	v_mfma_f32_16x16x32_bf16 v[46:49], v[180:183], v[204:207], v[46:49]
	v_mfma_f32_16x16x32_bf16 v[38:41], v[188:191], v[204:207], v[38:41]
	v_mfma_f32_16x16x32_bf16 v[30:33], v[180:183], v[212:215], v[30:33]
	v_mfma_f32_16x16x32_bf16 v[22:25], v[188:191], v[212:215], v[22:25]
	v_mfma_f32_16x16x32_bf16 v[14:17], v[180:183], v[220:223], v[14:17]
	v_mfma_f32_16x16x32_bf16 v[2:5], v[188:191], v[220:223], v[2:5]
	s_setprio 0
	s_barrier
	s_add_i32 s74, 0, 0x18000
	v_add_u32_e32 v159, s74, v151
	s_add_i32 s75, 0, 0x1c000
	ds_read_b128 v[160:163], v159
	ds_read_b128 v[164:167], v159 offset:1024
	ds_read_b128 v[168:171], v159 offset:2048
	ds_read_b128 v[172:175], v159 offset:3072
	v_add_u32_e32 v159, s75, v151
	ds_read_b128 v[176:179], v159
	ds_read_b128 v[180:183], v159 offset:1024
	ds_read_b128 v[184:187], v159 offset:2048
	ds_read_b128 v[188:191], v159 offset:3072
	s_add_u32 s52, s52, 0x40000
	s_addc_u32 s53, s53, 0
	s_mov_b32 m0, s59
	v_lshl_add_u64 v[230:231], s[52:53], 0, v[136:137]
	ds_read_b128 v[192:195], v157 offset:32768
	ds_read_b128 v[196:199], v157 offset:33792
	ds_read_b128 v[200:203], v157 offset:34816
	ds_read_b128 v[204:207], v157 offset:35840
	ds_read_b128 v[208:211], v157 offset:36864
	ds_read_b128 v[212:215], v157 offset:37888
	ds_read_b128 v[216:219], v157 offset:38912
	ds_read_b128 v[220:223], v157 offset:39936
	global_load_lds_dwordx4 v[230:231], off
	v_lshl_add_u64 v[230:231], s[52:53], 0, v[132:133]
	s_mov_b32 m0, s60
	s_nop 0
	global_load_lds_dwordx4 v[230:231], off
	s_waitcnt vmcnt(8)
	s_waitcnt lgkmcnt(0)
	s_setprio 1
	s_barrier
	v_mfma_f32_16x16x32_bf16 v[118:121], v[160:163], v[192:195], v[118:121]
	v_mfma_f32_16x16x32_bf16 v[114:117], v[168:171], v[192:195], v[114:117]
	v_mfma_f32_16x16x32_bf16 v[106:109], v[160:163], v[200:203], v[106:109]
	v_mfma_f32_16x16x32_bf16 v[98:101], v[168:171], v[200:203], v[98:101]
	v_mfma_f32_16x16x32_bf16 v[90:93], v[160:163], v[208:211], v[90:93]
	v_mfma_f32_16x16x32_bf16 v[82:85], v[168:171], v[208:211], v[82:85]
	v_mfma_f32_16x16x32_bf16 v[74:77], v[160:163], v[216:219], v[74:77]
	v_mfma_f32_16x16x32_bf16 v[66:69], v[168:171], v[216:219], v[66:69]
	v_mfma_f32_16x16x32_bf16 v[118:121], v[164:167], v[196:199], v[118:121]
	v_mfma_f32_16x16x32_bf16 v[114:117], v[172:175], v[196:199], v[114:117]
	v_mfma_f32_16x16x32_bf16 v[106:109], v[164:167], v[204:207], v[106:109]
	v_mfma_f32_16x16x32_bf16 v[98:101], v[172:175], v[204:207], v[98:101]
	v_mfma_f32_16x16x32_bf16 v[90:93], v[164:167], v[212:215], v[90:93]
	v_mfma_f32_16x16x32_bf16 v[82:85], v[172:175], v[212:215], v[82:85]
	v_mfma_f32_16x16x32_bf16 v[74:77], v[164:167], v[220:223], v[74:77]
	v_mfma_f32_16x16x32_bf16 v[66:69], v[172:175], v[220:223], v[66:69]
	s_setprio 0
	s_setprio 1
	v_mfma_f32_16x16x32_bf16 v[126:129], v[176:179], v[192:195], v[126:129]
	v_mfma_f32_16x16x32_bf16 v[122:125], v[184:187], v[192:195], v[122:125]
	v_mfma_f32_16x16x32_bf16 v[110:113], v[176:179], v[200:203], v[110:113]
	v_mfma_f32_16x16x32_bf16 v[102:105], v[184:187], v[200:203], v[102:105]
	v_mfma_f32_16x16x32_bf16 v[94:97], v[176:179], v[208:211], v[94:97]
	v_mfma_f32_16x16x32_bf16 v[86:89], v[184:187], v[208:211], v[86:89]
	v_mfma_f32_16x16x32_bf16 v[78:81], v[176:179], v[216:219], v[78:81]
	v_mfma_f32_16x16x32_bf16 v[70:73], v[184:187], v[216:219], v[70:73]
	v_mfma_f32_16x16x32_bf16 v[126:129], v[180:183], v[196:199], v[126:129]
	v_mfma_f32_16x16x32_bf16 v[122:125], v[188:191], v[196:199], v[122:125]
	v_mfma_f32_16x16x32_bf16 v[110:113], v[180:183], v[204:207], v[110:113]
	v_mfma_f32_16x16x32_bf16 v[102:105], v[188:191], v[204:207], v[102:105]
	v_mfma_f32_16x16x32_bf16 v[94:97], v[180:183], v[212:215], v[94:97]
	v_mfma_f32_16x16x32_bf16 v[86:89], v[188:191], v[212:215], v[86:89]
	v_mfma_f32_16x16x32_bf16 v[78:81], v[180:183], v[220:223], v[78:81]
	v_mfma_f32_16x16x32_bf16 v[70:73], v[188:191], v[220:223], v[70:73]
	s_setprio 0
	s_barrier
	s_add_i32 s52, s74, s54
	v_lshl_add_u64 v[148:149], v[148:149], 0, s[14:15]
	s_mov_b32 m0, s52
	ds_read_b128 v[192:195], v157 offset:49152
	ds_read_b128 v[196:199], v157 offset:50176
	ds_read_b128 v[200:203], v157 offset:51200
	ds_read_b128 v[204:207], v157 offset:52224
	ds_read_b128 v[208:211], v157 offset:53248
	ds_read_b128 v[212:215], v157 offset:54272
	ds_read_b128 v[216:219], v157 offset:55296
	ds_read_b128 v[220:223], v157 offset:56320
	global_load_lds_dwordx4 v[148:149], off
	s_add_i32 m0, s52, 0x2000
	s_add_u32 s50, s50, 0x40080
	v_lshl_add_u64 v[148:149], v[224:225], 0, s[14:15]
	s_addc_u32 s51, s51, 0
	s_add_i32 s52, s75, s54
	global_load_lds_dwordx4 v[148:149], off
	v_lshl_add_u64 v[148:149], s[50:51], 0, v[134:135]
	s_mov_b32 m0, s52
	s_nop 0
	global_load_lds_dwordx4 v[148:149], off
	v_lshl_add_u64 v[148:149], s[50:51], 0, v[130:131]
	s_add_i32 m0, s52, 0x2000
	s_nop 0
	global_load_lds_dwordx4 v[148:149], off
	v_lshl_add_u64 v[148:149], v[226:227], 0, s[14:15]
	s_mov_b32 m0, s62
	s_nop 0
	global_load_lds_dwordx4 v[148:149], off
	v_lshl_add_u64 v[148:149], v[228:229], 0, s[14:15]
	s_mov_b32 m0, s63
	s_nop 0
	global_load_lds_dwordx4 v[148:149], off
	s_waitcnt vmcnt(8)
	s_waitcnt lgkmcnt(0)
	s_setprio 1
	s_barrier
	v_mfma_f32_16x16x32_bf16 v[58:61], v[160:163], v[192:195], v[58:61]
	v_mfma_f32_16x16x32_bf16 v[50:53], v[168:171], v[192:195], v[50:53]
	v_mfma_f32_16x16x32_bf16 v[42:45], v[160:163], v[200:203], v[42:45]
	v_mfma_f32_16x16x32_bf16 v[34:37], v[168:171], v[200:203], v[34:37]
	v_mfma_f32_16x16x32_bf16 v[26:29], v[160:163], v[208:211], v[26:29]
	v_mfma_f32_16x16x32_bf16 v[18:21], v[168:171], v[208:211], v[18:21]
	v_mfma_f32_16x16x32_bf16 v[10:13], v[160:163], v[216:219], v[10:13]
	v_mfma_f32_16x16x32_bf16 v[6:9], v[168:171], v[216:219], v[6:9]
	v_mfma_f32_16x16x32_bf16 v[58:61], v[164:167], v[196:199], v[58:61]
	v_mfma_f32_16x16x32_bf16 v[50:53], v[172:175], v[196:199], v[50:53]
	v_mfma_f32_16x16x32_bf16 v[42:45], v[164:167], v[204:207], v[42:45]
	v_mfma_f32_16x16x32_bf16 v[34:37], v[172:175], v[204:207], v[34:37]
	v_mfma_f32_16x16x32_bf16 v[26:29], v[164:167], v[212:215], v[26:29]
	v_mfma_f32_16x16x32_bf16 v[18:21], v[172:175], v[212:215], v[18:21]
	v_mfma_f32_16x16x32_bf16 v[10:13], v[164:167], v[220:223], v[10:13]
	v_mfma_f32_16x16x32_bf16 v[6:9], v[172:175], v[220:223], v[6:9]
	s_setprio 0
	s_setprio 1
	v_mfma_f32_16x16x32_bf16 v[62:65], v[176:179], v[192:195], v[62:65]
	v_mfma_f32_16x16x32_bf16 v[54:57], v[184:187], v[192:195], v[54:57]
	v_mfma_f32_16x16x32_bf16 v[46:49], v[176:179], v[200:203], v[46:49]
	v_mfma_f32_16x16x32_bf16 v[38:41], v[184:187], v[200:203], v[38:41]
	v_mfma_f32_16x16x32_bf16 v[30:33], v[176:179], v[208:211], v[30:33]
	v_mfma_f32_16x16x32_bf16 v[22:25], v[184:187], v[208:211], v[22:25]
	v_mfma_f32_16x16x32_bf16 v[14:17], v[176:179], v[216:219], v[14:17]
	v_mfma_f32_16x16x32_bf16 v[2:5], v[184:187], v[216:219], v[2:5]
	v_mfma_f32_16x16x32_bf16 v[62:65], v[180:183], v[196:199], v[62:65]
	v_mfma_f32_16x16x32_bf16 v[54:57], v[188:191], v[196:199], v[54:57]
	v_mfma_f32_16x16x32_bf16 v[46:49], v[180:183], v[204:207], v[46:49]
	v_mfma_f32_16x16x32_bf16 v[38:41], v[188:191], v[204:207], v[38:41]
	v_mfma_f32_16x16x32_bf16 v[30:33], v[180:183], v[212:215], v[30:33]
	v_mfma_f32_16x16x32_bf16 v[22:25], v[188:191], v[212:215], v[22:25]
	v_mfma_f32_16x16x32_bf16 v[14:17], v[180:183], v[220:223], v[14:17]
	v_mfma_f32_16x16x32_bf16 v[2:5], v[188:191], v[220:223], v[2:5]
	s_setprio 0
	s_barrier
	s_add_i32 s73, s73, 2
	s_add_u32 s48, s48, 0x100
	s_addc_u32 s49, s49, 0
	s_add_u32 s71, s71, 0x100
	s_addc_u32 s72, s72, 0
	s_cmp_gt_u32 s73, 13
	s_cbranch_scc0 .LBB0_840
	s_lshl_b32 s25, s46, 8
	v_add_u32_e32 v148, s25, v150
	v_ashrrev_i32_e32 v149, 31, v148
	v_lshl_add_u64 v[160:161], v[148:149], 2, s[10:11]
	global_load_dword v149, v[160:161], off
	global_load_dword v232, v[160:161], off offset:64
	global_load_dword v233, v[160:161], off offset:128
	global_load_dword v234, v[160:161], off offset:192
	global_load_dword v235, v[160:161], off offset:512
	global_load_dword v236, v[160:161], off offset:576
	global_load_dword v237, v[160:161], off offset:640
	global_load_dword v238, v[160:161], off offset:704
	s_and_b64 vcc, exec, s[16:17]
	s_cbranch_vccz .LBB0_843
	s_barrier

.LBB0_1050:
	ds_read_b128 v[162:165], v156
	ds_read_b128 v[166:169], v156 offset:1024
	ds_read_b128 v[170:173], v156 offset:2048
	ds_read_b128 v[174:177], v156 offset:3072
	ds_read_b128 v[178:181], v157
	ds_read_b128 v[182:185], v157 offset:1024
	ds_read_b128 v[186:189], v157 offset:2048
	ds_read_b128 v[190:193], v157 offset:3072
	s_add_u32 s58, s56, 0xfffc0080
	s_addc_u32 s59, s57, -1
	s_cmp_eq_u32 s81, 12
	s_cselect_b32 s61, s9, s59
	s_cselect_b32 s60, s11, s58
	s_cselect_b32 s59, s49, s80
	s_cselect_b32 s58, s51, s79
	v_lshl_add_u64 v[150:151], s[56:57], 0, v[142:143]
	s_add_i32 m0, s63, 0xc000
	ds_read_b128 v[194:197], v158
	ds_read_b128 v[198:201], v158 offset:1024
	ds_read_b128 v[202:205], v158 offset:2048
	ds_read_b128 v[206:209], v158 offset:3072
	ds_read_b128 v[210:213], v158 offset:4096
	ds_read_b128 v[214:217], v158 offset:5120
	ds_read_b128 v[218:221], v158 offset:6144
	ds_read_b128 v[222:225], v158 offset:7168
	global_load_lds_dwordx4 v[150:151], off
	v_lshl_add_u64 v[150:151], s[56:57], 0, v[144:145]
	s_add_i32 m0, s63, 0xe000
	s_nop 0
	global_load_lds_dwordx4 v[150:151], off
	s_waitcnt vmcnt(8)
	s_waitcnt lgkmcnt(0)
	s_setprio 1
	s_barrier
	v_mfma_f32_16x16x32_bf16 v[126:129], v[162:165], v[194:197], v[126:129]
	v_mfma_f32_16x16x32_bf16 v[122:125], v[170:173], v[194:197], v[122:125]
	v_mfma_f32_16x16x32_bf16 v[110:113], v[162:165], v[202:205], v[110:113]
	v_mfma_f32_16x16x32_bf16 v[106:109], v[170:173], v[202:205], v[106:109]
	v_mfma_f32_16x16x32_bf16 v[94:97], v[162:165], v[210:213], v[94:97]
	v_mfma_f32_16x16x32_bf16 v[90:93], v[170:173], v[210:213], v[90:93]
	v_mfma_f32_16x16x32_bf16 v[78:81], v[162:165], v[218:221], v[78:81]
	v_mfma_f32_16x16x32_bf16 v[74:77], v[170:173], v[218:221], v[74:77]
	v_mfma_f32_16x16x32_bf16 v[126:129], v[166:169], v[198:201], v[126:129]
	v_mfma_f32_16x16x32_bf16 v[122:125], v[174:177], v[198:201], v[122:125]
	v_mfma_f32_16x16x32_bf16 v[110:113], v[166:169], v[206:209], v[110:113]
	v_mfma_f32_16x16x32_bf16 v[106:109], v[174:177], v[206:209], v[106:109]
	v_mfma_f32_16x16x32_bf16 v[94:97], v[166:169], v[214:217], v[94:97]
	v_mfma_f32_16x16x32_bf16 v[90:93], v[174:177], v[214:217], v[90:93]
	v_mfma_f32_16x16x32_bf16 v[78:81], v[166:169], v[222:225], v[78:81]
	v_mfma_f32_16x16x32_bf16 v[74:77], v[174:177], v[222:225], v[74:77]
	s_setprio 0
	s_setprio 1
	v_mfma_f32_16x16x32_bf16 v[118:121], v[178:181], v[194:197], v[118:121]
	v_mfma_f32_16x16x32_bf16 v[114:117], v[186:189], v[194:197], v[114:117]
	v_mfma_f32_16x16x32_bf16 v[102:105], v[178:181], v[202:205], v[102:105]
	v_mfma_f32_16x16x32_bf16 v[98:101], v[186:189], v[202:205], v[98:101]
	v_mfma_f32_16x16x32_bf16 v[86:89], v[178:181], v[210:213], v[86:89]
	v_mfma_f32_16x16x32_bf16 v[82:85], v[186:189], v[210:213], v[82:85]
	v_mfma_f32_16x16x32_bf16 v[70:73], v[178:181], v[218:221], v[70:73]
	v_mfma_f32_16x16x32_bf16 v[66:69], v[186:189], v[218:221], v[66:69]
	v_mfma_f32_16x16x32_bf16 v[118:121], v[182:185], v[198:201], v[118:121]
	v_mfma_f32_16x16x32_bf16 v[114:117], v[190:193], v[198:201], v[114:117]
	v_mfma_f32_16x16x32_bf16 v[102:105], v[182:185], v[206:209], v[102:105]
	v_mfma_f32_16x16x32_bf16 v[98:101], v[190:193], v[206:209], v[98:101]
	v_mfma_f32_16x16x32_bf16 v[86:89], v[182:185], v[214:217], v[86:89]
	v_mfma_f32_16x16x32_bf16 v[82:85], v[190:193], v[214:217], v[82:85]
	v_mfma_f32_16x16x32_bf16 v[70:73], v[182:185], v[222:225], v[70:73]
	v_mfma_f32_16x16x32_bf16 v[66:69], v[190:193], v[222:225], v[66:69]
	s_setprio 0
	s_barrier
	s_add_i32 s82, s73, s62
	v_lshl_add_u64 v[150:151], s[58:59], 0, v[132:133]
	s_mov_b32 m0, s82
	ds_read_b128 v[194:197], v158 offset:16384
	ds_read_b128 v[198:201], v158 offset:17408
	ds_read_b128 v[202:205], v158 offset:18432
	ds_read_b128 v[206:209], v158 offset:19456
	ds_read_b128 v[210:213], v158 offset:20480
	ds_read_b128 v[214:217], v158 offset:21504
	ds_read_b128 v[218:221], v158 offset:22528
	ds_read_b128 v[222:225], v158 offset:23552
	global_load_lds_dwordx4 v[150:151], off
	s_add_i32 m0, s82, 0x2000
	s_add_u32 s82, s58, 0x40000
	v_lshl_add_u64 v[226:227], s[58:59], 0, v[136:137]
	s_addc_u32 s83, s59, 0
	s_add_i32 s84, s74, s62
	global_load_lds_dwordx4 v[226:227], off
	v_lshl_add_u64 v[228:229], s[82:83], 0, v[132:133]
	s_mov_b32 m0, s84
	v_lshl_add_u64 v[230:231], s[60:61], 0, v[134:135]
	global_load_lds_dwordx4 v[228:229], off
	v_lshl_add_u64 v[228:229], s[82:83], 0, v[136:137]
	s_add_i32 m0, s84, 0x2000
	s_nop 0
	global_load_lds_dwordx4 v[228:229], off
	v_lshl_add_u64 v[228:229], s[60:61], 0, v[130:131]
	s_mov_b32 m0, s63
	s_nop 0
	global_load_lds_dwordx4 v[228:229], off
	s_mov_b32 m0, s64
	s_nop 0
	global_load_lds_dwordx4 v[230:231], off
	s_waitcnt vmcnt(8)
	s_waitcnt lgkmcnt(0)
	s_setprio 1
	s_barrier
	v_mfma_f32_16x16x32_bf16 v[62:65], v[162:165], v[194:197], v[62:65]
	v_mfma_f32_16x16x32_bf16 v[58:61], v[170:173], v[194:197], v[58:61]
	v_mfma_f32_16x16x32_bf16 v[46:49], v[162:165], v[202:205], v[46:49]
	v_mfma_f32_16x16x32_bf16 v[42:45], v[170:173], v[202:205], v[42:45]
	v_mfma_f32_16x16x32_bf16 v[30:33], v[162:165], v[210:213], v[30:33]
	v_mfma_f32_16x16x32_bf16 v[26:29], v[170:173], v[210:213], v[26:29]
	v_mfma_f32_16x16x32_bf16 v[14:17], v[162:165], v[218:221], v[14:17]
	v_mfma_f32_16x16x32_bf16 v[10:13], v[170:173], v[218:221], v[10:13]
	v_mfma_f32_16x16x32_bf16 v[62:65], v[166:169], v[198:201], v[62:65]
	v_mfma_f32_16x16x32_bf16 v[58:61], v[174:177], v[198:201], v[58:61]
	v_mfma_f32_16x16x32_bf16 v[46:49], v[166:169], v[206:209], v[46:49]
	v_mfma_f32_16x16x32_bf16 v[42:45], v[174:177], v[206:209], v[42:45]
	v_mfma_f32_16x16x32_bf16 v[30:33], v[166:169], v[214:217], v[30:33]
	v_mfma_f32_16x16x32_bf16 v[26:29], v[174:177], v[214:217], v[26:29]
	v_mfma_f32_16x16x32_bf16 v[14:17], v[166:169], v[222:225], v[14:17]
	v_mfma_f32_16x16x32_bf16 v[10:13], v[174:177], v[222:225], v[10:13]
	s_setprio 0
	s_setprio 1
	v_mfma_f32_16x16x32_bf16 v[54:57], v[178:181], v[194:197], v[54:57]
	v_mfma_f32_16x16x32_bf16 v[50:53], v[186:189], v[194:197], v[50:53]
	v_mfma_f32_16x16x32_bf16 v[38:41], v[178:181], v[202:205], v[38:41]
	v_mfma_f32_16x16x32_bf16 v[34:37], v[186:189], v[202:205], v[34:37]
	v_mfma_f32_16x16x32_bf16 v[22:25], v[178:181], v[210:213], v[22:25]
	v_mfma_f32_16x16x32_bf16 v[18:21], v[186:189], v[210:213], v[18:21]
	v_mfma_f32_16x16x32_bf16 v[6:9], v[178:181], v[218:221], v[6:9]
	v_mfma_f32_16x16x32_bf16 v[2:5], v[186:189], v[218:221], v[2:5]
	v_mfma_f32_16x16x32_bf16 v[54:57], v[182:185], v[198:201], v[54:57]
	v_mfma_f32_16x16x32_bf16 v[50:53], v[190:193], v[198:201], v[50:53]
	v_mfma_f32_16x16x32_bf16 v[38:41], v[182:185], v[206:209], v[38:41]
	v_mfma_f32_16x16x32_bf16 v[34:37], v[190:193], v[206:209], v[34:37]
	v_mfma_f32_16x16x32_bf16 v[22:25], v[182:185], v[214:217], v[22:25]
	v_mfma_f32_16x16x32_bf16 v[18:21], v[190:193], v[214:217], v[18:21]
	v_mfma_f32_16x16x32_bf16 v[6:9], v[182:185], v[222:225], v[6:9]
	v_mfma_f32_16x16x32_bf16 v[2:5], v[190:193], v[222:225], v[2:5]
	s_setprio 0
	s_barrier
	s_add_i32 s82, 0, 0x18000
	v_add_u32_e32 v152, s82, v155
	s_add_i32 s83, 0, 0x1c000
	ds_read_b128 v[162:165], v152
	ds_read_b128 v[166:169], v152 offset:1024
	ds_read_b128 v[170:173], v152 offset:2048
	ds_read_b128 v[174:177], v152 offset:3072
	v_add_u32_e32 v152, s83, v155
	ds_read_b128 v[178:181], v152
	ds_read_b128 v[182:185], v152 offset:1024
	ds_read_b128 v[186:189], v152 offset:2048
	ds_read_b128 v[190:193], v152 offset:3072
	s_add_u32 s60, s60, 0x40000
	s_addc_u32 s61, s61, 0
	s_mov_b32 m0, s65
	v_lshl_add_u64 v[232:233], s[60:61], 0, v[130:131]
	ds_read_b128 v[194:197], v158 offset:32768
	ds_read_b128 v[198:201], v158 offset:33792
	ds_read_b128 v[202:205], v158 offset:34816
	ds_read_b128 v[206:209], v158 offset:35840
	ds_read_b128 v[210:213], v158 offset:36864
	ds_read_b128 v[214:217], v158 offset:37888
	ds_read_b128 v[218:221], v158 offset:38912
	ds_read_b128 v[222:225], v158 offset:39936
	global_load_lds_dwordx4 v[232:233], off
	v_lshl_add_u64 v[232:233], s[60:61], 0, v[134:135]
	s_mov_b32 m0, s66
	s_nop 0
	global_load_lds_dwordx4 v[232:233], off
	s_waitcnt vmcnt(8)
	s_waitcnt lgkmcnt(0)
	s_setprio 1
	s_barrier
	v_mfma_f32_16x16x32_bf16 v[126:129], v[162:165], v[194:197], v[126:129]
	v_mfma_f32_16x16x32_bf16 v[122:125], v[170:173], v[194:197], v[122:125]
	v_mfma_f32_16x16x32_bf16 v[110:113], v[162:165], v[202:205], v[110:113]
	v_mfma_f32_16x16x32_bf16 v[106:109], v[170:173], v[202:205], v[106:109]
	v_mfma_f32_16x16x32_bf16 v[94:97], v[162:165], v[210:213], v[94:97]
	v_mfma_f32_16x16x32_bf16 v[90:93], v[170:173], v[210:213], v[90:93]
	v_mfma_f32_16x16x32_bf16 v[78:81], v[162:165], v[218:221], v[78:81]
	v_mfma_f32_16x16x32_bf16 v[74:77], v[170:173], v[218:221], v[74:77]
	v_mfma_f32_16x16x32_bf16 v[126:129], v[166:169], v[198:201], v[126:129]
	v_mfma_f32_16x16x32_bf16 v[122:125], v[174:177], v[198:201], v[122:125]
	v_mfma_f32_16x16x32_bf16 v[110:113], v[166:169], v[206:209], v[110:113]
	v_mfma_f32_16x16x32_bf16 v[106:109], v[174:177], v[206:209], v[106:109]
	v_mfma_f32_16x16x32_bf16 v[94:97], v[166:169], v[214:217], v[94:97]
	v_mfma_f32_16x16x32_bf16 v[90:93], v[174:177], v[214:217], v[90:93]
	v_mfma_f32_16x16x32_bf16 v[78:81], v[166:169], v[222:225], v[78:81]
	v_mfma_f32_16x16x32_bf16 v[74:77], v[174:177], v[222:225], v[74:77]
	s_setprio 0
	s_setprio 1
	v_mfma_f32_16x16x32_bf16 v[118:121], v[178:181], v[194:197], v[118:121]
	v_mfma_f32_16x16x32_bf16 v[114:117], v[186:189], v[194:197], v[114:117]
	v_mfma_f32_16x16x32_bf16 v[102:105], v[178:181], v[202:205], v[102:105]
	v_mfma_f32_16x16x32_bf16 v[98:101], v[186:189], v[202:205], v[98:101]
	v_mfma_f32_16x16x32_bf16 v[86:89], v[178:181], v[210:213], v[86:89]
	v_mfma_f32_16x16x32_bf16 v[82:85], v[186:189], v[210:213], v[82:85]
	v_mfma_f32_16x16x32_bf16 v[70:73], v[178:181], v[218:221], v[70:73]
	v_mfma_f32_16x16x32_bf16 v[66:69], v[186:189], v[218:221], v[66:69]
	v_mfma_f32_16x16x32_bf16 v[118:121], v[182:185], v[198:201], v[118:121]
	v_mfma_f32_16x16x32_bf16 v[114:117], v[190:193], v[198:201], v[114:117]
	v_mfma_f32_16x16x32_bf16 v[102:105], v[182:185], v[206:209], v[102:105]
	v_mfma_f32_16x16x32_bf16 v[98:101], v[190:193], v[206:209], v[98:101]
	v_mfma_f32_16x16x32_bf16 v[86:89], v[182:185], v[214:217], v[86:89]
	v_mfma_f32_16x16x32_bf16 v[82:85], v[190:193], v[214:217], v[82:85]
	v_mfma_f32_16x16x32_bf16 v[70:73], v[182:185], v[222:225], v[70:73]
	v_mfma_f32_16x16x32_bf16 v[66:69], v[190:193], v[222:225], v[66:69]
	s_setprio 0
	s_barrier
	s_add_i32 s60, s82, s62
	v_lshl_add_u64 v[150:151], v[150:151], 0, s[42:43]
	s_mov_b32 m0, s60
	ds_read_b128 v[194:197], v158 offset:49152
	ds_read_b128 v[198:201], v158 offset:50176
	ds_read_b128 v[202:205], v158 offset:51200
	ds_read_b128 v[206:209], v158 offset:52224
	ds_read_b128 v[210:213], v158 offset:53248
	ds_read_b128 v[214:217], v158 offset:54272
	ds_read_b128 v[218:221], v158 offset:55296
	ds_read_b128 v[222:225], v158 offset:56320
	global_load_lds_dwordx4 v[150:151], off
	s_add_i32 m0, s60, 0x2000
	s_add_u32 s58, s58, 0x40080
	v_lshl_add_u64 v[150:151], v[226:227], 0, s[42:43]
	s_addc_u32 s59, s59, 0
	s_add_i32 s60, s83, s62
	global_load_lds_dwordx4 v[150:151], off
	v_lshl_add_u64 v[150:151], s[58:59], 0, v[132:133]
	s_mov_b32 m0, s60
	s_nop 0
	global_load_lds_dwordx4 v[150:151], off
	v_lshl_add_u64 v[150:151], s[58:59], 0, v[136:137]
	s_add_i32 m0, s60, 0x2000
	s_nop 0
	global_load_lds_dwordx4 v[150:151], off
	v_lshl_add_u64 v[150:151], v[228:229], 0, s[42:43]
	s_mov_b32 m0, s68
	s_nop 0
	global_load_lds_dwordx4 v[150:151], off
	v_lshl_add_u64 v[150:151], v[230:231], 0, s[42:43]
	s_mov_b32 m0, s69
	s_nop 0
	global_load_lds_dwordx4 v[150:151], off
	s_waitcnt vmcnt(8)
	s_waitcnt lgkmcnt(0)
	s_setprio 1
	s_barrier
	v_mfma_f32_16x16x32_bf16 v[62:65], v[162:165], v[194:197], v[62:65]
	v_mfma_f32_16x16x32_bf16 v[58:61], v[170:173], v[194:197], v[58:61]
	v_mfma_f32_16x16x32_bf16 v[46:49], v[162:165], v[202:205], v[46:49]
	v_mfma_f32_16x16x32_bf16 v[42:45], v[170:173], v[202:205], v[42:45]
	v_mfma_f32_16x16x32_bf16 v[30:33], v[162:165], v[210:213], v[30:33]
	v_mfma_f32_16x16x32_bf16 v[26:29], v[170:173], v[210:213], v[26:29]
	v_mfma_f32_16x16x32_bf16 v[14:17], v[162:165], v[218:221], v[14:17]
	v_mfma_f32_16x16x32_bf16 v[10:13], v[170:173], v[218:221], v[10:13]
	v_mfma_f32_16x16x32_bf16 v[62:65], v[166:169], v[198:201], v[62:65]
	v_mfma_f32_16x16x32_bf16 v[58:61], v[174:177], v[198:201], v[58:61]
	v_mfma_f32_16x16x32_bf16 v[46:49], v[166:169], v[206:209], v[46:49]
	v_mfma_f32_16x16x32_bf16 v[42:45], v[174:177], v[206:209], v[42:45]
	v_mfma_f32_16x16x32_bf16 v[30:33], v[166:169], v[214:217], v[30:33]
	v_mfma_f32_16x16x32_bf16 v[26:29], v[174:177], v[214:217], v[26:29]
	v_mfma_f32_16x16x32_bf16 v[14:17], v[166:169], v[222:225], v[14:17]
	v_mfma_f32_16x16x32_bf16 v[10:13], v[174:177], v[222:225], v[10:13]
	s_setprio 0
	s_setprio 1
	v_mfma_f32_16x16x32_bf16 v[54:57], v[178:181], v[194:197], v[54:57]
	v_mfma_f32_16x16x32_bf16 v[50:53], v[186:189], v[194:197], v[50:53]
	v_mfma_f32_16x16x32_bf16 v[38:41], v[178:181], v[202:205], v[38:41]
	v_mfma_f32_16x16x32_bf16 v[34:37], v[186:189], v[202:205], v[34:37]
	v_mfma_f32_16x16x32_bf16 v[22:25], v[178:181], v[210:213], v[22:25]
	v_mfma_f32_16x16x32_bf16 v[18:21], v[186:189], v[210:213], v[18:21]
	v_mfma_f32_16x16x32_bf16 v[6:9], v[178:181], v[218:221], v[6:9]
	v_mfma_f32_16x16x32_bf16 v[2:5], v[186:189], v[218:221], v[2:5]
	v_mfma_f32_16x16x32_bf16 v[54:57], v[182:185], v[198:201], v[54:57]
	v_mfma_f32_16x16x32_bf16 v[50:53], v[190:193], v[198:201], v[50:53]
	v_mfma_f32_16x16x32_bf16 v[38:41], v[182:185], v[206:209], v[38:41]
	v_mfma_f32_16x16x32_bf16 v[34:37], v[190:193], v[206:209], v[34:37]
	v_mfma_f32_16x16x32_bf16 v[22:25], v[182:185], v[214:217], v[22:25]
	v_mfma_f32_16x16x32_bf16 v[18:21], v[190:193], v[214:217], v[18:21]
	v_mfma_f32_16x16x32_bf16 v[6:9], v[182:185], v[222:225], v[6:9]
	v_mfma_f32_16x16x32_bf16 v[2:5], v[190:193], v[222:225], v[2:5]
	s_setprio 0
	s_barrier
	s_add_i32 s81, s81, 2
	s_add_u32 s56, s56, 0x100
	s_addc_u32 s57, s57, 0
	s_add_u32 s79, s79, 0x100
	s_addc_u32 s80, s80, 0
	s_cmp_gt_u32 s81, 13
	s_cbranch_scc0 .LBB0_1050
	s_and_b64 vcc, exec, s[44:45]
	s_cbranch_vccz .LBB0_1053
	s_barrier

.LBB0_1224:
	ds_read_b128 v[2:5], v151
	ds_read_b128 v[6:9], v151 offset:1024
	ds_read_b128 v[10:13], v151 offset:2048
	ds_read_b128 v[14:17], v151 offset:3072
	ds_read_b128 v[18:21], v152
	ds_read_b128 v[22:25], v152 offset:1024
	ds_read_b128 v[26:29], v152 offset:2048
	ds_read_b128 v[30:33], v152 offset:3072
	s_ashr_i32 s49, s48, 31
	s_lshl_b64 s[50:51], s[48:49], 17
	s_add_u32 s50, s3, s50
	s_addc_u32 s51, s23, s51
	s_and_b64 s[52:53], s[4:5], exec
	s_cselect_b32 s63, s51, s57
	s_cselect_b32 s62, s50, s56
	s_ashr_i32 s47, s46, 31
	s_lshl_b64 s[52:53], s[46:47], 17
	s_add_u32 s52, s29, s52
	s_addc_u32 s53, s31, s53
	s_and_b64 s[60:61], s[4:5], exec
	s_cselect_b32 s61, s53, s59
	s_cselect_b32 s60, s52, s58
	s_add_u32 s76, s56, 0x10080
	s_addc_u32 s77, s57, 0
	s_add_i32 s79, s65, 0xc000
	v_lshl_add_u64 v[66:67], s[76:77], 0, v[130:131]
	s_mov_b32 m0, s79
	s_add_i32 s47, s65, 0xe000
	ds_read_b128 v[34:37], v153
	ds_read_b128 v[38:41], v153 offset:1024
	ds_read_b128 v[42:45], v153 offset:2048
	ds_read_b128 v[46:49], v153 offset:3072
	ds_read_b128 v[50:53], v153 offset:4096
	ds_read_b128 v[54:57], v153 offset:5120
	ds_read_b128 v[58:61], v153 offset:6144
	ds_read_b128 v[62:65], v153 offset:7168
	global_load_lds_dwordx4 v[66:67], off
	v_lshl_add_u64 v[66:67], s[76:77], 0, v[134:135]
	s_mov_b32 m0, s47
	s_nop 0
	global_load_lds_dwordx4 v[66:67], off
	s_waitcnt vmcnt(8)
	s_waitcnt lgkmcnt(0)
	s_setprio 1
	s_barrier
	v_mfma_f32_16x16x32_bf16 v[66:69], v[2:5], v[34:37], 0
	v_mfma_f32_16x16x32_bf16 v[70:73], v[10:13], v[34:37], 0
	v_mfma_f32_16x16x32_bf16 v[74:77], v[2:5], v[42:45], 0
	v_mfma_f32_16x16x32_bf16 v[78:81], v[10:13], v[42:45], 0
	s_waitcnt vmcnt(0)
	v_mfma_f32_16x16x32_bf16 v[82:85], v[2:5], v[50:53], 0
	v_mfma_f32_16x16x32_bf16 v[86:89], v[10:13], v[50:53], 0
	v_mfma_f32_16x16x32_bf16 v[90:93], v[2:5], v[58:61], 0
	v_mfma_f32_16x16x32_bf16 v[94:97], v[10:13], v[58:61], 0
	v_mfma_f32_16x16x32_bf16 v[66:69], v[6:9], v[38:41], v[66:69]
	v_mfma_f32_16x16x32_bf16 v[70:73], v[14:17], v[38:41], v[70:73]
	v_mfma_f32_16x16x32_bf16 v[74:77], v[6:9], v[46:49], v[74:77]
	v_mfma_f32_16x16x32_bf16 v[78:81], v[14:17], v[46:49], v[78:81]
	v_mfma_f32_16x16x32_bf16 v[82:85], v[6:9], v[54:57], v[82:85]
	v_mfma_f32_16x16x32_bf16 v[86:89], v[14:17], v[54:57], v[86:89]
	v_mfma_f32_16x16x32_bf16 v[90:93], v[6:9], v[62:65], v[90:93]
	v_mfma_f32_16x16x32_bf16 v[94:97], v[14:17], v[62:65], v[94:97]
	s_setprio 0
	s_setprio 1
	v_mfma_f32_16x16x32_bf16 v[98:101], v[18:21], v[34:37], 0
	v_mfma_f32_16x16x32_bf16 v[34:37], v[26:29], v[34:37], 0
	v_mfma_f32_16x16x32_bf16 v[98:101], v[22:25], v[38:41], v[98:101]
	v_mfma_f32_16x16x32_bf16 v[34:37], v[30:33], v[38:41], v[34:37]
	v_mfma_f32_16x16x32_bf16 v[38:41], v[18:21], v[42:45], 0
	v_mfma_f32_16x16x32_bf16 v[42:45], v[26:29], v[42:45], 0
	v_mfma_f32_16x16x32_bf16 v[38:41], v[22:25], v[46:49], v[38:41]
	v_mfma_f32_16x16x32_bf16 v[42:45], v[30:33], v[46:49], v[42:45]
	v_mfma_f32_16x16x32_bf16 v[46:49], v[18:21], v[50:53], 0
	v_mfma_f32_16x16x32_bf16 v[50:53], v[26:29], v[50:53], 0
	v_mfma_f32_16x16x32_bf16 v[46:49], v[22:25], v[54:57], v[46:49]
	v_mfma_f32_16x16x32_bf16 v[50:53], v[30:33], v[54:57], v[50:53]
	v_mfma_f32_16x16x32_bf16 v[54:57], v[18:21], v[58:61], 0
	v_mfma_f32_16x16x32_bf16 v[58:61], v[26:29], v[58:61], 0
	v_mfma_f32_16x16x32_bf16 v[54:57], v[22:25], v[62:65], v[54:57]
	v_mfma_f32_16x16x32_bf16 v[58:61], v[30:33], v[62:65], v[58:61]
	s_setprio 0
	s_barrier
	s_add_i32 s77, s73, s64
	v_lshl_add_u64 v[144:145], s[58:59], 0, v[132:133]
	s_add_i32 s49, s77, 0x2000
	v_lshl_add_u64 v[156:157], v[144:145], 0, s[42:43]
	s_mov_b32 m0, s77
	v_lshl_add_u64 v[220:221], s[58:59], 0, v[136:137]
	s_add_u32 s80, s58, 0x10100
	ds_read_b128 v[62:65], v153 offset:16384
	ds_read_b128 v[102:105], v153 offset:17408
	ds_read_b128 v[106:109], v153 offset:18432
	ds_read_b128 v[110:113], v153 offset:19456
	ds_read_b128 v[114:117], v153 offset:20480
	ds_read_b128 v[118:121], v153 offset:21504
	ds_read_b128 v[122:125], v153 offset:22528
	ds_read_b128 v[126:129], v153 offset:23552
	global_load_lds_dwordx4 v[156:157], off
	v_lshl_add_u64 v[156:157], v[220:221], 0, s[42:43]
	s_mov_b32 m0, s49
	s_addc_u32 s81, s59, 0
	s_add_i32 s75, s74, s64
	global_load_lds_dwordx4 v[156:157], off
	v_lshl_add_u64 v[156:157], s[80:81], 0, v[132:133]
	s_mov_b32 m0, s75
	s_add_i32 s76, s75, 0x2000
	global_load_lds_dwordx4 v[156:157], off
	v_lshl_add_u64 v[156:157], s[80:81], 0, v[136:137]
	s_mov_b32 m0, s76
	v_lshl_add_u64 v[222:223], s[56:57], 0, v[130:131]
	global_load_lds_dwordx4 v[156:157], off
	v_lshl_add_u64 v[156:157], v[222:223], 0, s[42:43]
	s_mov_b32 m0, s65
	v_lshl_add_u64 v[224:225], s[56:57], 0, v[134:135]
	global_load_lds_dwordx4 v[156:157], off
	v_lshl_add_u64 v[156:157], v[224:225], 0, s[42:43]
	s_mov_b32 m0, s66
	s_nop 0
	global_load_lds_dwordx4 v[156:157], off
	s_waitcnt vmcnt(8)
	s_waitcnt lgkmcnt(0)
	s_setprio 1
	s_barrier
	v_mfma_f32_16x16x32_bf16 v[156:159], v[2:5], v[62:65], 0
	v_mfma_f32_16x16x32_bf16 v[164:167], v[2:5], v[106:109], 0
	v_mfma_f32_16x16x32_bf16 v[172:175], v[2:5], v[114:117], 0
	v_mfma_f32_16x16x32_bf16 v[2:5], v[2:5], v[122:125], 0
	v_mfma_f32_16x16x32_bf16 v[156:159], v[6:9], v[102:105], v[156:159]
	v_mfma_f32_16x16x32_bf16 v[164:167], v[6:9], v[110:113], v[164:167]
	v_mfma_f32_16x16x32_bf16 v[172:175], v[6:9], v[118:121], v[172:175]
	v_mfma_f32_16x16x32_bf16 v[2:5], v[6:9], v[126:129], v[2:5]
	v_mfma_f32_16x16x32_bf16 v[6:9], v[10:13], v[122:125], 0
	v_mfma_f32_16x16x32_bf16 v[160:163], v[10:13], v[62:65], 0
	v_mfma_f32_16x16x32_bf16 v[168:171], v[10:13], v[106:109], 0
	v_mfma_f32_16x16x32_bf16 v[176:179], v[10:13], v[114:117], 0
	v_mfma_f32_16x16x32_bf16 v[6:9], v[14:17], v[126:129], v[6:9]
	v_mfma_f32_16x16x32_bf16 v[160:163], v[14:17], v[102:105], v[160:163]
	v_mfma_f32_16x16x32_bf16 v[168:171], v[14:17], v[110:113], v[168:171]
	v_mfma_f32_16x16x32_bf16 v[176:179], v[14:17], v[118:121], v[176:179]
	s_setprio 0
	s_setprio 1
	v_mfma_f32_16x16x32_bf16 v[10:13], v[18:21], v[62:65], 0
	v_mfma_f32_16x16x32_bf16 v[14:17], v[26:29], v[62:65], 0
	v_mfma_f32_16x16x32_bf16 v[10:13], v[22:25], v[102:105], v[10:13]
	v_mfma_f32_16x16x32_bf16 v[14:17], v[30:33], v[102:105], v[14:17]
	v_mfma_f32_16x16x32_bf16 v[62:65], v[18:21], v[106:109], 0
	v_mfma_f32_16x16x32_bf16 v[102:105], v[26:29], v[106:109], 0
	v_mfma_f32_16x16x32_bf16 v[106:109], v[18:21], v[114:117], 0
	v_mfma_f32_16x16x32_bf16 v[18:21], v[18:21], v[122:125], 0
	v_mfma_f32_16x16x32_bf16 v[62:65], v[22:25], v[110:113], v[62:65]
	v_mfma_f32_16x16x32_bf16 v[102:105], v[30:33], v[110:113], v[102:105]
	v_mfma_f32_16x16x32_bf16 v[106:109], v[22:25], v[118:121], v[106:109]
	v_mfma_f32_16x16x32_bf16 v[110:113], v[26:29], v[114:117], 0
	v_mfma_f32_16x16x32_bf16 v[18:21], v[22:25], v[126:129], v[18:21]
	v_mfma_f32_16x16x32_bf16 v[22:25], v[26:29], v[122:125], 0
	v_mfma_f32_16x16x32_bf16 v[110:113], v[30:33], v[118:121], v[110:113]
	v_mfma_f32_16x16x32_bf16 v[22:25], v[30:33], v[126:129], v[22:25]
	s_setprio 0
	s_barrier
	s_add_i32 s78, 0, 0x18000
	s_add_i32 s84, 0, 0x1c000
	v_add_u32_e32 v155, s78, v147
	v_add_u32_e32 v228, s84, v147
	ds_read_b128 v[26:29], v155
	ds_read_b128 v[30:33], v155 offset:1024
	ds_read_b128 v[114:117], v155 offset:2048
	ds_read_b128 v[118:121], v155 offset:3072
	ds_read_b128 v[122:125], v228
	ds_read_b128 v[126:129], v228 offset:1024
	ds_read_b128 v[180:183], v228 offset:2048
	ds_read_b128 v[184:187], v228 offset:3072
	s_add_u32 s80, s56, 0x10100
	s_addc_u32 s81, s57, 0
	s_mov_b32 m0, s67
	v_lshl_add_u64 v[226:227], s[80:81], 0, v[130:131]
	ds_read_b128 v[188:191], v153 offset:32768
	ds_read_b128 v[192:195], v153 offset:33792
	ds_read_b128 v[196:199], v153 offset:34816
	ds_read_b128 v[200:203], v153 offset:35840
	ds_read_b128 v[204:207], v153 offset:36864
	ds_read_b128 v[208:211], v153 offset:37888
	ds_read_b128 v[212:215], v153 offset:38912
	ds_read_b128 v[216:219], v153 offset:39936
	global_load_lds_dwordx4 v[226:227], off
	v_lshl_add_u64 v[226:227], s[80:81], 0, v[134:135]
	s_mov_b32 m0, s68
	s_nop 0
	global_load_lds_dwordx4 v[226:227], off
	s_waitcnt vmcnt(8)
	s_waitcnt lgkmcnt(0)
	s_setprio 1
	s_barrier
	v_mfma_f32_16x16x32_bf16 v[66:69], v[26:29], v[188:191], v[66:69]
	v_mfma_f32_16x16x32_bf16 v[70:73], v[114:117], v[188:191], v[70:73]
	v_mfma_f32_16x16x32_bf16 v[74:77], v[26:29], v[196:199], v[74:77]
	v_mfma_f32_16x16x32_bf16 v[78:81], v[114:117], v[196:199], v[78:81]
	v_mfma_f32_16x16x32_bf16 v[82:85], v[26:29], v[204:207], v[82:85]
	v_mfma_f32_16x16x32_bf16 v[86:89], v[114:117], v[204:207], v[86:89]
	v_mfma_f32_16x16x32_bf16 v[90:93], v[26:29], v[212:215], v[90:93]
	v_mfma_f32_16x16x32_bf16 v[94:97], v[114:117], v[212:215], v[94:97]
	v_mfma_f32_16x16x32_bf16 v[66:69], v[30:33], v[192:195], v[66:69]
	v_mfma_f32_16x16x32_bf16 v[70:73], v[118:121], v[192:195], v[70:73]
	v_mfma_f32_16x16x32_bf16 v[74:77], v[30:33], v[200:203], v[74:77]
	v_mfma_f32_16x16x32_bf16 v[78:81], v[118:121], v[200:203], v[78:81]
	v_mfma_f32_16x16x32_bf16 v[82:85], v[30:33], v[208:211], v[82:85]
	v_mfma_f32_16x16x32_bf16 v[86:89], v[118:121], v[208:211], v[86:89]
	v_mfma_f32_16x16x32_bf16 v[90:93], v[30:33], v[216:219], v[90:93]
	v_mfma_f32_16x16x32_bf16 v[94:97], v[118:121], v[216:219], v[94:97]
	s_setprio 0
	s_setprio 1
	v_mfma_f32_16x16x32_bf16 v[98:101], v[122:125], v[188:191], v[98:101]
	v_mfma_f32_16x16x32_bf16 v[34:37], v[180:183], v[188:191], v[34:37]
	v_mfma_f32_16x16x32_bf16 v[38:41], v[122:125], v[196:199], v[38:41]
	v_mfma_f32_16x16x32_bf16 v[42:45], v[180:183], v[196:199], v[42:45]
	v_mfma_f32_16x16x32_bf16 v[46:49], v[122:125], v[204:207], v[46:49]
	v_mfma_f32_16x16x32_bf16 v[50:53], v[180:183], v[204:207], v[50:53]
	v_mfma_f32_16x16x32_bf16 v[54:57], v[122:125], v[212:215], v[54:57]
	v_mfma_f32_16x16x32_bf16 v[58:61], v[180:183], v[212:215], v[58:61]
	v_mfma_f32_16x16x32_bf16 v[98:101], v[126:129], v[192:195], v[98:101]
	v_mfma_f32_16x16x32_bf16 v[34:37], v[184:187], v[192:195], v[34:37]
	v_mfma_f32_16x16x32_bf16 v[38:41], v[126:129], v[200:203], v[38:41]
	v_mfma_f32_16x16x32_bf16 v[42:45], v[184:187], v[200:203], v[42:45]
	v_mfma_f32_16x16x32_bf16 v[46:49], v[126:129], v[208:211], v[46:49]
	v_mfma_f32_16x16x32_bf16 v[50:53], v[184:187], v[208:211], v[50:53]
	v_mfma_f32_16x16x32_bf16 v[54:57], v[126:129], v[216:219], v[54:57]
	v_mfma_f32_16x16x32_bf16 v[58:61], v[184:187], v[216:219], v[58:61]
	s_setprio 0
	s_barrier
	s_add_i32 s80, s78, s64
	s_add_i32 s78, s80, 0x2000
	v_lshl_add_u64 v[144:145], v[144:145], 0, s[44:45]
	s_mov_b32 m0, s80
	s_add_u32 s82, s58, 0x10180
	ds_read_b128 v[188:191], v153 offset:49152
	ds_read_b128 v[192:195], v153 offset:50176
	ds_read_b128 v[196:199], v153 offset:51200
	ds_read_b128 v[200:203], v153 offset:52224
	ds_read_b128 v[204:207], v153 offset:53248
	ds_read_b128 v[208:211], v153 offset:54272
	ds_read_b128 v[212:215], v153 offset:55296
	ds_read_b128 v[216:219], v153 offset:56320
	global_load_lds_dwordx4 v[144:145], off
	v_lshl_add_u64 v[144:145], v[220:221], 0, s[44:45]
	s_mov_b32 m0, s78
	s_addc_u32 s83, s59, 0
	s_add_i32 s58, s84, s64
	global_load_lds_dwordx4 v[144:145], off
	v_lshl_add_u64 v[144:145], s[82:83], 0, v[132:133]
	s_mov_b32 m0, s58
	s_add_i32 s59, s58, 0x2000
	global_load_lds_dwordx4 v[144:145], off
	v_lshl_add_u64 v[144:145], s[82:83], 0, v[136:137]
	s_mov_b32 m0, s59
	s_nop 0
	global_load_lds_dwordx4 v[144:145], off
	v_lshl_add_u64 v[144:145], v[222:223], 0, s[44:45]
	s_mov_b32 m0, s69
	s_nop 0
	global_load_lds_dwordx4 v[144:145], off
	v_lshl_add_u64 v[144:145], v[224:225], 0, s[44:45]
	s_mov_b32 m0, s70
	s_nop 0
	global_load_lds_dwordx4 v[144:145], off
	s_waitcnt vmcnt(8)
	s_waitcnt lgkmcnt(0)
	s_setprio 1
	s_barrier
	v_mfma_f32_16x16x32_bf16 v[2:5], v[26:29], v[212:215], v[2:5]
	v_mfma_f32_16x16x32_bf16 v[6:9], v[114:117], v[212:215], v[6:9]
	v_mfma_f32_16x16x32_bf16 v[156:159], v[26:29], v[188:191], v[156:159]
	v_mfma_f32_16x16x32_bf16 v[160:163], v[114:117], v[188:191], v[160:163]
	v_mfma_f32_16x16x32_bf16 v[164:167], v[26:29], v[196:199], v[164:167]
	v_mfma_f32_16x16x32_bf16 v[168:171], v[114:117], v[196:199], v[168:171]
	v_mfma_f32_16x16x32_bf16 v[172:175], v[26:29], v[204:207], v[172:175]
	v_mfma_f32_16x16x32_bf16 v[176:179], v[114:117], v[204:207], v[176:179]
	v_mfma_f32_16x16x32_bf16 v[2:5], v[30:33], v[216:219], v[2:5]
	v_mfma_f32_16x16x32_bf16 v[6:9], v[118:121], v[216:219], v[6:9]
	v_mfma_f32_16x16x32_bf16 v[156:159], v[30:33], v[192:195], v[156:159]
	v_mfma_f32_16x16x32_bf16 v[160:163], v[118:121], v[192:195], v[160:163]
	v_mfma_f32_16x16x32_bf16 v[164:167], v[30:33], v[200:203], v[164:167]
	v_mfma_f32_16x16x32_bf16 v[168:171], v[118:121], v[200:203], v[168:171]
	v_mfma_f32_16x16x32_bf16 v[172:175], v[30:33], v[208:211], v[172:175]
	v_mfma_f32_16x16x32_bf16 v[176:179], v[118:121], v[208:211], v[176:179]
	s_setprio 0
	s_setprio 1
	v_mfma_f32_16x16x32_bf16 v[10:13], v[122:125], v[188:191], v[10:13]
	v_mfma_f32_16x16x32_bf16 v[14:17], v[180:183], v[188:191], v[14:17]
	v_mfma_f32_16x16x32_bf16 v[26:29], v[122:125], v[196:199], v[62:65]
	v_mfma_f32_16x16x32_bf16 v[30:33], v[180:183], v[196:199], v[102:105]
	v_mfma_f32_16x16x32_bf16 v[62:65], v[122:125], v[204:207], v[106:109]
	v_mfma_f32_16x16x32_bf16 v[102:105], v[180:183], v[204:207], v[110:113]
	v_mfma_f32_16x16x32_bf16 v[18:21], v[122:125], v[212:215], v[18:21]
	v_mfma_f32_16x16x32_bf16 v[22:25], v[180:183], v[212:215], v[22:25]
	v_mfma_f32_16x16x32_bf16 v[10:13], v[126:129], v[192:195], v[10:13]
	v_mfma_f32_16x16x32_bf16 v[14:17], v[184:187], v[192:195], v[14:17]
	v_mfma_f32_16x16x32_bf16 v[26:29], v[126:129], v[200:203], v[26:29]
	v_mfma_f32_16x16x32_bf16 v[30:33], v[184:187], v[200:203], v[30:33]
	v_mfma_f32_16x16x32_bf16 v[62:65], v[126:129], v[208:211], v[62:65]
	v_mfma_f32_16x16x32_bf16 v[102:105], v[184:187], v[208:211], v[102:105]
	v_mfma_f32_16x16x32_bf16 v[18:21], v[126:129], v[216:219], v[18:21]
	v_mfma_f32_16x16x32_bf16 v[22:25], v[184:187], v[216:219], v[22:25]
	s_setprio 0
	s_barrier
	ds_read_b128 v[106:109], v151
	ds_read_b128 v[110:113], v151 offset:1024
	ds_read_b128 v[114:117], v151 offset:2048
	ds_read_b128 v[118:121], v151 offset:3072
	ds_read_b128 v[122:125], v152
	ds_read_b128 v[126:129], v152 offset:1024
	ds_read_b128 v[180:183], v152 offset:2048
	ds_read_b128 v[184:187], v152 offset:3072
	s_add_u32 s56, s56, 0x10180
	s_addc_u32 s57, s57, 0
	s_mov_b32 m0, s79
	v_lshl_add_u64 v[144:145], s[56:57], 0, v[130:131]
	ds_read_b128 v[188:191], v153
	ds_read_b128 v[192:195], v153 offset:1024
	ds_read_b128 v[196:199], v153 offset:2048
	ds_read_b128 v[200:203], v153 offset:3072
	ds_read_b128 v[204:207], v153 offset:4096
	ds_read_b128 v[208:211], v153 offset:5120
	ds_read_b128 v[212:215], v153 offset:6144
	ds_read_b128 v[216:219], v153 offset:7168
	global_load_lds_dwordx4 v[144:145], off
	v_lshl_add_u64 v[144:145], s[56:57], 0, v[134:135]
	s_mov_b32 m0, s47
	s_nop 0
	global_load_lds_dwordx4 v[144:145], off
	s_waitcnt vmcnt(8)
	s_waitcnt lgkmcnt(0)
	s_setprio 1
	s_barrier
	v_mfma_f32_16x16x32_bf16 v[66:69], v[106:109], v[188:191], v[66:69]
	v_mfma_f32_16x16x32_bf16 v[70:73], v[114:117], v[188:191], v[70:73]
	v_mfma_f32_16x16x32_bf16 v[74:77], v[106:109], v[196:199], v[74:77]
	v_mfma_f32_16x16x32_bf16 v[78:81], v[114:117], v[196:199], v[78:81]
	v_mfma_f32_16x16x32_bf16 v[82:85], v[106:109], v[204:207], v[82:85]
	v_mfma_f32_16x16x32_bf16 v[86:89], v[114:117], v[204:207], v[86:89]
	v_mfma_f32_16x16x32_bf16 v[90:93], v[106:109], v[212:215], v[90:93]
	v_mfma_f32_16x16x32_bf16 v[94:97], v[114:117], v[212:215], v[94:97]
	v_mfma_f32_16x16x32_bf16 v[66:69], v[110:113], v[192:195], v[66:69]
	v_mfma_f32_16x16x32_bf16 v[70:73], v[118:121], v[192:195], v[70:73]
	v_mfma_f32_16x16x32_bf16 v[74:77], v[110:113], v[200:203], v[74:77]
	v_mfma_f32_16x16x32_bf16 v[78:81], v[118:121], v[200:203], v[78:81]
	v_mfma_f32_16x16x32_bf16 v[82:85], v[110:113], v[208:211], v[82:85]
	v_mfma_f32_16x16x32_bf16 v[86:89], v[118:121], v[208:211], v[86:89]
	v_mfma_f32_16x16x32_bf16 v[90:93], v[110:113], v[216:219], v[90:93]
	v_mfma_f32_16x16x32_bf16 v[94:97], v[118:121], v[216:219], v[94:97]
	s_setprio 0
	s_setprio 1
	v_mfma_f32_16x16x32_bf16 v[34:37], v[180:183], v[188:191], v[34:37]
	v_mfma_f32_16x16x32_bf16 v[38:41], v[122:125], v[196:199], v[38:41]
	v_mfma_f32_16x16x32_bf16 v[42:45], v[180:183], v[196:199], v[42:45]
	v_mfma_f32_16x16x32_bf16 v[46:49], v[122:125], v[204:207], v[46:49]
	v_mfma_f32_16x16x32_bf16 v[50:53], v[180:183], v[204:207], v[50:53]
	v_mfma_f32_16x16x32_bf16 v[54:57], v[122:125], v[212:215], v[54:57]
	v_mfma_f32_16x16x32_bf16 v[58:61], v[180:183], v[212:215], v[58:61]
	v_mfma_f32_16x16x32_bf16 v[98:101], v[122:125], v[188:191], v[98:101]
	v_mfma_f32_16x16x32_bf16 v[34:37], v[184:187], v[192:195], v[34:37]
	v_mfma_f32_16x16x32_bf16 v[38:41], v[126:129], v[200:203], v[38:41]
	v_mfma_f32_16x16x32_bf16 v[42:45], v[184:187], v[200:203], v[42:45]
	v_mfma_f32_16x16x32_bf16 v[46:49], v[126:129], v[208:211], v[46:49]
	v_mfma_f32_16x16x32_bf16 v[50:53], v[184:187], v[208:211], v[50:53]
	v_mfma_f32_16x16x32_bf16 v[54:57], v[126:129], v[216:219], v[54:57]
	v_mfma_f32_16x16x32_bf16 v[58:61], v[184:187], v[216:219], v[58:61]
	v_mfma_f32_16x16x32_bf16 v[220:223], v[126:129], v[192:195], v[98:101]
	s_setprio 0
	s_barrier
	s_mov_b32 m0, s77
	v_lshl_add_u64 v[144:145], s[60:61], 0, v[132:133]
	s_add_u32 s56, s60, 0x10000
	ds_read_b128 v[98:101], v153 offset:16384
	ds_read_b128 v[188:191], v153 offset:17408
	ds_read_b128 v[192:195], v153 offset:18432
	ds_read_b128 v[196:199], v153 offset:19456
	ds_read_b128 v[200:203], v153 offset:20480
	ds_read_b128 v[204:207], v153 offset:21504
	ds_read_b128 v[208:211], v153 offset:22528
	ds_read_b128 v[212:215], v153 offset:23552
	global_load_lds_dwordx4 v[144:145], off
	v_lshl_add_u64 v[240:241], s[60:61], 0, v[136:137]
	s_mov_b32 m0, s49
	s_addc_u32 s57, s61, 0
	global_load_lds_dwordx4 v[240:241], off
	v_lshl_add_u64 v[216:217], s[56:57], 0, v[132:133]
	s_mov_b32 m0, s75
	v_lshl_add_u64 v[252:253], s[62:63], 0, v[130:131]
	global_load_lds_dwordx4 v[216:217], off
	v_lshl_add_u64 v[216:217], s[56:57], 0, v[136:137]
	s_mov_b32 m0, s76
	v_lshl_add_u64 v[254:255], s[62:63], 0, v[134:135]
	global_load_lds_dwordx4 v[216:217], off
	s_mov_b32 m0, s65
	s_nop 0
	global_load_lds_dwordx4 v[252:253], off
	s_mov_b32 m0, s66
	s_nop 0
	global_load_lds_dwordx4 v[254:255], off
	s_waitcnt vmcnt(8)
	s_waitcnt lgkmcnt(0)
	s_setprio 1
	s_barrier
	v_mfma_f32_16x16x32_bf16 v[2:5], v[106:109], v[208:211], v[2:5]
	v_mfma_f32_16x16x32_bf16 v[6:9], v[114:117], v[208:211], v[6:9]
	v_mfma_f32_16x16x32_bf16 v[156:159], v[106:109], v[98:101], v[156:159]
	v_mfma_f32_16x16x32_bf16 v[160:163], v[114:117], v[98:101], v[160:163]
	v_mfma_f32_16x16x32_bf16 v[164:167], v[106:109], v[192:195], v[164:167]
	v_mfma_f32_16x16x32_bf16 v[168:171], v[114:117], v[192:195], v[168:171]
	v_mfma_f32_16x16x32_bf16 v[172:175], v[106:109], v[200:203], v[172:175]
	v_mfma_f32_16x16x32_bf16 v[176:179], v[114:117], v[200:203], v[176:179]
	v_mfma_f32_16x16x32_bf16 v[2:5], v[110:113], v[212:215], v[2:5]
	v_mfma_f32_16x16x32_bf16 v[6:9], v[118:121], v[212:215], v[6:9]
	v_mfma_f32_16x16x32_bf16 v[156:159], v[110:113], v[188:191], v[156:159]
	v_mfma_f32_16x16x32_bf16 v[160:163], v[118:121], v[188:191], v[160:163]
	v_mfma_f32_16x16x32_bf16 v[164:167], v[110:113], v[196:199], v[164:167]
	v_mfma_f32_16x16x32_bf16 v[168:171], v[118:121], v[196:199], v[168:171]
	v_mfma_f32_16x16x32_bf16 v[172:175], v[110:113], v[204:207], v[172:175]
	v_mfma_f32_16x16x32_bf16 v[176:179], v[118:121], v[204:207], v[176:179]
	s_setprio 0
	s_setprio 1
	v_mfma_f32_16x16x32_bf16 v[10:13], v[122:125], v[98:101], v[10:13]
	v_mfma_f32_16x16x32_bf16 v[14:17], v[180:183], v[98:101], v[14:17]
	v_mfma_f32_16x16x32_bf16 v[26:29], v[122:125], v[192:195], v[26:29]
	v_mfma_f32_16x16x32_bf16 v[30:33], v[180:183], v[192:195], v[30:33]
	v_mfma_f32_16x16x32_bf16 v[62:65], v[122:125], v[200:203], v[62:65]
	v_mfma_f32_16x16x32_bf16 v[18:21], v[122:125], v[208:211], v[18:21]
	v_mfma_f32_16x16x32_bf16 v[10:13], v[126:129], v[188:191], v[10:13]
	v_mfma_f32_16x16x32_bf16 v[14:17], v[184:187], v[188:191], v[14:17]
	v_mfma_f32_16x16x32_bf16 v[26:29], v[126:129], v[196:199], v[26:29]
	v_mfma_f32_16x16x32_bf16 v[30:33], v[184:187], v[196:199], v[30:33]
	v_mfma_f32_16x16x32_bf16 v[188:191], v[126:129], v[204:207], v[62:65]
	v_mfma_f32_16x16x32_bf16 v[62:65], v[180:183], v[200:203], v[102:105]
	v_mfma_f32_16x16x32_bf16 v[196:199], v[126:129], v[212:215], v[18:21]
	v_mfma_f32_16x16x32_bf16 v[18:21], v[180:183], v[208:211], v[22:25]
	v_mfma_f32_16x16x32_bf16 v[192:195], v[184:187], v[204:207], v[62:65]
	v_mfma_f32_16x16x32_bf16 v[180:183], v[184:187], v[212:215], v[18:21]
	s_setprio 0
	s_barrier
	s_nop 1
	ds_read_b128 v[62:65], v155
	ds_read_b128 v[184:187], v155 offset:1024
	ds_read_b128 v[200:203], v155 offset:2048
	ds_read_b128 v[204:207], v155 offset:3072
	ds_read_b128 v[208:211], v228
	ds_read_b128 v[212:215], v228 offset:1024
	ds_read_b128 v[216:219], v228 offset:2048
	ds_read_b128 v[224:227], v228 offset:3072
	s_add_u32 s56, s62, 0x10000
	s_addc_u32 s57, s63, 0
	s_mov_b32 m0, s67
	v_lshl_add_u64 v[98:99], s[56:57], 0, v[130:131]
	ds_read_b128 v[18:21], v153 offset:32768
	ds_read_b128 v[22:25], v153 offset:33792
	ds_read_b128 v[110:113], v153 offset:34816
	ds_read_b128 v[228:231], v153 offset:35840
	ds_read_b128 v[232:235], v153 offset:36864
	ds_read_b128 v[236:239], v153 offset:37888
	ds_read_b128 v[244:247], v153 offset:38912
	ds_read_b128 v[248:251], v153 offset:39936
	global_load_lds_dwordx4 v[98:99], off
	v_lshl_add_u64 v[98:99], s[56:57], 0, v[134:135]
	s_mov_b32 m0, s68
	s_nop 0
	global_load_lds_dwordx4 v[98:99], off
	s_waitcnt vmcnt(8)
	s_waitcnt lgkmcnt(0)
	s_setprio 1
	s_barrier
	v_mfma_f32_16x16x32_bf16 v[66:69], v[62:65], v[18:21], v[66:69]
	v_mfma_f32_16x16x32_bf16 v[114:117], v[184:187], v[22:25], v[66:69]
	v_mfma_f32_16x16x32_bf16 v[66:69], v[200:203], v[18:21], v[70:73]
	v_mfma_f32_16x16x32_bf16 v[118:121], v[204:207], v[22:25], v[66:69]
	v_mfma_f32_16x16x32_bf16 v[66:69], v[62:65], v[110:113], v[74:77]
	v_mfma_f32_16x16x32_bf16 v[98:101], v[184:187], v[228:231], v[66:69]
	v_mfma_f32_16x16x32_bf16 v[66:69], v[200:203], v[110:113], v[78:81]
	v_mfma_f32_16x16x32_bf16 v[102:105], v[204:207], v[228:231], v[66:69]
	v_mfma_f32_16x16x32_bf16 v[66:69], v[62:65], v[232:235], v[82:85]
	v_mfma_f32_16x16x32_bf16 v[82:85], v[184:187], v[236:239], v[66:69]
	v_mfma_f32_16x16x32_bf16 v[66:69], v[200:203], v[232:235], v[86:89]
	v_mfma_f32_16x16x32_bf16 v[86:89], v[204:207], v[236:239], v[66:69]
	v_mfma_f32_16x16x32_bf16 v[66:69], v[62:65], v[244:247], v[90:93]
	v_mfma_f32_16x16x32_bf16 v[70:73], v[200:203], v[244:247], v[94:97]
	v_mfma_f32_16x16x32_bf16 v[66:69], v[184:187], v[248:251], v[66:69]
	v_mfma_f32_16x16x32_bf16 v[70:73], v[204:207], v[248:251], v[70:73]
	s_setprio 0
	s_setprio 1
	v_mfma_f32_16x16x32_bf16 v[74:77], v[208:211], v[18:21], v[220:223]
	v_mfma_f32_16x16x32_bf16 v[18:21], v[216:219], v[18:21], v[34:37]
	v_mfma_f32_16x16x32_bf16 v[126:129], v[224:227], v[22:25], v[18:21]
	v_mfma_f32_16x16x32_bf16 v[18:21], v[208:211], v[110:113], v[38:41]
	v_mfma_f32_16x16x32_bf16 v[106:109], v[212:215], v[228:231], v[18:21]
	v_mfma_f32_16x16x32_bf16 v[18:21], v[216:219], v[110:113], v[42:45]
	v_mfma_f32_16x16x32_bf16 v[110:113], v[224:227], v[228:231], v[18:21]
	v_mfma_f32_16x16x32_bf16 v[18:21], v[208:211], v[232:235], v[46:49]
	v_mfma_f32_16x16x32_bf16 v[90:93], v[212:215], v[236:239], v[18:21]
	v_mfma_f32_16x16x32_bf16 v[18:21], v[216:219], v[232:235], v[50:53]
	v_mfma_f32_16x16x32_bf16 v[94:97], v[224:227], v[236:239], v[18:21]
	v_mfma_f32_16x16x32_bf16 v[18:21], v[208:211], v[244:247], v[54:57]
	v_mfma_f32_16x16x32_bf16 v[122:125], v[212:215], v[22:25], v[74:77]
	v_mfma_f32_16x16x32_bf16 v[74:77], v[212:215], v[248:251], v[18:21]
	v_mfma_f32_16x16x32_bf16 v[18:21], v[216:219], v[244:247], v[58:61]
	v_mfma_f32_16x16x32_bf16 v[78:81], v[224:227], v[248:251], v[18:21]
	s_setprio 0
	s_barrier
	s_mov_b32 m0, s80
	s_nop 3
	v_lshl_add_u64 v[18:19], v[144:145], 0, s[16:17]
	s_add_u32 s56, s60, 0x10080
	ds_read_b128 v[42:45], v153 offset:49152
	ds_read_b128 v[46:49], v153 offset:50176
	ds_read_b128 v[220:223], v153 offset:51200
	ds_read_b128 v[228:231], v153 offset:52224
	ds_read_b128 v[232:235], v153 offset:53248
	ds_read_b128 v[236:239], v153 offset:54272
	ds_read_b128 v[244:247], v153 offset:55296
	ds_read_b128 v[248:251], v153 offset:56320
	global_load_lds_dwordx4 v[18:19], off
	v_lshl_add_u64 v[18:19], v[240:241], 0, s[16:17]
	s_mov_b32 m0, s78
	s_addc_u32 s57, s61, 0
	global_load_lds_dwordx4 v[18:19], off
	v_lshl_add_u64 v[18:19], s[56:57], 0, v[132:133]
	s_mov_b32 m0, s58
	s_nop 0
	global_load_lds_dwordx4 v[18:19], off
	v_lshl_add_u64 v[18:19], s[56:57], 0, v[136:137]
	s_mov_b32 m0, s59
	s_nop 0
	global_load_lds_dwordx4 v[18:19], off
	v_lshl_add_u64 v[18:19], v[252:253], 0, s[16:17]
	s_mov_b32 m0, s69
	s_nop 0
	global_load_lds_dwordx4 v[18:19], off
	v_lshl_add_u64 v[18:19], v[254:255], 0, s[16:17]
	s_mov_b32 m0, s70
	s_nop 0
	global_load_lds_dwordx4 v[18:19], off
	s_waitcnt vmcnt(8)
	s_waitcnt lgkmcnt(0)
	s_setprio 1
	s_barrier
	v_mfma_f32_16x16x32_bf16 v[18:21], v[62:65], v[42:45], v[156:159]
	v_mfma_f32_16x16x32_bf16 v[50:53], v[184:187], v[46:49], v[18:21]
	v_mfma_f32_16x16x32_bf16 v[18:21], v[200:203], v[42:45], v[160:163]
	v_mfma_f32_16x16x32_bf16 v[54:57], v[204:207], v[46:49], v[18:21]
	v_mfma_f32_16x16x32_bf16 v[18:21], v[62:65], v[220:223], v[164:167]
	v_mfma_f32_16x16x32_bf16 v[34:37], v[184:187], v[228:231], v[18:21]
	v_mfma_f32_16x16x32_bf16 v[18:21], v[200:203], v[220:223], v[168:171]
	v_mfma_f32_16x16x32_bf16 v[38:41], v[204:207], v[228:231], v[18:21]
	v_mfma_f32_16x16x32_bf16 v[18:21], v[62:65], v[232:235], v[172:175]
	v_mfma_f32_16x16x32_bf16 v[22:25], v[200:203], v[232:235], v[176:179]
	v_mfma_f32_16x16x32_bf16 v[2:5], v[62:65], v[244:247], v[2:5]
	v_mfma_f32_16x16x32_bf16 v[6:9], v[200:203], v[244:247], v[6:9]
	v_mfma_f32_16x16x32_bf16 v[18:21], v[184:187], v[236:239], v[18:21]
	v_mfma_f32_16x16x32_bf16 v[22:25], v[204:207], v[236:239], v[22:25]
	v_mfma_f32_16x16x32_bf16 v[2:5], v[184:187], v[248:251], v[2:5]
	v_mfma_f32_16x16x32_bf16 v[6:9], v[204:207], v[248:251], v[6:9]
	s_setprio 0
	s_setprio 1
	v_mfma_f32_16x16x32_bf16 v[10:13], v[208:211], v[42:45], v[10:13]
	v_mfma_f32_16x16x32_bf16 v[58:61], v[212:215], v[46:49], v[10:13]
	v_mfma_f32_16x16x32_bf16 v[10:13], v[216:219], v[42:45], v[14:17]
	v_mfma_f32_16x16x32_bf16 v[62:65], v[224:227], v[46:49], v[10:13]
	v_mfma_f32_16x16x32_bf16 v[10:13], v[208:211], v[220:223], v[26:29]
	v_mfma_f32_16x16x32_bf16 v[42:45], v[212:215], v[228:231], v[10:13]
	v_mfma_f32_16x16x32_bf16 v[10:13], v[216:219], v[220:223], v[30:33]
	v_mfma_f32_16x16x32_bf16 v[46:49], v[224:227], v[228:231], v[10:13]
	v_mfma_f32_16x16x32_bf16 v[10:13], v[208:211], v[232:235], v[188:191]
	v_mfma_f32_16x16x32_bf16 v[26:29], v[212:215], v[236:239], v[10:13]
	v_mfma_f32_16x16x32_bf16 v[10:13], v[216:219], v[232:235], v[192:195]
	v_mfma_f32_16x16x32_bf16 v[30:33], v[224:227], v[236:239], v[10:13]
	v_mfma_f32_16x16x32_bf16 v[10:13], v[208:211], v[244:247], v[196:199]
	v_mfma_f32_16x16x32_bf16 v[14:17], v[216:219], v[244:247], v[180:183]
	v_mfma_f32_16x16x32_bf16 v[10:13], v[212:215], v[248:251], v[10:13]
	v_mfma_f32_16x16x32_bf16 v[14:17], v[224:227], v[248:251], v[14:17]
	s_setprio 0
	s_barrier
	s_andn2_b64 vcc, exec, s[24:25]
	s_cbranch_vccnz .LBB0_1226
	s_barrier

.LBB0_1357:
	ds_read_b128 v[158:161], v152
	ds_read_b128 v[162:165], v152 offset:1024
	ds_read_b128 v[166:169], v152 offset:2048
	ds_read_b128 v[170:173], v152 offset:3072
	ds_read_b128 v[174:177], v153
	ds_read_b128 v[178:181], v153 offset:1024
	ds_read_b128 v[182:185], v153 offset:2048
	ds_read_b128 v[186:189], v153 offset:3072
	s_add_u32 s56, s54, 0xfffc0080
	s_addc_u32 s57, s55, -1
	s_cmp_eq_u32 s76, 12
	s_cselect_b32 s59, s45, s57
	s_cselect_b32 s58, s51, s56
	s_cselect_b32 s57, s43, s75
	s_cselect_b32 s56, s53, s74
	v_lshl_add_u64 v[148:149], s[54:55], 0, v[140:141]
	s_add_i32 m0, s61, 0xc000
	ds_read_b128 v[190:193], v154
	ds_read_b128 v[194:197], v154 offset:1024
	ds_read_b128 v[198:201], v154 offset:2048
	ds_read_b128 v[202:205], v154 offset:3072
	ds_read_b128 v[206:209], v154 offset:4096
	ds_read_b128 v[210:213], v154 offset:5120
	ds_read_b128 v[214:217], v154 offset:6144
	ds_read_b128 v[218:221], v154 offset:7168
	global_load_lds_dwordx4 v[148:149], off
	v_lshl_add_u64 v[148:149], s[54:55], 0, v[142:143]
	s_add_i32 m0, s61, 0xe000
	s_nop 0
	global_load_lds_dwordx4 v[148:149], off
	s_waitcnt vmcnt(8)
	s_waitcnt lgkmcnt(0)
	s_setprio 1
	s_barrier
	v_mfma_f32_16x16x32_bf16 v[126:129], v[158:161], v[190:193], v[126:129]
	v_mfma_f32_16x16x32_bf16 v[122:125], v[166:169], v[190:193], v[122:125]
	v_mfma_f32_16x16x32_bf16 v[110:113], v[158:161], v[198:201], v[110:113]
	v_mfma_f32_16x16x32_bf16 v[106:109], v[166:169], v[198:201], v[106:109]
	v_mfma_f32_16x16x32_bf16 v[94:97], v[158:161], v[206:209], v[94:97]
	v_mfma_f32_16x16x32_bf16 v[90:93], v[166:169], v[206:209], v[90:93]
	v_mfma_f32_16x16x32_bf16 v[78:81], v[158:161], v[214:217], v[78:81]
	v_mfma_f32_16x16x32_bf16 v[74:77], v[166:169], v[214:217], v[74:77]
	v_mfma_f32_16x16x32_bf16 v[126:129], v[162:165], v[194:197], v[126:129]
	v_mfma_f32_16x16x32_bf16 v[122:125], v[170:173], v[194:197], v[122:125]
	v_mfma_f32_16x16x32_bf16 v[110:113], v[162:165], v[202:205], v[110:113]
	v_mfma_f32_16x16x32_bf16 v[106:109], v[170:173], v[202:205], v[106:109]
	v_mfma_f32_16x16x32_bf16 v[94:97], v[162:165], v[210:213], v[94:97]
	v_mfma_f32_16x16x32_bf16 v[90:93], v[170:173], v[210:213], v[90:93]
	v_mfma_f32_16x16x32_bf16 v[78:81], v[162:165], v[218:221], v[78:81]
	v_mfma_f32_16x16x32_bf16 v[74:77], v[170:173], v[218:221], v[74:77]
	s_setprio 0
	s_setprio 1
	v_mfma_f32_16x16x32_bf16 v[118:121], v[174:177], v[190:193], v[118:121]
	v_mfma_f32_16x16x32_bf16 v[114:117], v[182:185], v[190:193], v[114:117]
	v_mfma_f32_16x16x32_bf16 v[102:105], v[174:177], v[198:201], v[102:105]
	v_mfma_f32_16x16x32_bf16 v[98:101], v[182:185], v[198:201], v[98:101]
	v_mfma_f32_16x16x32_bf16 v[86:89], v[174:177], v[206:209], v[86:89]
	v_mfma_f32_16x16x32_bf16 v[82:85], v[182:185], v[206:209], v[82:85]
	v_mfma_f32_16x16x32_bf16 v[70:73], v[174:177], v[214:217], v[70:73]
	v_mfma_f32_16x16x32_bf16 v[66:69], v[182:185], v[214:217], v[66:69]
	v_mfma_f32_16x16x32_bf16 v[118:121], v[178:181], v[194:197], v[118:121]
	v_mfma_f32_16x16x32_bf16 v[114:117], v[186:189], v[194:197], v[114:117]
	v_mfma_f32_16x16x32_bf16 v[102:105], v[178:181], v[202:205], v[102:105]
	v_mfma_f32_16x16x32_bf16 v[98:101], v[186:189], v[202:205], v[98:101]
	v_mfma_f32_16x16x32_bf16 v[86:89], v[178:181], v[210:213], v[86:89]
	v_mfma_f32_16x16x32_bf16 v[82:85], v[186:189], v[210:213], v[82:85]
	v_mfma_f32_16x16x32_bf16 v[70:73], v[178:181], v[218:221], v[70:73]
	v_mfma_f32_16x16x32_bf16 v[66:69], v[186:189], v[218:221], v[66:69]
	s_setprio 0
	s_barrier
	s_add_i32 s77, s71, s60
	v_lshl_add_u64 v[148:149], s[56:57], 0, v[132:133]
	s_mov_b32 m0, s77
	ds_read_b128 v[190:193], v154 offset:16384
	ds_read_b128 v[194:197], v154 offset:17408
	ds_read_b128 v[198:201], v154 offset:18432
	ds_read_b128 v[202:205], v154 offset:19456
	ds_read_b128 v[206:209], v154 offset:20480
	ds_read_b128 v[210:213], v154 offset:21504
	ds_read_b128 v[214:217], v154 offset:22528
	ds_read_b128 v[218:221], v154 offset:23552
	global_load_lds_dwordx4 v[148:149], off
	s_add_i32 m0, s77, 0x2000
	s_add_u32 s78, s56, 0x40000
	v_lshl_add_u64 v[222:223], s[56:57], 0, v[136:137]
	s_addc_u32 s79, s57, 0
	s_add_i32 s77, s72, s60
	global_load_lds_dwordx4 v[222:223], off
	v_lshl_add_u64 v[224:225], s[78:79], 0, v[132:133]
	s_mov_b32 m0, s77
	v_lshl_add_u64 v[226:227], s[58:59], 0, v[134:135]
	global_load_lds_dwordx4 v[224:225], off
	v_lshl_add_u64 v[224:225], s[78:79], 0, v[136:137]
	s_add_i32 m0, s77, 0x2000
	s_nop 0
	global_load_lds_dwordx4 v[224:225], off
	v_lshl_add_u64 v[224:225], s[58:59], 0, v[130:131]
	s_mov_b32 m0, s61
	s_nop 0
	global_load_lds_dwordx4 v[224:225], off
	s_mov_b32 m0, s62
	s_nop 0
	global_load_lds_dwordx4 v[226:227], off
	s_waitcnt vmcnt(8)
	s_waitcnt lgkmcnt(0)
	s_setprio 1
	s_barrier
	v_mfma_f32_16x16x32_bf16 v[62:65], v[158:161], v[190:193], v[62:65]
	v_mfma_f32_16x16x32_bf16 v[58:61], v[166:169], v[190:193], v[58:61]
	v_mfma_f32_16x16x32_bf16 v[46:49], v[158:161], v[198:201], v[46:49]
	v_mfma_f32_16x16x32_bf16 v[42:45], v[166:169], v[198:201], v[42:45]
	v_mfma_f32_16x16x32_bf16 v[30:33], v[158:161], v[206:209], v[30:33]
	v_mfma_f32_16x16x32_bf16 v[26:29], v[166:169], v[206:209], v[26:29]
	v_mfma_f32_16x16x32_bf16 v[14:17], v[158:161], v[214:217], v[14:17]
	v_mfma_f32_16x16x32_bf16 v[10:13], v[166:169], v[214:217], v[10:13]
	v_mfma_f32_16x16x32_bf16 v[62:65], v[162:165], v[194:197], v[62:65]
	v_mfma_f32_16x16x32_bf16 v[58:61], v[170:173], v[194:197], v[58:61]
	v_mfma_f32_16x16x32_bf16 v[46:49], v[162:165], v[202:205], v[46:49]
	v_mfma_f32_16x16x32_bf16 v[42:45], v[170:173], v[202:205], v[42:45]
	v_mfma_f32_16x16x32_bf16 v[30:33], v[162:165], v[210:213], v[30:33]
	v_mfma_f32_16x16x32_bf16 v[26:29], v[170:173], v[210:213], v[26:29]
	v_mfma_f32_16x16x32_bf16 v[14:17], v[162:165], v[218:221], v[14:17]
	v_mfma_f32_16x16x32_bf16 v[10:13], v[170:173], v[218:221], v[10:13]
	s_setprio 0
	s_setprio 1
	v_mfma_f32_16x16x32_bf16 v[54:57], v[174:177], v[190:193], v[54:57]
	v_mfma_f32_16x16x32_bf16 v[50:53], v[182:185], v[190:193], v[50:53]
	v_mfma_f32_16x16x32_bf16 v[38:41], v[174:177], v[198:201], v[38:41]
	v_mfma_f32_16x16x32_bf16 v[34:37], v[182:185], v[198:201], v[34:37]
	v_mfma_f32_16x16x32_bf16 v[22:25], v[174:177], v[206:209], v[22:25]
	v_mfma_f32_16x16x32_bf16 v[18:21], v[182:185], v[206:209], v[18:21]
	v_mfma_f32_16x16x32_bf16 v[6:9], v[174:177], v[214:217], v[6:9]
	v_mfma_f32_16x16x32_bf16 v[2:5], v[182:185], v[214:217], v[2:5]
	v_mfma_f32_16x16x32_bf16 v[54:57], v[178:181], v[194:197], v[54:57]
	v_mfma_f32_16x16x32_bf16 v[50:53], v[186:189], v[194:197], v[50:53]
	v_mfma_f32_16x16x32_bf16 v[38:41], v[178:181], v[202:205], v[38:41]
	v_mfma_f32_16x16x32_bf16 v[34:37], v[186:189], v[202:205], v[34:37]
	v_mfma_f32_16x16x32_bf16 v[22:25], v[178:181], v[210:213], v[22:25]
	v_mfma_f32_16x16x32_bf16 v[18:21], v[186:189], v[210:213], v[18:21]
	v_mfma_f32_16x16x32_bf16 v[6:9], v[178:181], v[218:221], v[6:9]
	v_mfma_f32_16x16x32_bf16 v[2:5], v[186:189], v[218:221], v[2:5]
	s_setprio 0
	s_barrier
	s_add_i32 s77, 0, 0x18000
	v_add_u32_e32 v157, s77, v151
	s_add_i32 s78, 0, 0x1c000
	ds_read_b128 v[158:161], v157
	ds_read_b128 v[162:165], v157 offset:1024
	ds_read_b128 v[166:169], v157 offset:2048
	ds_read_b128 v[170:173], v157 offset:3072
	v_add_u32_e32 v157, s78, v151
	ds_read_b128 v[174:177], v157
	ds_read_b128 v[178:181], v157 offset:1024
	ds_read_b128 v[182:185], v157 offset:2048
	ds_read_b128 v[186:189], v157 offset:3072
	s_add_u32 s58, s58, 0x40000
	s_addc_u32 s59, s59, 0
	s_mov_b32 m0, s63
	v_lshl_add_u64 v[228:229], s[58:59], 0, v[130:131]
	ds_read_b128 v[190:193], v154 offset:32768
	ds_read_b128 v[194:197], v154 offset:33792
	ds_read_b128 v[198:201], v154 offset:34816
	ds_read_b128 v[202:205], v154 offset:35840
	ds_read_b128 v[206:209], v154 offset:36864
	ds_read_b128 v[210:213], v154 offset:37888
	ds_read_b128 v[214:217], v154 offset:38912
	ds_read_b128 v[218:221], v154 offset:39936
	global_load_lds_dwordx4 v[228:229], off
	v_lshl_add_u64 v[228:229], s[58:59], 0, v[134:135]
	s_mov_b32 m0, s64
	s_nop 0
	global_load_lds_dwordx4 v[228:229], off
	s_waitcnt vmcnt(8)
	s_waitcnt lgkmcnt(0)
	s_setprio 1
	s_barrier
	v_mfma_f32_16x16x32_bf16 v[126:129], v[158:161], v[190:193], v[126:129]
	v_mfma_f32_16x16x32_bf16 v[122:125], v[166:169], v[190:193], v[122:125]
	v_mfma_f32_16x16x32_bf16 v[110:113], v[158:161], v[198:201], v[110:113]
	v_mfma_f32_16x16x32_bf16 v[106:109], v[166:169], v[198:201], v[106:109]
	v_mfma_f32_16x16x32_bf16 v[94:97], v[158:161], v[206:209], v[94:97]
	v_mfma_f32_16x16x32_bf16 v[90:93], v[166:169], v[206:209], v[90:93]
	v_mfma_f32_16x16x32_bf16 v[78:81], v[158:161], v[214:217], v[78:81]
	v_mfma_f32_16x16x32_bf16 v[74:77], v[166:169], v[214:217], v[74:77]
	v_mfma_f32_16x16x32_bf16 v[126:129], v[162:165], v[194:197], v[126:129]
	v_mfma_f32_16x16x32_bf16 v[122:125], v[170:173], v[194:197], v[122:125]
	v_mfma_f32_16x16x32_bf16 v[110:113], v[162:165], v[202:205], v[110:113]
	v_mfma_f32_16x16x32_bf16 v[106:109], v[170:173], v[202:205], v[106:109]
	v_mfma_f32_16x16x32_bf16 v[94:97], v[162:165], v[210:213], v[94:97]
	v_mfma_f32_16x16x32_bf16 v[90:93], v[170:173], v[210:213], v[90:93]
	v_mfma_f32_16x16x32_bf16 v[78:81], v[162:165], v[218:221], v[78:81]
	v_mfma_f32_16x16x32_bf16 v[74:77], v[170:173], v[218:221], v[74:77]
	s_setprio 0
	s_setprio 1
	v_mfma_f32_16x16x32_bf16 v[118:121], v[174:177], v[190:193], v[118:121]
	v_mfma_f32_16x16x32_bf16 v[114:117], v[182:185], v[190:193], v[114:117]
	v_mfma_f32_16x16x32_bf16 v[102:105], v[174:177], v[198:201], v[102:105]
	v_mfma_f32_16x16x32_bf16 v[98:101], v[182:185], v[198:201], v[98:101]
	v_mfma_f32_16x16x32_bf16 v[86:89], v[174:177], v[206:209], v[86:89]
	v_mfma_f32_16x16x32_bf16 v[82:85], v[182:185], v[206:209], v[82:85]
	v_mfma_f32_16x16x32_bf16 v[70:73], v[174:177], v[214:217], v[70:73]
	v_mfma_f32_16x16x32_bf16 v[66:69], v[182:185], v[214:217], v[66:69]
	v_mfma_f32_16x16x32_bf16 v[118:121], v[178:181], v[194:197], v[118:121]
	v_mfma_f32_16x16x32_bf16 v[114:117], v[186:189], v[194:197], v[114:117]
	v_mfma_f32_16x16x32_bf16 v[102:105], v[178:181], v[202:205], v[102:105]
	v_mfma_f32_16x16x32_bf16 v[98:101], v[186:189], v[202:205], v[98:101]
	v_mfma_f32_16x16x32_bf16 v[86:89], v[178:181], v[210:213], v[86:89]
	v_mfma_f32_16x16x32_bf16 v[82:85], v[186:189], v[210:213], v[82:85]
	v_mfma_f32_16x16x32_bf16 v[70:73], v[178:181], v[218:221], v[70:73]
	v_mfma_f32_16x16x32_bf16 v[66:69], v[186:189], v[218:221], v[66:69]
	s_setprio 0
	s_barrier
	s_add_i32 s58, s77, s60
	v_lshl_add_u64 v[148:149], v[148:149], 0, s[24:25]
	s_mov_b32 m0, s58
	ds_read_b128 v[190:193], v154 offset:49152
	ds_read_b128 v[194:197], v154 offset:50176
	ds_read_b128 v[198:201], v154 offset:51200
	ds_read_b128 v[202:205], v154 offset:52224
	ds_read_b128 v[206:209], v154 offset:53248
	ds_read_b128 v[210:213], v154 offset:54272
	ds_read_b128 v[214:217], v154 offset:55296
	ds_read_b128 v[218:221], v154 offset:56320
	global_load_lds_dwordx4 v[148:149], off
	s_add_i32 m0, s58, 0x2000
	s_add_u32 s56, s56, 0x40080
	v_lshl_add_u64 v[148:149], v[222:223], 0, s[24:25]
	s_addc_u32 s57, s57, 0
	s_add_i32 s58, s78, s60
	global_load_lds_dwordx4 v[148:149], off
	v_lshl_add_u64 v[148:149], s[56:57], 0, v[132:133]
	s_mov_b32 m0, s58
	s_nop 0
	global_load_lds_dwordx4 v[148:149], off
	v_lshl_add_u64 v[148:149], s[56:57], 0, v[136:137]
	s_add_i32 m0, s58, 0x2000
	s_nop 0
	global_load_lds_dwordx4 v[148:149], off
	v_lshl_add_u64 v[148:149], v[224:225], 0, s[24:25]
	s_mov_b32 m0, s66
	s_nop 0
	global_load_lds_dwordx4 v[148:149], off
	v_lshl_add_u64 v[148:149], v[226:227], 0, s[24:25]
	s_mov_b32 m0, s67
	s_nop 0
	global_load_lds_dwordx4 v[148:149], off
	s_waitcnt vmcnt(8)
	s_waitcnt lgkmcnt(0)
	s_setprio 1
	s_barrier
	v_mfma_f32_16x16x32_bf16 v[62:65], v[158:161], v[190:193], v[62:65]
	v_mfma_f32_16x16x32_bf16 v[58:61], v[166:169], v[190:193], v[58:61]
	v_mfma_f32_16x16x32_bf16 v[46:49], v[158:161], v[198:201], v[46:49]
	v_mfma_f32_16x16x32_bf16 v[42:45], v[166:169], v[198:201], v[42:45]
	v_mfma_f32_16x16x32_bf16 v[30:33], v[158:161], v[206:209], v[30:33]
	v_mfma_f32_16x16x32_bf16 v[26:29], v[166:169], v[206:209], v[26:29]
	v_mfma_f32_16x16x32_bf16 v[14:17], v[158:161], v[214:217], v[14:17]
	v_mfma_f32_16x16x32_bf16 v[10:13], v[166:169], v[214:217], v[10:13]
	v_mfma_f32_16x16x32_bf16 v[62:65], v[162:165], v[194:197], v[62:65]
	v_mfma_f32_16x16x32_bf16 v[58:61], v[170:173], v[194:197], v[58:61]
	v_mfma_f32_16x16x32_bf16 v[46:49], v[162:165], v[202:205], v[46:49]
	v_mfma_f32_16x16x32_bf16 v[42:45], v[170:173], v[202:205], v[42:45]
	v_mfma_f32_16x16x32_bf16 v[30:33], v[162:165], v[210:213], v[30:33]
	v_mfma_f32_16x16x32_bf16 v[26:29], v[170:173], v[210:213], v[26:29]
	v_mfma_f32_16x16x32_bf16 v[14:17], v[162:165], v[218:221], v[14:17]
	v_mfma_f32_16x16x32_bf16 v[10:13], v[170:173], v[218:221], v[10:13]
	s_setprio 0
	s_setprio 1
	v_mfma_f32_16x16x32_bf16 v[54:57], v[174:177], v[190:193], v[54:57]
	v_mfma_f32_16x16x32_bf16 v[50:53], v[182:185], v[190:193], v[50:53]
	v_mfma_f32_16x16x32_bf16 v[38:41], v[174:177], v[198:201], v[38:41]
	v_mfma_f32_16x16x32_bf16 v[34:37], v[182:185], v[198:201], v[34:37]
	v_mfma_f32_16x16x32_bf16 v[22:25], v[174:177], v[206:209], v[22:25]
	v_mfma_f32_16x16x32_bf16 v[18:21], v[182:185], v[206:209], v[18:21]
	v_mfma_f32_16x16x32_bf16 v[6:9], v[174:177], v[214:217], v[6:9]
	v_mfma_f32_16x16x32_bf16 v[2:5], v[182:185], v[214:217], v[2:5]
	v_mfma_f32_16x16x32_bf16 v[54:57], v[178:181], v[194:197], v[54:57]
	v_mfma_f32_16x16x32_bf16 v[50:53], v[186:189], v[194:197], v[50:53]
	v_mfma_f32_16x16x32_bf16 v[38:41], v[178:181], v[202:205], v[38:41]
	v_mfma_f32_16x16x32_bf16 v[34:37], v[186:189], v[202:205], v[34:37]
	v_mfma_f32_16x16x32_bf16 v[22:25], v[178:181], v[210:213], v[22:25]
	v_mfma_f32_16x16x32_bf16 v[18:21], v[186:189], v[210:213], v[18:21]
	v_mfma_f32_16x16x32_bf16 v[6:9], v[178:181], v[218:221], v[6:9]
	v_mfma_f32_16x16x32_bf16 v[2:5], v[186:189], v[218:221], v[2:5]
	s_setprio 0
	s_barrier
	s_add_i32 s76, s76, 2
	s_add_u32 s54, s54, 0x100
	s_addc_u32 s55, s55, 0
	s_add_u32 s74, s74, 0x100
	s_addc_u32 s75, s75, 0
	s_cmp_gt_u32 s76, 13
	s_cbranch_scc0 .LBB0_1357
	s_and_b64 vcc, exec, s[26:27]
	s_cbranch_vccz .LBB0_1360
	s_barrier

.LBB0_1396:
	ds_read_b128 v[2:5], v146
	ds_read_b128 v[6:9], v146 offset:1024
	ds_read_b128 v[10:13], v146 offset:2048
	ds_read_b128 v[14:17], v146 offset:3072
	ds_read_b128 v[18:21], v147
	ds_read_b128 v[22:25], v147 offset:1024
	ds_read_b128 v[26:29], v147 offset:2048
	ds_read_b128 v[30:33], v147 offset:3072
	s_ashr_i32 s45, s44, 31
	s_lshl_b64 s[48:49], s[44:45], 17
	s_add_u32 s48, s3, s48
	s_addc_u32 s49, s23, s49
	s_and_b64 s[50:51], s[52:53], exec
	s_cselect_b32 s63, s49, s57
	s_cselect_b32 s62, s48, s56
	s_ashr_i32 s47, s46, 31
	s_lshl_b64 s[50:51], s[46:47], 17
	s_add_u32 s50, s29, s50
	s_addc_u32 s51, s31, s51
	s_and_b64 s[60:61], s[52:53], exec
	s_cselect_b32 s61, s51, s59
	s_cselect_b32 s60, s50, s58
	s_add_u32 s84, s56, 0x10080
	s_addc_u32 s85, s57, 0
	s_mov_b32 m0, s73
	v_lshl_add_u64 v[66:67], s[84:85], 0, v[130:131]
	ds_read_b128 v[34:37], v148
	ds_read_b128 v[38:41], v148 offset:1024
	ds_read_b128 v[42:45], v148 offset:2048
	ds_read_b128 v[46:49], v148 offset:3072
	ds_read_b128 v[50:53], v148 offset:4096
	ds_read_b128 v[54:57], v148 offset:5120
	ds_read_b128 v[58:61], v148 offset:6144
	ds_read_b128 v[62:65], v148 offset:7168
	global_load_lds_dwordx4 v[66:67], off
	v_lshl_add_u64 v[66:67], s[84:85], 0, v[134:135]
	s_mov_b32 m0, s74
	s_nop 0
	global_load_lds_dwordx4 v[66:67], off
	s_waitcnt vmcnt(8)
	s_waitcnt lgkmcnt(0)
	s_setprio 1
	s_barrier
	v_mfma_f32_16x16x32_bf16 v[66:69], v[2:5], v[34:37], 0
	v_mfma_f32_16x16x32_bf16 v[70:73], v[10:13], v[34:37], 0
	v_mfma_f32_16x16x32_bf16 v[74:77], v[2:5], v[42:45], 0
	v_mfma_f32_16x16x32_bf16 v[78:81], v[10:13], v[42:45], 0
	s_waitcnt vmcnt(0)
	v_mfma_f32_16x16x32_bf16 v[82:85], v[2:5], v[50:53], 0
	v_mfma_f32_16x16x32_bf16 v[86:89], v[10:13], v[50:53], 0
	v_mfma_f32_16x16x32_bf16 v[90:93], v[2:5], v[58:61], 0
	v_mfma_f32_16x16x32_bf16 v[94:97], v[10:13], v[58:61], 0
	v_mfma_f32_16x16x32_bf16 v[66:69], v[6:9], v[38:41], v[66:69]
	v_mfma_f32_16x16x32_bf16 v[70:73], v[14:17], v[38:41], v[70:73]
	v_mfma_f32_16x16x32_bf16 v[74:77], v[6:9], v[46:49], v[74:77]
	v_mfma_f32_16x16x32_bf16 v[78:81], v[14:17], v[46:49], v[78:81]
	v_mfma_f32_16x16x32_bf16 v[82:85], v[6:9], v[54:57], v[82:85]
	v_mfma_f32_16x16x32_bf16 v[86:89], v[14:17], v[54:57], v[86:89]
	v_mfma_f32_16x16x32_bf16 v[90:93], v[6:9], v[62:65], v[90:93]
	v_mfma_f32_16x16x32_bf16 v[94:97], v[14:17], v[62:65], v[94:97]
	s_setprio 0
	s_setprio 1
	v_mfma_f32_16x16x32_bf16 v[98:101], v[18:21], v[34:37], 0
	v_mfma_f32_16x16x32_bf16 v[34:37], v[26:29], v[34:37], 0
	v_mfma_f32_16x16x32_bf16 v[98:101], v[22:25], v[38:41], v[98:101]
	v_mfma_f32_16x16x32_bf16 v[34:37], v[30:33], v[38:41], v[34:37]
	v_mfma_f32_16x16x32_bf16 v[38:41], v[18:21], v[42:45], 0
	v_mfma_f32_16x16x32_bf16 v[42:45], v[26:29], v[42:45], 0
	v_mfma_f32_16x16x32_bf16 v[38:41], v[22:25], v[46:49], v[38:41]
	v_mfma_f32_16x16x32_bf16 v[42:45], v[30:33], v[46:49], v[42:45]
	v_mfma_f32_16x16x32_bf16 v[46:49], v[18:21], v[50:53], 0
	v_mfma_f32_16x16x32_bf16 v[50:53], v[26:29], v[50:53], 0
	v_mfma_f32_16x16x32_bf16 v[46:49], v[22:25], v[54:57], v[46:49]
	v_mfma_f32_16x16x32_bf16 v[50:53], v[30:33], v[54:57], v[50:53]
	v_mfma_f32_16x16x32_bf16 v[54:57], v[18:21], v[58:61], 0
	v_mfma_f32_16x16x32_bf16 v[58:61], v[26:29], v[58:61], 0
	v_mfma_f32_16x16x32_bf16 v[54:57], v[22:25], v[62:65], v[54:57]
	v_mfma_f32_16x16x32_bf16 v[58:61], v[30:33], v[62:65], v[58:61]
	s_setprio 0
	s_barrier
	v_lshl_add_u64 v[140:141], s[58:59], 0, v[132:133]
	s_mov_b32 m0, s75
	v_lshl_add_u64 v[152:153], v[140:141], 0, s[26:27]
	v_lshl_add_u64 v[216:217], s[58:59], 0, v[136:137]
	s_add_u32 s84, s58, 0x10100
	ds_read_b128 v[62:65], v148 offset:16384
	ds_read_b128 v[102:105], v148 offset:17408
	ds_read_b128 v[106:109], v148 offset:18432
	ds_read_b128 v[110:113], v148 offset:19456
	ds_read_b128 v[114:117], v148 offset:20480
	ds_read_b128 v[118:121], v148 offset:21504
	ds_read_b128 v[122:125], v148 offset:22528
	ds_read_b128 v[126:129], v148 offset:23552
	global_load_lds_dwordx4 v[152:153], off
	v_lshl_add_u64 v[152:153], v[216:217], 0, s[26:27]
	s_mov_b32 m0, s76
	s_addc_u32 s85, s59, 0
	global_load_lds_dwordx4 v[152:153], off
	v_lshl_add_u64 v[152:153], s[84:85], 0, v[132:133]
	s_mov_b32 m0, s77
	v_lshl_add_u64 v[218:219], s[56:57], 0, v[130:131]
	global_load_lds_dwordx4 v[152:153], off
	v_lshl_add_u64 v[152:153], s[84:85], 0, v[136:137]
	s_mov_b32 m0, s78
	v_lshl_add_u64 v[220:221], s[56:57], 0, v[134:135]
	global_load_lds_dwordx4 v[152:153], off
	v_lshl_add_u64 v[152:153], v[218:219], 0, s[26:27]
	s_mov_b32 m0, s64
	s_nop 0
	global_load_lds_dwordx4 v[152:153], off
	v_lshl_add_u64 v[152:153], v[220:221], 0, s[26:27]
	s_mov_b32 m0, s65
	s_nop 0
	global_load_lds_dwordx4 v[152:153], off
	s_waitcnt vmcnt(8)
	s_waitcnt lgkmcnt(0)
	s_setprio 1
	s_barrier
	v_mfma_f32_16x16x32_bf16 v[152:155], v[2:5], v[62:65], 0
	v_mfma_f32_16x16x32_bf16 v[160:163], v[2:5], v[106:109], 0
	v_mfma_f32_16x16x32_bf16 v[168:171], v[2:5], v[114:117], 0
	v_mfma_f32_16x16x32_bf16 v[2:5], v[2:5], v[122:125], 0
	v_mfma_f32_16x16x32_bf16 v[152:155], v[6:9], v[102:105], v[152:155]
	v_mfma_f32_16x16x32_bf16 v[160:163], v[6:9], v[110:113], v[160:163]
	v_mfma_f32_16x16x32_bf16 v[168:171], v[6:9], v[118:121], v[168:171]
	v_mfma_f32_16x16x32_bf16 v[2:5], v[6:9], v[126:129], v[2:5]
	v_mfma_f32_16x16x32_bf16 v[6:9], v[10:13], v[122:125], 0
	v_mfma_f32_16x16x32_bf16 v[156:159], v[10:13], v[62:65], 0
	v_mfma_f32_16x16x32_bf16 v[164:167], v[10:13], v[106:109], 0
	v_mfma_f32_16x16x32_bf16 v[172:175], v[10:13], v[114:117], 0
	v_mfma_f32_16x16x32_bf16 v[6:9], v[14:17], v[126:129], v[6:9]
	v_mfma_f32_16x16x32_bf16 v[156:159], v[14:17], v[102:105], v[156:159]
	v_mfma_f32_16x16x32_bf16 v[164:167], v[14:17], v[110:113], v[164:167]
	v_mfma_f32_16x16x32_bf16 v[172:175], v[14:17], v[118:121], v[172:175]
	s_setprio 0
	s_setprio 1
	v_mfma_f32_16x16x32_bf16 v[10:13], v[18:21], v[62:65], 0
	v_mfma_f32_16x16x32_bf16 v[14:17], v[26:29], v[62:65], 0
	v_mfma_f32_16x16x32_bf16 v[10:13], v[22:25], v[102:105], v[10:13]
	v_mfma_f32_16x16x32_bf16 v[14:17], v[30:33], v[102:105], v[14:17]
	v_mfma_f32_16x16x32_bf16 v[62:65], v[18:21], v[106:109], 0
	v_mfma_f32_16x16x32_bf16 v[102:105], v[26:29], v[106:109], 0
	v_mfma_f32_16x16x32_bf16 v[106:109], v[18:21], v[114:117], 0
	v_mfma_f32_16x16x32_bf16 v[18:21], v[18:21], v[122:125], 0
	v_mfma_f32_16x16x32_bf16 v[62:65], v[22:25], v[110:113], v[62:65]
	v_mfma_f32_16x16x32_bf16 v[102:105], v[30:33], v[110:113], v[102:105]
	v_mfma_f32_16x16x32_bf16 v[106:109], v[22:25], v[118:121], v[106:109]
	v_mfma_f32_16x16x32_bf16 v[110:113], v[26:29], v[114:117], 0
	v_mfma_f32_16x16x32_bf16 v[18:21], v[22:25], v[126:129], v[18:21]
	v_mfma_f32_16x16x32_bf16 v[22:25], v[26:29], v[122:125], 0
	v_mfma_f32_16x16x32_bf16 v[110:113], v[30:33], v[118:121], v[110:113]
	v_mfma_f32_16x16x32_bf16 v[22:25], v[30:33], v[126:129], v[22:25]
	s_setprio 0
	s_barrier
	ds_read_b128 v[26:29], v150
	ds_read_b128 v[30:33], v150 offset:1024
	ds_read_b128 v[114:117], v150 offset:2048
	ds_read_b128 v[118:121], v150 offset:3072
	ds_read_b128 v[122:125], v151
	ds_read_b128 v[126:129], v151 offset:1024
	ds_read_b128 v[176:179], v151 offset:2048
	ds_read_b128 v[180:183], v151 offset:3072
	s_add_u32 s84, s56, 0x10100
	s_addc_u32 s85, s57, 0
	s_mov_b32 m0, s66
	v_lshl_add_u64 v[222:223], s[84:85], 0, v[130:131]
	ds_read_b128 v[184:187], v148 offset:32768
	ds_read_b128 v[188:191], v148 offset:33792
	ds_read_b128 v[192:195], v148 offset:34816
	ds_read_b128 v[196:199], v148 offset:35840
	ds_read_b128 v[200:203], v148 offset:36864
	ds_read_b128 v[204:207], v148 offset:37888
	ds_read_b128 v[208:211], v148 offset:38912
	ds_read_b128 v[212:215], v148 offset:39936
	global_load_lds_dwordx4 v[222:223], off
	v_lshl_add_u64 v[222:223], s[84:85], 0, v[134:135]
	s_mov_b32 m0, s67
	s_nop 0
	global_load_lds_dwordx4 v[222:223], off
	s_waitcnt vmcnt(8)
	s_waitcnt lgkmcnt(0)
	s_setprio 1
	s_barrier
	v_mfma_f32_16x16x32_bf16 v[66:69], v[26:29], v[184:187], v[66:69]
	v_mfma_f32_16x16x32_bf16 v[70:73], v[114:117], v[184:187], v[70:73]
	v_mfma_f32_16x16x32_bf16 v[74:77], v[26:29], v[192:195], v[74:77]
	v_mfma_f32_16x16x32_bf16 v[78:81], v[114:117], v[192:195], v[78:81]
	v_mfma_f32_16x16x32_bf16 v[82:85], v[26:29], v[200:203], v[82:85]
	v_mfma_f32_16x16x32_bf16 v[86:89], v[114:117], v[200:203], v[86:89]
	v_mfma_f32_16x16x32_bf16 v[90:93], v[26:29], v[208:211], v[90:93]
	v_mfma_f32_16x16x32_bf16 v[94:97], v[114:117], v[208:211], v[94:97]
	v_mfma_f32_16x16x32_bf16 v[66:69], v[30:33], v[188:191], v[66:69]
	v_mfma_f32_16x16x32_bf16 v[70:73], v[118:121], v[188:191], v[70:73]
	v_mfma_f32_16x16x32_bf16 v[74:77], v[30:33], v[196:199], v[74:77]
	v_mfma_f32_16x16x32_bf16 v[78:81], v[118:121], v[196:199], v[78:81]
	v_mfma_f32_16x16x32_bf16 v[82:85], v[30:33], v[204:207], v[82:85]
	v_mfma_f32_16x16x32_bf16 v[86:89], v[118:121], v[204:207], v[86:89]
	v_mfma_f32_16x16x32_bf16 v[90:93], v[30:33], v[212:215], v[90:93]
	v_mfma_f32_16x16x32_bf16 v[94:97], v[118:121], v[212:215], v[94:97]
	s_setprio 0
	s_setprio 1
	v_mfma_f32_16x16x32_bf16 v[98:101], v[122:125], v[184:187], v[98:101]
	v_mfma_f32_16x16x32_bf16 v[34:37], v[176:179], v[184:187], v[34:37]
	v_mfma_f32_16x16x32_bf16 v[38:41], v[122:125], v[192:195], v[38:41]
	v_mfma_f32_16x16x32_bf16 v[42:45], v[176:179], v[192:195], v[42:45]
	v_mfma_f32_16x16x32_bf16 v[46:49], v[122:125], v[200:203], v[46:49]
	v_mfma_f32_16x16x32_bf16 v[50:53], v[176:179], v[200:203], v[50:53]
	v_mfma_f32_16x16x32_bf16 v[54:57], v[122:125], v[208:211], v[54:57]
	v_mfma_f32_16x16x32_bf16 v[58:61], v[176:179], v[208:211], v[58:61]
	v_mfma_f32_16x16x32_bf16 v[98:101], v[126:129], v[188:191], v[98:101]
	v_mfma_f32_16x16x32_bf16 v[34:37], v[180:183], v[188:191], v[34:37]
	v_mfma_f32_16x16x32_bf16 v[38:41], v[126:129], v[196:199], v[38:41]
	v_mfma_f32_16x16x32_bf16 v[42:45], v[180:183], v[196:199], v[42:45]
	v_mfma_f32_16x16x32_bf16 v[46:49], v[126:129], v[204:207], v[46:49]
	v_mfma_f32_16x16x32_bf16 v[50:53], v[180:183], v[204:207], v[50:53]
	v_mfma_f32_16x16x32_bf16 v[54:57], v[126:129], v[212:215], v[54:57]
	v_mfma_f32_16x16x32_bf16 v[58:61], v[180:183], v[212:215], v[58:61]
	s_setprio 0
	s_barrier
	s_mov_b32 m0, s79
	v_lshl_add_u64 v[140:141], v[140:141], 0, s[42:43]
	s_add_u32 s58, s58, 0x10180
	ds_read_b128 v[184:187], v148 offset:49152
	ds_read_b128 v[188:191], v148 offset:50176
	ds_read_b128 v[192:195], v148 offset:51200
	ds_read_b128 v[196:199], v148 offset:52224
	ds_read_b128 v[200:203], v148 offset:53248
	ds_read_b128 v[204:207], v148 offset:54272
	ds_read_b128 v[208:211], v148 offset:55296
	ds_read_b128 v[212:215], v148 offset:56320
	global_load_lds_dwordx4 v[140:141], off
	v_lshl_add_u64 v[140:141], v[216:217], 0, s[42:43]
	s_mov_b32 m0, s80
	s_addc_u32 s59, s59, 0
	global_load_lds_dwordx4 v[140:141], off
	v_lshl_add_u64 v[140:141], s[58:59], 0, v[132:133]
	s_mov_b32 m0, s81
	s_nop 0
	global_load_lds_dwordx4 v[140:141], off
	v_lshl_add_u64 v[140:141], s[58:59], 0, v[136:137]
	s_mov_b32 m0, s82
	s_nop 0
	global_load_lds_dwordx4 v[140:141], off
	v_lshl_add_u64 v[140:141], v[218:219], 0, s[42:43]
	s_mov_b32 m0, s69
	s_nop 0
	global_load_lds_dwordx4 v[140:141], off
	v_lshl_add_u64 v[140:141], v[220:221], 0, s[42:43]
	s_mov_b32 m0, s70
	s_nop 0
	global_load_lds_dwordx4 v[140:141], off
	s_waitcnt vmcnt(8)
	s_waitcnt lgkmcnt(0)
	s_setprio 1
	s_barrier
	v_mfma_f32_16x16x32_bf16 v[2:5], v[26:29], v[208:211], v[2:5]
	v_mfma_f32_16x16x32_bf16 v[6:9], v[114:117], v[208:211], v[6:9]
	v_mfma_f32_16x16x32_bf16 v[152:155], v[26:29], v[184:187], v[152:155]
	v_mfma_f32_16x16x32_bf16 v[156:159], v[114:117], v[184:187], v[156:159]
	v_mfma_f32_16x16x32_bf16 v[160:163], v[26:29], v[192:195], v[160:163]
	v_mfma_f32_16x16x32_bf16 v[164:167], v[114:117], v[192:195], v[164:167]
	v_mfma_f32_16x16x32_bf16 v[168:171], v[26:29], v[200:203], v[168:171]
	v_mfma_f32_16x16x32_bf16 v[172:175], v[114:117], v[200:203], v[172:175]
	v_mfma_f32_16x16x32_bf16 v[2:5], v[30:33], v[212:215], v[2:5]
	v_mfma_f32_16x16x32_bf16 v[6:9], v[118:121], v[212:215], v[6:9]
	v_mfma_f32_16x16x32_bf16 v[152:155], v[30:33], v[188:191], v[152:155]
	v_mfma_f32_16x16x32_bf16 v[156:159], v[118:121], v[188:191], v[156:159]
	v_mfma_f32_16x16x32_bf16 v[160:163], v[30:33], v[196:199], v[160:163]
	v_mfma_f32_16x16x32_bf16 v[164:167], v[118:121], v[196:199], v[164:167]
	v_mfma_f32_16x16x32_bf16 v[168:171], v[30:33], v[204:207], v[168:171]
	v_mfma_f32_16x16x32_bf16 v[172:175], v[118:121], v[204:207], v[172:175]
	s_setprio 0
	s_setprio 1
	v_mfma_f32_16x16x32_bf16 v[10:13], v[122:125], v[184:187], v[10:13]
	v_mfma_f32_16x16x32_bf16 v[14:17], v[176:179], v[184:187], v[14:17]
	v_mfma_f32_16x16x32_bf16 v[26:29], v[122:125], v[192:195], v[62:65]
	v_mfma_f32_16x16x32_bf16 v[30:33], v[176:179], v[192:195], v[102:105]
	v_mfma_f32_16x16x32_bf16 v[62:65], v[122:125], v[200:203], v[106:109]
	v_mfma_f32_16x16x32_bf16 v[102:105], v[176:179], v[200:203], v[110:113]
	v_mfma_f32_16x16x32_bf16 v[18:21], v[122:125], v[208:211], v[18:21]
	v_mfma_f32_16x16x32_bf16 v[22:25], v[176:179], v[208:211], v[22:25]
	v_mfma_f32_16x16x32_bf16 v[10:13], v[126:129], v[188:191], v[10:13]
	v_mfma_f32_16x16x32_bf16 v[14:17], v[180:183], v[188:191], v[14:17]
	v_mfma_f32_16x16x32_bf16 v[26:29], v[126:129], v[196:199], v[26:29]
	v_mfma_f32_16x16x32_bf16 v[30:33], v[180:183], v[196:199], v[30:33]
	v_mfma_f32_16x16x32_bf16 v[62:65], v[126:129], v[204:207], v[62:65]
	v_mfma_f32_16x16x32_bf16 v[102:105], v[180:183], v[204:207], v[102:105]
	v_mfma_f32_16x16x32_bf16 v[18:21], v[126:129], v[212:215], v[18:21]
	v_mfma_f32_16x16x32_bf16 v[22:25], v[180:183], v[212:215], v[22:25]
	s_setprio 0
	s_barrier
	ds_read_b128 v[106:109], v146
	ds_read_b128 v[110:113], v146 offset:1024
	ds_read_b128 v[114:117], v146 offset:2048
	ds_read_b128 v[118:121], v146 offset:3072
	ds_read_b128 v[122:125], v147
	ds_read_b128 v[126:129], v147 offset:1024
	ds_read_b128 v[176:179], v147 offset:2048
	ds_read_b128 v[180:183], v147 offset:3072
	s_add_u32 s56, s56, 0x10180
	s_addc_u32 s57, s57, 0
	s_mov_b32 m0, s73
	v_lshl_add_u64 v[140:141], s[56:57], 0, v[130:131]
	ds_read_b128 v[184:187], v148
	ds_read_b128 v[188:191], v148 offset:1024
	ds_read_b128 v[192:195], v148 offset:2048
	ds_read_b128 v[196:199], v148 offset:3072
	ds_read_b128 v[200:203], v148 offset:4096
	ds_read_b128 v[204:207], v148 offset:5120
	ds_read_b128 v[208:211], v148 offset:6144
	ds_read_b128 v[212:215], v148 offset:7168
	global_load_lds_dwordx4 v[140:141], off
	v_lshl_add_u64 v[140:141], s[56:57], 0, v[134:135]
	s_mov_b32 m0, s74
	s_nop 0
	global_load_lds_dwordx4 v[140:141], off
	s_waitcnt vmcnt(8)
	s_waitcnt lgkmcnt(0)
	s_setprio 1
	s_barrier
	v_mfma_f32_16x16x32_bf16 v[66:69], v[106:109], v[184:187], v[66:69]
	v_mfma_f32_16x16x32_bf16 v[70:73], v[114:117], v[184:187], v[70:73]
	v_mfma_f32_16x16x32_bf16 v[74:77], v[106:109], v[192:195], v[74:77]
	v_mfma_f32_16x16x32_bf16 v[78:81], v[114:117], v[192:195], v[78:81]
	v_mfma_f32_16x16x32_bf16 v[82:85], v[106:109], v[200:203], v[82:85]
	v_mfma_f32_16x16x32_bf16 v[86:89], v[114:117], v[200:203], v[86:89]
	v_mfma_f32_16x16x32_bf16 v[90:93], v[106:109], v[208:211], v[90:93]
	v_mfma_f32_16x16x32_bf16 v[94:97], v[114:117], v[208:211], v[94:97]
	v_mfma_f32_16x16x32_bf16 v[66:69], v[110:113], v[188:191], v[66:69]
	v_mfma_f32_16x16x32_bf16 v[70:73], v[118:121], v[188:191], v[70:73]
	v_mfma_f32_16x16x32_bf16 v[74:77], v[110:113], v[196:199], v[74:77]
	v_mfma_f32_16x16x32_bf16 v[78:81], v[118:121], v[196:199], v[78:81]
	v_mfma_f32_16x16x32_bf16 v[82:85], v[110:113], v[204:207], v[82:85]
	v_mfma_f32_16x16x32_bf16 v[86:89], v[118:121], v[204:207], v[86:89]
	v_mfma_f32_16x16x32_bf16 v[90:93], v[110:113], v[212:215], v[90:93]
	v_mfma_f32_16x16x32_bf16 v[94:97], v[118:121], v[212:215], v[94:97]
	s_setprio 0
	s_setprio 1
	v_mfma_f32_16x16x32_bf16 v[34:37], v[176:179], v[184:187], v[34:37]
	v_mfma_f32_16x16x32_bf16 v[38:41], v[122:125], v[192:195], v[38:41]
	v_mfma_f32_16x16x32_bf16 v[42:45], v[176:179], v[192:195], v[42:45]
	v_mfma_f32_16x16x32_bf16 v[46:49], v[122:125], v[200:203], v[46:49]
	v_mfma_f32_16x16x32_bf16 v[50:53], v[176:179], v[200:203], v[50:53]
	v_mfma_f32_16x16x32_bf16 v[54:57], v[122:125], v[208:211], v[54:57]
	v_mfma_f32_16x16x32_bf16 v[58:61], v[176:179], v[208:211], v[58:61]
	v_mfma_f32_16x16x32_bf16 v[98:101], v[122:125], v[184:187], v[98:101]
	v_mfma_f32_16x16x32_bf16 v[34:37], v[180:183], v[188:191], v[34:37]
	v_mfma_f32_16x16x32_bf16 v[38:41], v[126:129], v[196:199], v[38:41]
	v_mfma_f32_16x16x32_bf16 v[42:45], v[180:183], v[196:199], v[42:45]
	v_mfma_f32_16x16x32_bf16 v[46:49], v[126:129], v[204:207], v[46:49]
	v_mfma_f32_16x16x32_bf16 v[50:53], v[180:183], v[204:207], v[50:53]
	v_mfma_f32_16x16x32_bf16 v[54:57], v[126:129], v[212:215], v[54:57]
	v_mfma_f32_16x16x32_bf16 v[58:61], v[180:183], v[212:215], v[58:61]
	v_mfma_f32_16x16x32_bf16 v[216:219], v[126:129], v[188:191], v[98:101]
	s_setprio 0
	s_barrier
	s_mov_b32 m0, s75
	v_lshl_add_u64 v[140:141], s[60:61], 0, v[132:133]
	s_add_u32 s56, s60, 0x10000
	ds_read_b128 v[98:101], v148 offset:16384
	ds_read_b128 v[184:187], v148 offset:17408
	ds_read_b128 v[188:191], v148 offset:18432
	ds_read_b128 v[192:195], v148 offset:19456
	ds_read_b128 v[196:199], v148 offset:20480
	ds_read_b128 v[200:203], v148 offset:21504
	ds_read_b128 v[204:207], v148 offset:22528
	ds_read_b128 v[208:211], v148 offset:23552
	global_load_lds_dwordx4 v[140:141], off
	v_lshl_add_u64 v[240:241], s[60:61], 0, v[136:137]
	s_mov_b32 m0, s76
	s_addc_u32 s57, s61, 0
	global_load_lds_dwordx4 v[240:241], off
	v_lshl_add_u64 v[212:213], s[56:57], 0, v[132:133]
	s_mov_b32 m0, s77
	v_lshl_add_u64 v[248:249], s[62:63], 0, v[130:131]
	global_load_lds_dwordx4 v[212:213], off
	v_lshl_add_u64 v[212:213], s[56:57], 0, v[136:137]
	s_mov_b32 m0, s78
	v_lshl_add_u64 v[250:251], s[62:63], 0, v[134:135]
	global_load_lds_dwordx4 v[212:213], off
	s_mov_b32 m0, s64
	s_nop 0
	global_load_lds_dwordx4 v[248:249], off
	s_mov_b32 m0, s65
	s_nop 0
	global_load_lds_dwordx4 v[250:251], off
	s_waitcnt vmcnt(8)
	s_waitcnt lgkmcnt(0)
	s_setprio 1
	s_barrier
	v_mfma_f32_16x16x32_bf16 v[2:5], v[106:109], v[204:207], v[2:5]
	v_mfma_f32_16x16x32_bf16 v[6:9], v[114:117], v[204:207], v[6:9]
	v_mfma_f32_16x16x32_bf16 v[152:155], v[106:109], v[98:101], v[152:155]
	v_mfma_f32_16x16x32_bf16 v[156:159], v[114:117], v[98:101], v[156:159]
	v_mfma_f32_16x16x32_bf16 v[160:163], v[106:109], v[188:191], v[160:163]
	v_mfma_f32_16x16x32_bf16 v[164:167], v[114:117], v[188:191], v[164:167]
	v_mfma_f32_16x16x32_bf16 v[168:171], v[106:109], v[196:199], v[168:171]
	v_mfma_f32_16x16x32_bf16 v[172:175], v[114:117], v[196:199], v[172:175]
	v_mfma_f32_16x16x32_bf16 v[2:5], v[110:113], v[208:211], v[2:5]
	v_mfma_f32_16x16x32_bf16 v[6:9], v[118:121], v[208:211], v[6:9]
	v_mfma_f32_16x16x32_bf16 v[152:155], v[110:113], v[184:187], v[152:155]
	v_mfma_f32_16x16x32_bf16 v[156:159], v[118:121], v[184:187], v[156:159]
	v_mfma_f32_16x16x32_bf16 v[160:163], v[110:113], v[192:195], v[160:163]
	v_mfma_f32_16x16x32_bf16 v[164:167], v[118:121], v[192:195], v[164:167]
	v_mfma_f32_16x16x32_bf16 v[168:171], v[110:113], v[200:203], v[168:171]
	v_mfma_f32_16x16x32_bf16 v[172:175], v[118:121], v[200:203], v[172:175]
	s_setprio 0
	s_setprio 1
	v_mfma_f32_16x16x32_bf16 v[10:13], v[122:125], v[98:101], v[10:13]
	v_mfma_f32_16x16x32_bf16 v[14:17], v[176:179], v[98:101], v[14:17]
	v_mfma_f32_16x16x32_bf16 v[26:29], v[122:125], v[188:191], v[26:29]
	v_mfma_f32_16x16x32_bf16 v[30:33], v[176:179], v[188:191], v[30:33]
	v_mfma_f32_16x16x32_bf16 v[62:65], v[122:125], v[196:199], v[62:65]
	v_mfma_f32_16x16x32_bf16 v[18:21], v[122:125], v[204:207], v[18:21]
	v_mfma_f32_16x16x32_bf16 v[10:13], v[126:129], v[184:187], v[10:13]
	v_mfma_f32_16x16x32_bf16 v[14:17], v[180:183], v[184:187], v[14:17]
	v_mfma_f32_16x16x32_bf16 v[26:29], v[126:129], v[192:195], v[26:29]
	v_mfma_f32_16x16x32_bf16 v[30:33], v[180:183], v[192:195], v[30:33]
	v_mfma_f32_16x16x32_bf16 v[184:187], v[126:129], v[200:203], v[62:65]
	v_mfma_f32_16x16x32_bf16 v[62:65], v[176:179], v[196:199], v[102:105]
	v_mfma_f32_16x16x32_bf16 v[192:195], v[126:129], v[208:211], v[18:21]
	v_mfma_f32_16x16x32_bf16 v[18:21], v[176:179], v[204:207], v[22:25]
	v_mfma_f32_16x16x32_bf16 v[188:191], v[180:183], v[200:203], v[62:65]
	v_mfma_f32_16x16x32_bf16 v[176:179], v[180:183], v[208:211], v[18:21]
	s_setprio 0
	s_barrier
	s_nop 1
	ds_read_b128 v[62:65], v150
	ds_read_b128 v[180:183], v150 offset:1024
	ds_read_b128 v[196:199], v150 offset:2048
	ds_read_b128 v[200:203], v150 offset:3072
	ds_read_b128 v[204:207], v151
	ds_read_b128 v[208:211], v151 offset:1024
	ds_read_b128 v[212:215], v151 offset:2048
	ds_read_b128 v[220:223], v151 offset:3072
	s_add_u32 s56, s62, 0x10000
	s_addc_u32 s57, s63, 0
	s_mov_b32 m0, s66
	v_lshl_add_u64 v[98:99], s[56:57], 0, v[130:131]
	ds_read_b128 v[18:21], v148 offset:32768
	ds_read_b128 v[22:25], v148 offset:33792
	ds_read_b128 v[110:113], v148 offset:34816
	ds_read_b128 v[224:227], v148 offset:35840
	ds_read_b128 v[228:231], v148 offset:36864
	ds_read_b128 v[232:235], v148 offset:37888
	ds_read_b128 v[236:239], v148 offset:38912
	ds_read_b128 v[244:247], v148 offset:39936
	global_load_lds_dwordx4 v[98:99], off
	v_lshl_add_u64 v[98:99], s[56:57], 0, v[134:135]
	s_mov_b32 m0, s67
	s_nop 0
	global_load_lds_dwordx4 v[98:99], off
	s_waitcnt vmcnt(8)
	s_waitcnt lgkmcnt(0)
	s_setprio 1
	s_barrier
	v_mfma_f32_16x16x32_bf16 v[66:69], v[62:65], v[18:21], v[66:69]
	v_mfma_f32_16x16x32_bf16 v[114:117], v[180:183], v[22:25], v[66:69]
	v_mfma_f32_16x16x32_bf16 v[66:69], v[196:199], v[18:21], v[70:73]
	v_mfma_f32_16x16x32_bf16 v[118:121], v[200:203], v[22:25], v[66:69]
	v_mfma_f32_16x16x32_bf16 v[66:69], v[62:65], v[110:113], v[74:77]
	v_mfma_f32_16x16x32_bf16 v[98:101], v[180:183], v[224:227], v[66:69]
	v_mfma_f32_16x16x32_bf16 v[66:69], v[196:199], v[110:113], v[78:81]
	v_mfma_f32_16x16x32_bf16 v[102:105], v[200:203], v[224:227], v[66:69]
	v_mfma_f32_16x16x32_bf16 v[66:69], v[62:65], v[228:231], v[82:85]
	v_mfma_f32_16x16x32_bf16 v[82:85], v[180:183], v[232:235], v[66:69]
	v_mfma_f32_16x16x32_bf16 v[66:69], v[196:199], v[228:231], v[86:89]
	v_mfma_f32_16x16x32_bf16 v[86:89], v[200:203], v[232:235], v[66:69]
	v_mfma_f32_16x16x32_bf16 v[66:69], v[62:65], v[236:239], v[90:93]
	v_mfma_f32_16x16x32_bf16 v[70:73], v[196:199], v[236:239], v[94:97]
	v_mfma_f32_16x16x32_bf16 v[66:69], v[180:183], v[244:247], v[66:69]
	v_mfma_f32_16x16x32_bf16 v[70:73], v[200:203], v[244:247], v[70:73]
	s_setprio 0
	s_setprio 1
	v_mfma_f32_16x16x32_bf16 v[74:77], v[204:207], v[18:21], v[216:219]
	v_mfma_f32_16x16x32_bf16 v[18:21], v[212:215], v[18:21], v[34:37]
	v_mfma_f32_16x16x32_bf16 v[126:129], v[220:223], v[22:25], v[18:21]
	v_mfma_f32_16x16x32_bf16 v[18:21], v[204:207], v[110:113], v[38:41]
	v_mfma_f32_16x16x32_bf16 v[106:109], v[208:211], v[224:227], v[18:21]
	v_mfma_f32_16x16x32_bf16 v[18:21], v[212:215], v[110:113], v[42:45]
	v_mfma_f32_16x16x32_bf16 v[110:113], v[220:223], v[224:227], v[18:21]
	v_mfma_f32_16x16x32_bf16 v[18:21], v[204:207], v[228:231], v[46:49]
	v_mfma_f32_16x16x32_bf16 v[90:93], v[208:211], v[232:235], v[18:21]
	v_mfma_f32_16x16x32_bf16 v[18:21], v[212:215], v[228:231], v[50:53]
	v_mfma_f32_16x16x32_bf16 v[94:97], v[220:223], v[232:235], v[18:21]
	v_mfma_f32_16x16x32_bf16 v[18:21], v[204:207], v[236:239], v[54:57]
	v_mfma_f32_16x16x32_bf16 v[122:125], v[208:211], v[22:25], v[74:77]
	v_mfma_f32_16x16x32_bf16 v[74:77], v[208:211], v[244:247], v[18:21]
	v_mfma_f32_16x16x32_bf16 v[18:21], v[212:215], v[236:239], v[58:61]
	v_mfma_f32_16x16x32_bf16 v[78:81], v[220:223], v[244:247], v[18:21]
	s_setprio 0
	s_barrier
	s_mov_b32 m0, s79
	s_nop 3
	v_lshl_add_u64 v[18:19], v[140:141], 0, s[16:17]
	s_add_u32 s56, s60, 0x10080
	ds_read_b128 v[42:45], v148 offset:49152
	ds_read_b128 v[46:49], v148 offset:50176
	ds_read_b128 v[216:219], v148 offset:51200
	ds_read_b128 v[224:227], v148 offset:52224
	ds_read_b128 v[228:231], v148 offset:53248
	ds_read_b128 v[232:235], v148 offset:54272
	ds_read_b128 v[236:239], v148 offset:55296
	ds_read_b128 v[244:247], v148 offset:56320
	global_load_lds_dwordx4 v[18:19], off
	v_lshl_add_u64 v[18:19], v[240:241], 0, s[16:17]
	s_mov_b32 m0, s80
	s_addc_u32 s57, s61, 0
	global_load_lds_dwordx4 v[18:19], off
	v_lshl_add_u64 v[18:19], s[56:57], 0, v[132:133]
	s_mov_b32 m0, s81
	s_nop 0
	global_load_lds_dwordx4 v[18:19], off
	v_lshl_add_u64 v[18:19], s[56:57], 0, v[136:137]
	s_mov_b32 m0, s82
	s_nop 0
	global_load_lds_dwordx4 v[18:19], off
	v_lshl_add_u64 v[18:19], v[248:249], 0, s[16:17]
	s_mov_b32 m0, s69
	s_nop 0
	global_load_lds_dwordx4 v[18:19], off
	v_lshl_add_u64 v[18:19], v[250:251], 0, s[16:17]
	s_mov_b32 m0, s70
	s_nop 0
	global_load_lds_dwordx4 v[18:19], off
	s_waitcnt vmcnt(8)
	s_waitcnt lgkmcnt(0)
	s_setprio 1
	s_barrier
	v_mfma_f32_16x16x32_bf16 v[18:21], v[62:65], v[42:45], v[152:155]
	v_mfma_f32_16x16x32_bf16 v[50:53], v[180:183], v[46:49], v[18:21]
	v_mfma_f32_16x16x32_bf16 v[18:21], v[196:199], v[42:45], v[156:159]
	v_mfma_f32_16x16x32_bf16 v[54:57], v[200:203], v[46:49], v[18:21]
	v_mfma_f32_16x16x32_bf16 v[18:21], v[62:65], v[216:219], v[160:163]
	v_mfma_f32_16x16x32_bf16 v[34:37], v[180:183], v[224:227], v[18:21]
	v_mfma_f32_16x16x32_bf16 v[18:21], v[196:199], v[216:219], v[164:167]
	v_mfma_f32_16x16x32_bf16 v[38:41], v[200:203], v[224:227], v[18:21]
	v_mfma_f32_16x16x32_bf16 v[18:21], v[62:65], v[228:231], v[168:171]
	v_mfma_f32_16x16x32_bf16 v[22:25], v[196:199], v[228:231], v[172:175]
	v_mfma_f32_16x16x32_bf16 v[2:5], v[62:65], v[236:239], v[2:5]
	v_mfma_f32_16x16x32_bf16 v[6:9], v[196:199], v[236:239], v[6:9]
	v_mfma_f32_16x16x32_bf16 v[18:21], v[180:183], v[232:235], v[18:21]
	v_mfma_f32_16x16x32_bf16 v[22:25], v[200:203], v[232:235], v[22:25]
	v_mfma_f32_16x16x32_bf16 v[2:5], v[180:183], v[244:247], v[2:5]
	v_mfma_f32_16x16x32_bf16 v[6:9], v[200:203], v[244:247], v[6:9]
	s_setprio 0
	s_setprio 1
	v_mfma_f32_16x16x32_bf16 v[10:13], v[204:207], v[42:45], v[10:13]
	v_mfma_f32_16x16x32_bf16 v[58:61], v[208:211], v[46:49], v[10:13]
	v_mfma_f32_16x16x32_bf16 v[10:13], v[212:215], v[42:45], v[14:17]
	v_mfma_f32_16x16x32_bf16 v[62:65], v[220:223], v[46:49], v[10:13]
	v_mfma_f32_16x16x32_bf16 v[10:13], v[204:207], v[216:219], v[26:29]
	v_mfma_f32_16x16x32_bf16 v[42:45], v[208:211], v[224:227], v[10:13]
	v_mfma_f32_16x16x32_bf16 v[10:13], v[212:215], v[216:219], v[30:33]
	v_mfma_f32_16x16x32_bf16 v[46:49], v[220:223], v[224:227], v[10:13]
	v_mfma_f32_16x16x32_bf16 v[10:13], v[204:207], v[228:231], v[184:187]
	v_mfma_f32_16x16x32_bf16 v[26:29], v[208:211], v[232:235], v[10:13]
	v_mfma_f32_16x16x32_bf16 v[10:13], v[212:215], v[228:231], v[188:191]
	v_mfma_f32_16x16x32_bf16 v[30:33], v[220:223], v[232:235], v[10:13]
	v_mfma_f32_16x16x32_bf16 v[10:13], v[204:207], v[236:239], v[192:195]
	v_mfma_f32_16x16x32_bf16 v[14:17], v[212:215], v[236:239], v[176:179]
	v_mfma_f32_16x16x32_bf16 v[10:13], v[208:211], v[244:247], v[10:13]
	v_mfma_f32_16x16x32_bf16 v[14:17], v[220:223], v[244:247], v[14:17]
	s_setprio 0
	s_barrier
	s_andn2_b64 vcc, exec, s[24:25]
	s_cbranch_vccnz .LBB0_1398
	s_barrier

.LBB0_1486:
	ds_read_b128 v[152:155], v157
	ds_read_b128 v[162:165], v157 offset:1024
	ds_read_b128 v[166:169], v157 offset:2048
	ds_read_b128 v[170:173], v157 offset:3072
	ds_read_b128 v[174:177], v158
	ds_read_b128 v[178:181], v158 offset:1024
	ds_read_b128 v[182:185], v158 offset:2048
	ds_read_b128 v[186:189], v158 offset:3072
	s_add_u32 s6, s50, 0x100
	s_addc_u32 s7, s51, 0
	s_cmp_eq_u32 s80, 8
	s_cselect_b32 s55, s47, s7
	s_cselect_b32 s54, s46, s6
	s_cselect_b32 s53, s49, s79
	s_cselect_b32 s52, s48, s10
	v_lshl_add_u64 v[222:223], s[50:51], 0, v[144:145]
	s_add_i32 m0, s57, 0xc000
	ds_read_b128 v[190:193], v159
	ds_read_b128 v[194:197], v159 offset:1024
	ds_read_b128 v[198:201], v159 offset:2048
	ds_read_b128 v[202:205], v159 offset:3072
	ds_read_b128 v[206:209], v159 offset:4096
	ds_read_b128 v[210:213], v159 offset:5120
	ds_read_b128 v[214:217], v159 offset:6144
	ds_read_b128 v[218:221], v159 offset:7168
	global_load_lds_dwordx4 v[222:223], off
	v_lshl_add_u64 v[222:223], s[50:51], 0, v[146:147]
	s_add_i32 m0, s57, 0xe000
	s_nop 0
	global_load_lds_dwordx4 v[222:223], off
	s_waitcnt vmcnt(8)
	s_waitcnt lgkmcnt(0)
	s_setprio 1
	s_barrier
	v_mfma_f32_16x16x32_bf16 v[126:129], v[152:155], v[190:193], v[126:129]
	v_mfma_f32_16x16x32_bf16 v[122:125], v[166:169], v[190:193], v[122:125]
	v_mfma_f32_16x16x32_bf16 v[110:113], v[152:155], v[198:201], v[110:113]
	v_mfma_f32_16x16x32_bf16 v[106:109], v[166:169], v[198:201], v[106:109]
	v_mfma_f32_16x16x32_bf16 v[94:97], v[152:155], v[206:209], v[94:97]
	v_mfma_f32_16x16x32_bf16 v[90:93], v[166:169], v[206:209], v[90:93]
	v_mfma_f32_16x16x32_bf16 v[78:81], v[152:155], v[214:217], v[78:81]
	v_mfma_f32_16x16x32_bf16 v[74:77], v[166:169], v[214:217], v[74:77]
	v_mfma_f32_16x16x32_bf16 v[126:129], v[162:165], v[194:197], v[126:129]
	v_mfma_f32_16x16x32_bf16 v[122:125], v[170:173], v[194:197], v[122:125]
	v_mfma_f32_16x16x32_bf16 v[110:113], v[162:165], v[202:205], v[110:113]
	v_mfma_f32_16x16x32_bf16 v[106:109], v[170:173], v[202:205], v[106:109]
	v_mfma_f32_16x16x32_bf16 v[94:97], v[162:165], v[210:213], v[94:97]
	v_mfma_f32_16x16x32_bf16 v[90:93], v[170:173], v[210:213], v[90:93]
	v_mfma_f32_16x16x32_bf16 v[78:81], v[162:165], v[218:221], v[78:81]
	v_mfma_f32_16x16x32_bf16 v[74:77], v[170:173], v[218:221], v[74:77]
	s_setprio 0
	s_setprio 1
	v_mfma_f32_16x16x32_bf16 v[118:121], v[174:177], v[190:193], v[118:121]
	v_mfma_f32_16x16x32_bf16 v[114:117], v[182:185], v[190:193], v[114:117]
	v_mfma_f32_16x16x32_bf16 v[102:105], v[174:177], v[198:201], v[102:105]
	v_mfma_f32_16x16x32_bf16 v[98:101], v[182:185], v[198:201], v[98:101]
	v_mfma_f32_16x16x32_bf16 v[86:89], v[174:177], v[206:209], v[86:89]
	v_mfma_f32_16x16x32_bf16 v[82:85], v[182:185], v[206:209], v[82:85]
	v_mfma_f32_16x16x32_bf16 v[70:73], v[174:177], v[214:217], v[70:73]
	v_mfma_f32_16x16x32_bf16 v[66:69], v[182:185], v[214:217], v[66:69]
	v_mfma_f32_16x16x32_bf16 v[118:121], v[178:181], v[194:197], v[118:121]
	v_mfma_f32_16x16x32_bf16 v[114:117], v[186:189], v[194:197], v[114:117]
	v_mfma_f32_16x16x32_bf16 v[102:105], v[178:181], v[202:205], v[102:105]
	v_mfma_f32_16x16x32_bf16 v[98:101], v[186:189], v[202:205], v[98:101]
	v_mfma_f32_16x16x32_bf16 v[86:89], v[178:181], v[210:213], v[86:89]
	v_mfma_f32_16x16x32_bf16 v[82:85], v[186:189], v[210:213], v[82:85]
	v_mfma_f32_16x16x32_bf16 v[70:73], v[178:181], v[218:221], v[70:73]
	v_mfma_f32_16x16x32_bf16 v[66:69], v[186:189], v[218:221], v[66:69]
	s_setprio 0
	s_barrier
	s_add_i32 s50, s68, s56
	v_lshl_add_u64 v[222:223], s[52:53], 0, v[132:133]
	s_mov_b32 m0, s50
	ds_read_b128 v[190:193], v159 offset:16384
	ds_read_b128 v[194:197], v159 offset:17408
	ds_read_b128 v[198:201], v159 offset:18432
	ds_read_b128 v[202:205], v159 offset:19456
	ds_read_b128 v[206:209], v159 offset:20480
	ds_read_b128 v[210:213], v159 offset:21504
	ds_read_b128 v[214:217], v159 offset:22528
	ds_read_b128 v[218:221], v159 offset:23552
	global_load_lds_dwordx4 v[222:223], off
	s_add_i32 m0, s50, 0x2000
	s_add_u32 s50, s52, 0x30000
	v_lshl_add_u64 v[224:225], s[52:53], 0, v[136:137]
	s_addc_u32 s51, s53, 0
	s_add_i32 s81, s69, s56
	global_load_lds_dwordx4 v[224:225], off
	v_lshl_add_u64 v[226:227], s[50:51], 0, v[132:133]
	s_mov_b32 m0, s81
	v_lshl_add_u64 v[228:229], s[54:55], 0, v[134:135]
	global_load_lds_dwordx4 v[226:227], off
	v_lshl_add_u64 v[226:227], s[50:51], 0, v[136:137]
	s_add_i32 m0, s81, 0x2000
	s_nop 0
	global_load_lds_dwordx4 v[226:227], off
	v_lshl_add_u64 v[226:227], s[54:55], 0, v[130:131]
	s_mov_b32 m0, s57
	s_nop 0
	global_load_lds_dwordx4 v[226:227], off
	s_mov_b32 m0, s58
	s_nop 0
	global_load_lds_dwordx4 v[228:229], off
	s_waitcnt vmcnt(8)
	s_waitcnt lgkmcnt(0)
	s_setprio 1
	s_barrier
	v_mfma_f32_16x16x32_bf16 v[62:65], v[152:155], v[190:193], v[62:65]
	v_mfma_f32_16x16x32_bf16 v[58:61], v[166:169], v[190:193], v[58:61]
	v_mfma_f32_16x16x32_bf16 v[46:49], v[152:155], v[198:201], v[46:49]
	v_mfma_f32_16x16x32_bf16 v[42:45], v[166:169], v[198:201], v[42:45]
	v_mfma_f32_16x16x32_bf16 v[30:33], v[152:155], v[206:209], v[30:33]
	v_mfma_f32_16x16x32_bf16 v[26:29], v[166:169], v[206:209], v[26:29]
	v_mfma_f32_16x16x32_bf16 v[14:17], v[152:155], v[214:217], v[14:17]
	v_mfma_f32_16x16x32_bf16 v[10:13], v[166:169], v[214:217], v[10:13]
	v_mfma_f32_16x16x32_bf16 v[62:65], v[162:165], v[194:197], v[62:65]
	v_mfma_f32_16x16x32_bf16 v[58:61], v[170:173], v[194:197], v[58:61]
	v_mfma_f32_16x16x32_bf16 v[46:49], v[162:165], v[202:205], v[46:49]
	v_mfma_f32_16x16x32_bf16 v[42:45], v[170:173], v[202:205], v[42:45]
	v_mfma_f32_16x16x32_bf16 v[30:33], v[162:165], v[210:213], v[30:33]
	v_mfma_f32_16x16x32_bf16 v[26:29], v[170:173], v[210:213], v[26:29]
	v_mfma_f32_16x16x32_bf16 v[14:17], v[162:165], v[218:221], v[14:17]
	v_mfma_f32_16x16x32_bf16 v[10:13], v[170:173], v[218:221], v[10:13]
	s_setprio 0
	s_setprio 1
	v_mfma_f32_16x16x32_bf16 v[54:57], v[174:177], v[190:193], v[54:57]
	v_mfma_f32_16x16x32_bf16 v[50:53], v[182:185], v[190:193], v[50:53]
	v_mfma_f32_16x16x32_bf16 v[38:41], v[174:177], v[198:201], v[38:41]
	v_mfma_f32_16x16x32_bf16 v[34:37], v[182:185], v[198:201], v[34:37]
	v_mfma_f32_16x16x32_bf16 v[22:25], v[174:177], v[206:209], v[22:25]
	v_mfma_f32_16x16x32_bf16 v[18:21], v[182:185], v[206:209], v[18:21]
	v_mfma_f32_16x16x32_bf16 v[6:9], v[174:177], v[214:217], v[6:9]
	v_mfma_f32_16x16x32_bf16 v[2:5], v[182:185], v[214:217], v[2:5]
	v_mfma_f32_16x16x32_bf16 v[54:57], v[178:181], v[194:197], v[54:57]
	v_mfma_f32_16x16x32_bf16 v[50:53], v[186:189], v[194:197], v[50:53]
	v_mfma_f32_16x16x32_bf16 v[38:41], v[178:181], v[202:205], v[38:41]
	v_mfma_f32_16x16x32_bf16 v[34:37], v[186:189], v[202:205], v[34:37]
	v_mfma_f32_16x16x32_bf16 v[22:25], v[178:181], v[210:213], v[22:25]
	v_mfma_f32_16x16x32_bf16 v[18:21], v[186:189], v[210:213], v[18:21]
	v_mfma_f32_16x16x32_bf16 v[6:9], v[178:181], v[218:221], v[6:9]
	v_mfma_f32_16x16x32_bf16 v[2:5], v[186:189], v[218:221], v[2:5]
	s_setprio 0
	s_barrier
	s_add_i32 s81, 0, 0x18000
	v_add_u32_e32 v138, s81, v143
	s_add_i32 s82, 0, 0x1c000
	ds_read_b128 v[152:155], v138
	ds_read_b128 v[162:165], v138 offset:1024
	ds_read_b128 v[166:169], v138 offset:2048
	ds_read_b128 v[170:173], v138 offset:3072
	v_add_u32_e32 v138, s82, v143
	ds_read_b128 v[174:177], v138
	ds_read_b128 v[178:181], v138 offset:1024
	ds_read_b128 v[182:185], v138 offset:2048
	ds_read_b128 v[186:189], v138 offset:3072
	s_add_u32 s50, s54, 0x30000
	s_addc_u32 s51, s55, 0
	s_mov_b32 m0, s59
	v_lshl_add_u64 v[230:231], s[50:51], 0, v[130:131]
	ds_read_b128 v[190:193], v159 offset:32768
	ds_read_b128 v[194:197], v159 offset:33792
	ds_read_b128 v[198:201], v159 offset:34816
	ds_read_b128 v[202:205], v159 offset:35840
	ds_read_b128 v[206:209], v159 offset:36864
	ds_read_b128 v[210:213], v159 offset:37888
	ds_read_b128 v[214:217], v159 offset:38912
	ds_read_b128 v[218:221], v159 offset:39936
	global_load_lds_dwordx4 v[230:231], off
	v_lshl_add_u64 v[230:231], s[50:51], 0, v[134:135]
	s_mov_b32 m0, s60
	s_nop 0
	global_load_lds_dwordx4 v[230:231], off
	s_waitcnt vmcnt(8)
	s_waitcnt lgkmcnt(0)
	s_setprio 1
	s_barrier
	v_mfma_f32_16x16x32_bf16 v[126:129], v[152:155], v[190:193], v[126:129]
	v_mfma_f32_16x16x32_bf16 v[122:125], v[166:169], v[190:193], v[122:125]
	v_mfma_f32_16x16x32_bf16 v[110:113], v[152:155], v[198:201], v[110:113]
	v_mfma_f32_16x16x32_bf16 v[106:109], v[166:169], v[198:201], v[106:109]
	v_mfma_f32_16x16x32_bf16 v[94:97], v[152:155], v[206:209], v[94:97]
	v_mfma_f32_16x16x32_bf16 v[90:93], v[166:169], v[206:209], v[90:93]
	v_mfma_f32_16x16x32_bf16 v[78:81], v[152:155], v[214:217], v[78:81]
	v_mfma_f32_16x16x32_bf16 v[74:77], v[166:169], v[214:217], v[74:77]
	v_mfma_f32_16x16x32_bf16 v[126:129], v[162:165], v[194:197], v[126:129]
	v_mfma_f32_16x16x32_bf16 v[122:125], v[170:173], v[194:197], v[122:125]
	v_mfma_f32_16x16x32_bf16 v[110:113], v[162:165], v[202:205], v[110:113]
	v_mfma_f32_16x16x32_bf16 v[106:109], v[170:173], v[202:205], v[106:109]
	v_mfma_f32_16x16x32_bf16 v[94:97], v[162:165], v[210:213], v[94:97]
	v_mfma_f32_16x16x32_bf16 v[90:93], v[170:173], v[210:213], v[90:93]
	v_mfma_f32_16x16x32_bf16 v[78:81], v[162:165], v[218:221], v[78:81]
	v_mfma_f32_16x16x32_bf16 v[74:77], v[170:173], v[218:221], v[74:77]
	s_setprio 0
	s_setprio 1
	v_mfma_f32_16x16x32_bf16 v[118:121], v[174:177], v[190:193], v[118:121]
	v_mfma_f32_16x16x32_bf16 v[114:117], v[182:185], v[190:193], v[114:117]
	v_mfma_f32_16x16x32_bf16 v[102:105], v[174:177], v[198:201], v[102:105]
	v_mfma_f32_16x16x32_bf16 v[98:101], v[182:185], v[198:201], v[98:101]
	v_mfma_f32_16x16x32_bf16 v[86:89], v[174:177], v[206:209], v[86:89]
	v_mfma_f32_16x16x32_bf16 v[82:85], v[182:185], v[206:209], v[82:85]
	v_mfma_f32_16x16x32_bf16 v[70:73], v[174:177], v[214:217], v[70:73]
	v_mfma_f32_16x16x32_bf16 v[66:69], v[182:185], v[214:217], v[66:69]
	v_mfma_f32_16x16x32_bf16 v[118:121], v[178:181], v[194:197], v[118:121]
	v_mfma_f32_16x16x32_bf16 v[114:117], v[186:189], v[194:197], v[114:117]
	v_mfma_f32_16x16x32_bf16 v[102:105], v[178:181], v[202:205], v[102:105]
	v_mfma_f32_16x16x32_bf16 v[98:101], v[186:189], v[202:205], v[98:101]
	v_mfma_f32_16x16x32_bf16 v[86:89], v[178:181], v[210:213], v[86:89]
	v_mfma_f32_16x16x32_bf16 v[82:85], v[186:189], v[210:213], v[82:85]
	v_mfma_f32_16x16x32_bf16 v[70:73], v[178:181], v[218:221], v[70:73]
	v_mfma_f32_16x16x32_bf16 v[66:69], v[186:189], v[218:221], v[66:69]
	s_setprio 0
	s_barrier
	s_add_i32 s50, s81, s56
	v_lshl_add_u64 v[222:223], v[222:223], 0, s[42:43]
	s_mov_b32 m0, s50
	ds_read_b128 v[190:193], v159 offset:49152
	ds_read_b128 v[194:197], v159 offset:50176
	ds_read_b128 v[198:201], v159 offset:51200
	ds_read_b128 v[202:205], v159 offset:52224
	ds_read_b128 v[206:209], v159 offset:53248
	ds_read_b128 v[210:213], v159 offset:54272
	ds_read_b128 v[214:217], v159 offset:55296
	ds_read_b128 v[218:221], v159 offset:56320
	global_load_lds_dwordx4 v[222:223], off
	s_add_i32 m0, s50, 0x2000
	s_add_u32 s50, s52, 0x30080
	v_lshl_add_u64 v[222:223], v[224:225], 0, s[42:43]
	s_addc_u32 s51, s53, 0
	s_add_i32 s52, s82, s56
	global_load_lds_dwordx4 v[222:223], off
	v_lshl_add_u64 v[222:223], s[50:51], 0, v[132:133]
	s_mov_b32 m0, s52
	s_nop 0
	global_load_lds_dwordx4 v[222:223], off
	v_lshl_add_u64 v[222:223], s[50:51], 0, v[136:137]
	s_add_i32 m0, s52, 0x2000
	s_nop 0
	global_load_lds_dwordx4 v[222:223], off
	v_lshl_add_u64 v[222:223], v[226:227], 0, s[42:43]
	s_mov_b32 m0, s61
	s_nop 0
	global_load_lds_dwordx4 v[222:223], off
	v_lshl_add_u64 v[222:223], v[228:229], 0, s[42:43]
	s_mov_b32 m0, s62
	s_nop 0
	global_load_lds_dwordx4 v[222:223], off
	s_waitcnt vmcnt(8)
	s_waitcnt lgkmcnt(0)
	s_setprio 1
	s_barrier
	v_mfma_f32_16x16x32_bf16 v[62:65], v[152:155], v[190:193], v[62:65]
	v_mfma_f32_16x16x32_bf16 v[58:61], v[166:169], v[190:193], v[58:61]
	v_mfma_f32_16x16x32_bf16 v[46:49], v[152:155], v[198:201], v[46:49]
	v_mfma_f32_16x16x32_bf16 v[42:45], v[166:169], v[198:201], v[42:45]
	v_mfma_f32_16x16x32_bf16 v[30:33], v[152:155], v[206:209], v[30:33]
	v_mfma_f32_16x16x32_bf16 v[26:29], v[166:169], v[206:209], v[26:29]
	v_mfma_f32_16x16x32_bf16 v[14:17], v[152:155], v[214:217], v[14:17]
	v_mfma_f32_16x16x32_bf16 v[10:13], v[166:169], v[214:217], v[10:13]
	v_mfma_f32_16x16x32_bf16 v[62:65], v[162:165], v[194:197], v[62:65]
	v_mfma_f32_16x16x32_bf16 v[58:61], v[170:173], v[194:197], v[58:61]
	v_mfma_f32_16x16x32_bf16 v[46:49], v[162:165], v[202:205], v[46:49]
	v_mfma_f32_16x16x32_bf16 v[42:45], v[170:173], v[202:205], v[42:45]
	v_mfma_f32_16x16x32_bf16 v[30:33], v[162:165], v[210:213], v[30:33]
	v_mfma_f32_16x16x32_bf16 v[26:29], v[170:173], v[210:213], v[26:29]
	v_mfma_f32_16x16x32_bf16 v[14:17], v[162:165], v[218:221], v[14:17]
	v_mfma_f32_16x16x32_bf16 v[10:13], v[170:173], v[218:221], v[10:13]
	s_setprio 0
	s_setprio 1
	v_mfma_f32_16x16x32_bf16 v[54:57], v[174:177], v[190:193], v[54:57]
	v_mfma_f32_16x16x32_bf16 v[50:53], v[182:185], v[190:193], v[50:53]
	v_mfma_f32_16x16x32_bf16 v[38:41], v[174:177], v[198:201], v[38:41]
	v_mfma_f32_16x16x32_bf16 v[34:37], v[182:185], v[198:201], v[34:37]
	v_mfma_f32_16x16x32_bf16 v[22:25], v[174:177], v[206:209], v[22:25]
	v_mfma_f32_16x16x32_bf16 v[18:21], v[182:185], v[206:209], v[18:21]
	v_mfma_f32_16x16x32_bf16 v[6:9], v[174:177], v[214:217], v[6:9]
	v_mfma_f32_16x16x32_bf16 v[2:5], v[182:185], v[214:217], v[2:5]
	v_mfma_f32_16x16x32_bf16 v[54:57], v[178:181], v[194:197], v[54:57]
	v_mfma_f32_16x16x32_bf16 v[50:53], v[186:189], v[194:197], v[50:53]
	v_mfma_f32_16x16x32_bf16 v[38:41], v[178:181], v[202:205], v[38:41]
	v_mfma_f32_16x16x32_bf16 v[34:37], v[186:189], v[202:205], v[34:37]
	v_mfma_f32_16x16x32_bf16 v[22:25], v[178:181], v[210:213], v[22:25]
	v_mfma_f32_16x16x32_bf16 v[18:21], v[186:189], v[210:213], v[18:21]
	v_mfma_f32_16x16x32_bf16 v[6:9], v[178:181], v[218:221], v[6:9]
	v_mfma_f32_16x16x32_bf16 v[2:5], v[186:189], v[218:221], v[2:5]
	s_setprio 0
	s_barrier
	s_add_i32 s80, s80, 2
	s_add_u32 s10, s10, 0x100
	s_addc_u32 s79, s79, 0
	s_cmp_gt_u32 s80, 9
	s_mov_b64 s[50:51], s[6:7]
	s_cbranch_scc0 .LBB0_1486
	s_and_b64 vcc, exec, s[44:45]
	s_cbranch_vccz .LBB0_1489
	s_barrier

.LBB0_1909:
	ds_read_b128 v[114:117], v225
	ds_read_b128 v[126:129], v225 offset:1024
	ds_read_b128 v[138:141], v225 offset:2048
	ds_read_b128 v[142:145], v225 offset:3072
	ds_read_b128 v[146:149], v226
	ds_read_b128 v[150:153], v226 offset:1024
	ds_read_b128 v[154:157], v226 offset:2048
	ds_read_b128 v[158:161], v226 offset:3072
	s_add_u32 s46, s44, 0x100
	s_addc_u32 s47, s45, 0
	s_cmp_eq_u32 s71, 40
	s_cselect_b32 s51, s9, s47
	s_cselect_b32 s50, s8, s46
	s_cselect_b32 s49, s43, s70
	s_cselect_b32 s48, s42, s69
	v_lshl_add_u64 v[214:215], s[44:45], 0, v[198:199]
	s_add_i32 m0, s53, 0xc000
	ds_read_b128 v[162:165], v227
	ds_read_b128 v[166:169], v227 offset:1024
	ds_read_b128 v[170:173], v227 offset:2048
	ds_read_b128 v[174:177], v227 offset:3072
	ds_read_b128 v[178:181], v227 offset:4096
	ds_read_b128 v[182:185], v227 offset:5120
	ds_read_b128 v[206:209], v227 offset:6144
	ds_read_b128 v[210:213], v227 offset:7168
	global_load_lds_dwordx4 v[214:215], off
	v_lshl_add_u64 v[214:215], s[44:45], 0, v[200:201]
	s_add_i32 m0, s53, 0xe000
	s_nop 0
	global_load_lds_dwordx4 v[214:215], off
	s_waitcnt vmcnt(8)
	s_waitcnt lgkmcnt(0)
	s_setprio 1
	s_barrier
	v_mfma_f32_16x16x32_bf16 v[134:137], v[114:117], v[162:165], v[134:137]
	v_mfma_f32_16x16x32_bf16 v[130:133], v[138:141], v[162:165], v[130:133]
	v_mfma_f32_16x16x32_bf16 v[110:113], v[114:117], v[170:173], v[110:113]
	v_mfma_f32_16x16x32_bf16 v[106:109], v[138:141], v[170:173], v[106:109]
	v_mfma_f32_16x16x32_bf16 v[94:97], v[114:117], v[178:181], v[94:97]
	v_mfma_f32_16x16x32_bf16 v[90:93], v[138:141], v[178:181], v[90:93]
	v_mfma_f32_16x16x32_bf16 v[78:81], v[114:117], v[206:209], v[78:81]
	v_mfma_f32_16x16x32_bf16 v[74:77], v[138:141], v[206:209], v[74:77]
	v_mfma_f32_16x16x32_bf16 v[134:137], v[126:129], v[166:169], v[134:137]
	v_mfma_f32_16x16x32_bf16 v[130:133], v[142:145], v[166:169], v[130:133]
	v_mfma_f32_16x16x32_bf16 v[110:113], v[126:129], v[174:177], v[110:113]
	v_mfma_f32_16x16x32_bf16 v[106:109], v[142:145], v[174:177], v[106:109]
	v_mfma_f32_16x16x32_bf16 v[94:97], v[126:129], v[182:185], v[94:97]
	v_mfma_f32_16x16x32_bf16 v[90:93], v[142:145], v[182:185], v[90:93]
	v_mfma_f32_16x16x32_bf16 v[78:81], v[126:129], v[210:213], v[78:81]
	v_mfma_f32_16x16x32_bf16 v[74:77], v[142:145], v[210:213], v[74:77]
	s_setprio 0
	s_setprio 1
	v_mfma_f32_16x16x32_bf16 v[122:125], v[146:149], v[162:165], v[122:125]
	v_mfma_f32_16x16x32_bf16 v[118:121], v[154:157], v[162:165], v[118:121]
	v_mfma_f32_16x16x32_bf16 v[102:105], v[146:149], v[170:173], v[102:105]
	v_mfma_f32_16x16x32_bf16 v[98:101], v[154:157], v[170:173], v[98:101]
	v_mfma_f32_16x16x32_bf16 v[86:89], v[146:149], v[178:181], v[86:89]
	v_mfma_f32_16x16x32_bf16 v[82:85], v[154:157], v[178:181], v[82:85]
	v_mfma_f32_16x16x32_bf16 v[70:73], v[146:149], v[206:209], v[70:73]
	v_mfma_f32_16x16x32_bf16 v[66:69], v[154:157], v[206:209], v[66:69]
	v_mfma_f32_16x16x32_bf16 v[122:125], v[150:153], v[166:169], v[122:125]
	v_mfma_f32_16x16x32_bf16 v[118:121], v[158:161], v[166:169], v[118:121]
	v_mfma_f32_16x16x32_bf16 v[102:105], v[150:153], v[174:177], v[102:105]
	v_mfma_f32_16x16x32_bf16 v[98:101], v[158:161], v[174:177], v[98:101]
	v_mfma_f32_16x16x32_bf16 v[86:89], v[150:153], v[182:185], v[86:89]
	v_mfma_f32_16x16x32_bf16 v[82:85], v[158:161], v[182:185], v[82:85]
	v_mfma_f32_16x16x32_bf16 v[70:73], v[150:153], v[210:213], v[70:73]
	v_mfma_f32_16x16x32_bf16 v[66:69], v[158:161], v[210:213], v[66:69]
	s_setprio 0
	s_barrier
	s_add_i32 s44, s63, s52
	v_lshl_add_u64 v[214:215], s[48:49], 0, v[188:189]
	s_mov_b32 m0, s44
	ds_read_b128 v[162:165], v227 offset:16384
	ds_read_b128 v[166:169], v227 offset:17408
	ds_read_b128 v[170:173], v227 offset:18432
	ds_read_b128 v[174:177], v227 offset:19456
	ds_read_b128 v[178:181], v227 offset:20480
	ds_read_b128 v[182:185], v227 offset:21504
	ds_read_b128 v[206:209], v227 offset:22528
	ds_read_b128 v[210:213], v227 offset:23552
	global_load_lds_dwordx4 v[214:215], off
	s_add_i32 m0, s44, 0x2000
	s_add_u32 s44, s48, 0xb0000
	v_lshl_add_u64 v[216:217], s[48:49], 0, v[192:193]
	s_addc_u32 s45, s49, 0
	s_add_i32 s72, s64, s52
	global_load_lds_dwordx4 v[216:217], off
	v_lshl_add_u64 v[218:219], s[44:45], 0, v[188:189]
	s_mov_b32 m0, s72
	v_lshl_add_u64 v[220:221], s[50:51], 0, v[190:191]
	global_load_lds_dwordx4 v[218:219], off
	v_lshl_add_u64 v[218:219], s[44:45], 0, v[192:193]
	s_add_i32 m0, s72, 0x2000
	s_nop 0
	global_load_lds_dwordx4 v[218:219], off
	v_lshl_add_u64 v[218:219], s[50:51], 0, v[186:187]
	s_mov_b32 m0, s53
	s_nop 0
	global_load_lds_dwordx4 v[218:219], off
	s_mov_b32 m0, s54
	s_nop 0
	global_load_lds_dwordx4 v[220:221], off
	s_waitcnt vmcnt(8)
	s_waitcnt lgkmcnt(0)
	s_setprio 1
	s_barrier
	v_mfma_f32_16x16x32_bf16 v[62:65], v[114:117], v[162:165], v[62:65]
	v_mfma_f32_16x16x32_bf16 v[58:61], v[138:141], v[162:165], v[58:61]
	v_mfma_f32_16x16x32_bf16 v[46:49], v[114:117], v[170:173], v[46:49]
	v_mfma_f32_16x16x32_bf16 v[42:45], v[138:141], v[170:173], v[42:45]
	v_mfma_f32_16x16x32_bf16 v[30:33], v[114:117], v[178:181], v[30:33]
	v_mfma_f32_16x16x32_bf16 v[26:29], v[138:141], v[178:181], v[26:29]
	v_mfma_f32_16x16x32_bf16 v[14:17], v[114:117], v[206:209], v[14:17]
	v_mfma_f32_16x16x32_bf16 v[10:13], v[138:141], v[206:209], v[10:13]
	v_mfma_f32_16x16x32_bf16 v[62:65], v[126:129], v[166:169], v[62:65]
	v_mfma_f32_16x16x32_bf16 v[58:61], v[142:145], v[166:169], v[58:61]
	v_mfma_f32_16x16x32_bf16 v[46:49], v[126:129], v[174:177], v[46:49]
	v_mfma_f32_16x16x32_bf16 v[42:45], v[142:145], v[174:177], v[42:45]
	v_mfma_f32_16x16x32_bf16 v[30:33], v[126:129], v[182:185], v[30:33]
	v_mfma_f32_16x16x32_bf16 v[26:29], v[142:145], v[182:185], v[26:29]
	v_mfma_f32_16x16x32_bf16 v[14:17], v[126:129], v[210:213], v[14:17]
	v_mfma_f32_16x16x32_bf16 v[10:13], v[142:145], v[210:213], v[10:13]
	s_setprio 0
	s_setprio 1
	v_mfma_f32_16x16x32_bf16 v[54:57], v[146:149], v[162:165], v[54:57]
	v_mfma_f32_16x16x32_bf16 v[50:53], v[154:157], v[162:165], v[50:53]
	v_mfma_f32_16x16x32_bf16 v[38:41], v[146:149], v[170:173], v[38:41]
	v_mfma_f32_16x16x32_bf16 v[34:37], v[154:157], v[170:173], v[34:37]
	v_mfma_f32_16x16x32_bf16 v[22:25], v[146:149], v[178:181], v[22:25]
	v_mfma_f32_16x16x32_bf16 v[18:21], v[154:157], v[178:181], v[18:21]
	v_mfma_f32_16x16x32_bf16 v[6:9], v[146:149], v[206:209], v[6:9]
	v_mfma_f32_16x16x32_bf16 v[2:5], v[154:157], v[206:209], v[2:5]
	v_mfma_f32_16x16x32_bf16 v[54:57], v[150:153], v[166:169], v[54:57]
	v_mfma_f32_16x16x32_bf16 v[50:53], v[158:161], v[166:169], v[50:53]
	v_mfma_f32_16x16x32_bf16 v[38:41], v[150:153], v[174:177], v[38:41]
	v_mfma_f32_16x16x32_bf16 v[34:37], v[158:161], v[174:177], v[34:37]
	v_mfma_f32_16x16x32_bf16 v[22:25], v[150:153], v[182:185], v[22:25]
	v_mfma_f32_16x16x32_bf16 v[18:21], v[158:161], v[182:185], v[18:21]
	v_mfma_f32_16x16x32_bf16 v[6:9], v[150:153], v[210:213], v[6:9]
	v_mfma_f32_16x16x32_bf16 v[2:5], v[158:161], v[210:213], v[2:5]
	s_setprio 0
	s_barrier
	s_add_i32 s72, 0, 0x18000
	s_add_i32 s73, 0, 0x1c000
	v_add_u32_e32 v142, s72, v224
	v_add_u32_e32 v158, s73, v224
	ds_read_b128 v[114:117], v142
	ds_read_b128 v[126:129], v142 offset:1024
	ds_read_b128 v[138:141], v142 offset:2048
	ds_read_b128 v[142:145], v142 offset:3072
	ds_read_b128 v[146:149], v158
	ds_read_b128 v[150:153], v158 offset:1024
	ds_read_b128 v[154:157], v158 offset:2048
	ds_read_b128 v[158:161], v158 offset:3072
	s_add_u32 s44, s50, 0xb0000
	s_addc_u32 s45, s51, 0
	s_mov_b32 m0, s55
	v_lshl_add_u64 v[222:223], s[44:45], 0, v[186:187]
	ds_read_b128 v[162:165], v227 offset:32768
	ds_read_b128 v[166:169], v227 offset:33792
	ds_read_b128 v[170:173], v227 offset:34816
	ds_read_b128 v[174:177], v227 offset:35840
	ds_read_b128 v[178:181], v227 offset:36864
	ds_read_b128 v[182:185], v227 offset:37888
	ds_read_b128 v[206:209], v227 offset:38912
	ds_read_b128 v[210:213], v227 offset:39936
	global_load_lds_dwordx4 v[222:223], off
	v_lshl_add_u64 v[222:223], s[44:45], 0, v[190:191]
	s_mov_b32 m0, s56
	s_nop 0
	global_load_lds_dwordx4 v[222:223], off
	s_waitcnt vmcnt(8)
	s_waitcnt lgkmcnt(0)
	s_setprio 1
	s_barrier
	v_mfma_f32_16x16x32_bf16 v[134:137], v[114:117], v[162:165], v[134:137]
	v_mfma_f32_16x16x32_bf16 v[130:133], v[138:141], v[162:165], v[130:133]
	v_mfma_f32_16x16x32_bf16 v[110:113], v[114:117], v[170:173], v[110:113]
	v_mfma_f32_16x16x32_bf16 v[106:109], v[138:141], v[170:173], v[106:109]
	v_mfma_f32_16x16x32_bf16 v[94:97], v[114:117], v[178:181], v[94:97]
	v_mfma_f32_16x16x32_bf16 v[90:93], v[138:141], v[178:181], v[90:93]
	v_mfma_f32_16x16x32_bf16 v[78:81], v[114:117], v[206:209], v[78:81]
	v_mfma_f32_16x16x32_bf16 v[74:77], v[138:141], v[206:209], v[74:77]
	v_mfma_f32_16x16x32_bf16 v[134:137], v[126:129], v[166:169], v[134:137]
	v_mfma_f32_16x16x32_bf16 v[130:133], v[142:145], v[166:169], v[130:133]
	v_mfma_f32_16x16x32_bf16 v[110:113], v[126:129], v[174:177], v[110:113]
	v_mfma_f32_16x16x32_bf16 v[106:109], v[142:145], v[174:177], v[106:109]
	v_mfma_f32_16x16x32_bf16 v[94:97], v[126:129], v[182:185], v[94:97]
	v_mfma_f32_16x16x32_bf16 v[90:93], v[142:145], v[182:185], v[90:93]
	v_mfma_f32_16x16x32_bf16 v[78:81], v[126:129], v[210:213], v[78:81]
	v_mfma_f32_16x16x32_bf16 v[74:77], v[142:145], v[210:213], v[74:77]
	s_setprio 0
	s_setprio 1
	v_mfma_f32_16x16x32_bf16 v[122:125], v[146:149], v[162:165], v[122:125]
	v_mfma_f32_16x16x32_bf16 v[118:121], v[154:157], v[162:165], v[118:121]
	v_mfma_f32_16x16x32_bf16 v[102:105], v[146:149], v[170:173], v[102:105]
	v_mfma_f32_16x16x32_bf16 v[98:101], v[154:157], v[170:173], v[98:101]
	v_mfma_f32_16x16x32_bf16 v[86:89], v[146:149], v[178:181], v[86:89]
	v_mfma_f32_16x16x32_bf16 v[82:85], v[154:157], v[178:181], v[82:85]
	v_mfma_f32_16x16x32_bf16 v[70:73], v[146:149], v[206:209], v[70:73]
	v_mfma_f32_16x16x32_bf16 v[66:69], v[154:157], v[206:209], v[66:69]
	v_mfma_f32_16x16x32_bf16 v[122:125], v[150:153], v[166:169], v[122:125]
	v_mfma_f32_16x16x32_bf16 v[118:121], v[158:161], v[166:169], v[118:121]
	v_mfma_f32_16x16x32_bf16 v[102:105], v[150:153], v[174:177], v[102:105]
	v_mfma_f32_16x16x32_bf16 v[98:101], v[158:161], v[174:177], v[98:101]
	v_mfma_f32_16x16x32_bf16 v[86:89], v[150:153], v[182:185], v[86:89]
	v_mfma_f32_16x16x32_bf16 v[82:85], v[158:161], v[182:185], v[82:85]
	v_mfma_f32_16x16x32_bf16 v[70:73], v[150:153], v[210:213], v[70:73]
	v_mfma_f32_16x16x32_bf16 v[66:69], v[158:161], v[210:213], v[66:69]
	s_setprio 0
	s_barrier
	s_add_i32 s44, s72, s52
	v_lshl_add_u64 v[214:215], v[214:215], 0, s[24:25]
	s_mov_b32 m0, s44
	ds_read_b128 v[162:165], v227 offset:49152
	ds_read_b128 v[166:169], v227 offset:50176
	ds_read_b128 v[170:173], v227 offset:51200
	ds_read_b128 v[174:177], v227 offset:52224
	ds_read_b128 v[178:181], v227 offset:53248
	ds_read_b128 v[182:185], v227 offset:54272
	ds_read_b128 v[206:209], v227 offset:55296
	ds_read_b128 v[210:213], v227 offset:56320
	global_load_lds_dwordx4 v[214:215], off
	s_add_i32 m0, s44, 0x2000
	s_add_u32 s44, s48, 0xb0080
	v_lshl_add_u64 v[214:215], v[216:217], 0, s[24:25]
	s_addc_u32 s45, s49, 0
	s_add_i32 s48, s73, s52
	global_load_lds_dwordx4 v[214:215], off
	v_lshl_add_u64 v[214:215], s[44:45], 0, v[188:189]
	s_mov_b32 m0, s48
	s_nop 0
	global_load_lds_dwordx4 v[214:215], off
	v_lshl_add_u64 v[214:215], s[44:45], 0, v[192:193]
	s_add_i32 m0, s48, 0x2000
	s_nop 0
	global_load_lds_dwordx4 v[214:215], off
	v_lshl_add_u64 v[214:215], v[218:219], 0, s[24:25]
	s_mov_b32 m0, s58
	s_nop 0
	global_load_lds_dwordx4 v[214:215], off
	v_lshl_add_u64 v[214:215], v[220:221], 0, s[24:25]
	s_mov_b32 m0, s59
	s_nop 0
	global_load_lds_dwordx4 v[214:215], off
	s_waitcnt vmcnt(8)
	s_waitcnt lgkmcnt(0)
	s_setprio 1
	s_barrier
	v_mfma_f32_16x16x32_bf16 v[62:65], v[114:117], v[162:165], v[62:65]
	v_mfma_f32_16x16x32_bf16 v[58:61], v[138:141], v[162:165], v[58:61]
	v_mfma_f32_16x16x32_bf16 v[46:49], v[114:117], v[170:173], v[46:49]
	v_mfma_f32_16x16x32_bf16 v[42:45], v[138:141], v[170:173], v[42:45]
	v_mfma_f32_16x16x32_bf16 v[30:33], v[114:117], v[178:181], v[30:33]
	v_mfma_f32_16x16x32_bf16 v[26:29], v[138:141], v[178:181], v[26:29]
	v_mfma_f32_16x16x32_bf16 v[14:17], v[114:117], v[206:209], v[14:17]
	v_mfma_f32_16x16x32_bf16 v[10:13], v[138:141], v[206:209], v[10:13]
	v_mfma_f32_16x16x32_bf16 v[62:65], v[126:129], v[166:169], v[62:65]
	v_mfma_f32_16x16x32_bf16 v[58:61], v[142:145], v[166:169], v[58:61]
	v_mfma_f32_16x16x32_bf16 v[46:49], v[126:129], v[174:177], v[46:49]
	v_mfma_f32_16x16x32_bf16 v[42:45], v[142:145], v[174:177], v[42:45]
	v_mfma_f32_16x16x32_bf16 v[30:33], v[126:129], v[182:185], v[30:33]
	v_mfma_f32_16x16x32_bf16 v[26:29], v[142:145], v[182:185], v[26:29]
	v_mfma_f32_16x16x32_bf16 v[14:17], v[126:129], v[210:213], v[14:17]
	v_mfma_f32_16x16x32_bf16 v[10:13], v[142:145], v[210:213], v[10:13]
	s_setprio 0
	s_setprio 1
	v_mfma_f32_16x16x32_bf16 v[54:57], v[146:149], v[162:165], v[54:57]
	v_mfma_f32_16x16x32_bf16 v[50:53], v[154:157], v[162:165], v[50:53]
	v_mfma_f32_16x16x32_bf16 v[38:41], v[146:149], v[170:173], v[38:41]
	v_mfma_f32_16x16x32_bf16 v[34:37], v[154:157], v[170:173], v[34:37]
	v_mfma_f32_16x16x32_bf16 v[22:25], v[146:149], v[178:181], v[22:25]
	v_mfma_f32_16x16x32_bf16 v[18:21], v[154:157], v[178:181], v[18:21]
	v_mfma_f32_16x16x32_bf16 v[6:9], v[146:149], v[206:209], v[6:9]
	v_mfma_f32_16x16x32_bf16 v[2:5], v[154:157], v[206:209], v[2:5]
	v_mfma_f32_16x16x32_bf16 v[54:57], v[150:153], v[166:169], v[54:57]
	v_mfma_f32_16x16x32_bf16 v[50:53], v[158:161], v[166:169], v[50:53]
	v_mfma_f32_16x16x32_bf16 v[38:41], v[150:153], v[174:177], v[38:41]
	v_mfma_f32_16x16x32_bf16 v[34:37], v[158:161], v[174:177], v[34:37]
	v_mfma_f32_16x16x32_bf16 v[22:25], v[150:153], v[182:185], v[22:25]
	v_mfma_f32_16x16x32_bf16 v[18:21], v[158:161], v[182:185], v[18:21]
	v_mfma_f32_16x16x32_bf16 v[6:9], v[150:153], v[210:213], v[6:9]
	v_mfma_f32_16x16x32_bf16 v[2:5], v[158:161], v[210:213], v[2:5]
	s_setprio 0
	s_barrier
	s_add_i32 s71, s71, 2
	s_add_u32 s69, s69, 0x100
	s_addc_u32 s70, s70, 0
	s_cmp_gt_u32 s71, 41
	s_mov_b64 s[44:45], s[46:47]
	s_cbranch_scc0 .LBB0_1909
	s_and_b64 vcc, exec, s[26:27]
	s_cbranch_vccz .LBB0_1912
	s_barrier
